# k32: k27 + loop-edge edit: in all 18 GEMM K loops the scalar pointer/counter updates and the loop compare moved from after the last barrier into the shadow of the last MFMA group
# speedup vs baseline: 1.0065x; 1.0059x over previous
.LBB0_202:
	ds_read_b128 v[148:151], v167
	ds_read_b128 v[152:155], v167 offset:1024
	ds_read_b128 v[156:159], v167 offset:2048
	ds_read_b128 v[160:163], v167 offset:3072
	ds_read_b128 v[172:175], v168
	ds_read_b128 v[176:179], v168 offset:1024
	ds_read_b128 v[180:183], v168 offset:2048
	ds_read_b128 v[184:187], v168 offset:3072
	s_add_u32 s0, s28, 0xfffc0080
	s_addc_u32 s1, s29, -1
	s_cmp_eq_u32 s51, 12
	s_cselect_b32 s31, s21, s1
	s_cselect_b32 s30, s47, s0
	s_cselect_b32 s3, s19, s50
	s_cselect_b32 s2, s48, s49
	v_lshl_add_u64 v[220:221], s[28:29], 0, v[140:141]
	s_add_i32 m0, s27, 0xc000
	ds_read_b128 v[188:191], v169
	ds_read_b128 v[192:195], v169 offset:1024
	ds_read_b128 v[196:199], v169 offset:2048
	ds_read_b128 v[200:203], v169 offset:3072
	ds_read_b128 v[204:207], v169 offset:4096
	ds_read_b128 v[208:211], v169 offset:5120
	ds_read_b128 v[212:215], v169 offset:6144
	ds_read_b128 v[216:219], v169 offset:7168
	global_load_lds_dwordx4 v[220:221], off
	v_lshl_add_u64 v[220:221], s[28:29], 0, v[142:143]
	s_add_i32 m0, s27, 0xe000
	s_nop 0
	global_load_lds_dwordx4 v[220:221], off
	s_waitcnt vmcnt(8)
	s_waitcnt lgkmcnt(0)
	s_barrier
	s_setprio 1
	s_waitcnt lgkmcnt(0)
	v_mfma_f32_16x16x32_bf16 v[126:129], v[148:151], v[188:191], v[126:129]
	v_mfma_f32_16x16x32_bf16 v[126:129], v[152:155], v[192:195], v[126:129]
	v_mfma_f32_16x16x32_bf16 v[118:121], v[156:159], v[188:191], v[118:121]
	v_mfma_f32_16x16x32_bf16 v[118:121], v[160:163], v[192:195], v[118:121]
	v_mfma_f32_16x16x32_bf16 v[110:113], v[148:151], v[196:199], v[110:113]
	v_mfma_f32_16x16x32_bf16 v[110:113], v[152:155], v[200:203], v[110:113]
	v_mfma_f32_16x16x32_bf16 v[106:109], v[156:159], v[196:199], v[106:109]
	v_mfma_f32_16x16x32_bf16 v[106:109], v[160:163], v[200:203], v[106:109]
	v_mfma_f32_16x16x32_bf16 v[94:97], v[148:151], v[204:207], v[94:97]
	v_mfma_f32_16x16x32_bf16 v[94:97], v[152:155], v[208:211], v[94:97]
	v_mfma_f32_16x16x32_bf16 v[90:93], v[156:159], v[204:207], v[90:93]
	v_mfma_f32_16x16x32_bf16 v[90:93], v[160:163], v[208:211], v[90:93]
	v_mfma_f32_16x16x32_bf16 v[78:81], v[148:151], v[212:215], v[78:81]
	v_mfma_f32_16x16x32_bf16 v[78:81], v[152:155], v[216:219], v[78:81]
	v_mfma_f32_16x16x32_bf16 v[74:77], v[156:159], v[212:215], v[74:77]
	v_mfma_f32_16x16x32_bf16 v[74:77], v[160:163], v[216:219], v[74:77]
	s_setprio 0
	s_setprio 1
	v_mfma_f32_16x16x32_bf16 v[122:125], v[172:175], v[188:191], v[122:125]
	v_mfma_f32_16x16x32_bf16 v[122:125], v[176:179], v[192:195], v[122:125]
	v_mfma_f32_16x16x32_bf16 v[114:117], v[180:183], v[188:191], v[114:117]
	v_mfma_f32_16x16x32_bf16 v[114:117], v[184:187], v[192:195], v[114:117]
	v_mfma_f32_16x16x32_bf16 v[102:105], v[172:175], v[196:199], v[102:105]
	v_mfma_f32_16x16x32_bf16 v[102:105], v[176:179], v[200:203], v[102:105]
	v_mfma_f32_16x16x32_bf16 v[98:101], v[180:183], v[196:199], v[98:101]
	v_mfma_f32_16x16x32_bf16 v[98:101], v[184:187], v[200:203], v[98:101]
	v_mfma_f32_16x16x32_bf16 v[86:89], v[172:175], v[204:207], v[86:89]
	v_mfma_f32_16x16x32_bf16 v[86:89], v[176:179], v[208:211], v[86:89]
	v_mfma_f32_16x16x32_bf16 v[82:85], v[180:183], v[204:207], v[82:85]
	v_mfma_f32_16x16x32_bf16 v[82:85], v[184:187], v[208:211], v[82:85]
	v_mfma_f32_16x16x32_bf16 v[70:73], v[172:175], v[212:215], v[70:73]
	v_mfma_f32_16x16x32_bf16 v[70:73], v[176:179], v[216:219], v[70:73]
	v_mfma_f32_16x16x32_bf16 v[66:69], v[180:183], v[212:215], v[66:69]
	v_mfma_f32_16x16x32_bf16 v[66:69], v[184:187], v[216:219], v[66:69]
	s_setprio 0
	s_barrier
	s_add_i32 s0, s43, s36
	v_lshl_add_u64 v[220:221], s[2:3], 0, v[132:133]
	s_mov_b32 m0, s0
	ds_read_b128 v[188:191], v169 offset:16384
	ds_read_b128 v[192:195], v169 offset:17408
	ds_read_b128 v[196:199], v169 offset:18432
	ds_read_b128 v[200:203], v169 offset:19456
	ds_read_b128 v[204:207], v169 offset:20480
	ds_read_b128 v[208:211], v169 offset:21504
	ds_read_b128 v[212:215], v169 offset:22528
	ds_read_b128 v[216:219], v169 offset:23552
	global_load_lds_dwordx4 v[220:221], off
	s_add_i32 m0, s0, 0x2000
	s_add_u32 s0, s2, 0x40000
	v_lshl_add_u64 v[222:223], s[2:3], 0, v[136:137]
	s_addc_u32 s1, s3, 0
	s_add_i32 s52, s44, s36
	global_load_lds_dwordx4 v[222:223], off
	v_lshl_add_u64 v[224:225], s[0:1], 0, v[132:133]
	s_mov_b32 m0, s52
	v_lshl_add_u64 v[226:227], s[30:31], 0, v[134:135]
	global_load_lds_dwordx4 v[224:225], off
	v_lshl_add_u64 v[224:225], s[0:1], 0, v[136:137]
	s_add_i32 m0, s52, 0x2000
	s_nop 0
	global_load_lds_dwordx4 v[224:225], off
	v_lshl_add_u64 v[224:225], s[30:31], 0, v[130:131]
	s_mov_b32 m0, s27
	s_nop 0
	global_load_lds_dwordx4 v[224:225], off
	s_mov_b32 m0, s37
	s_nop 0
	global_load_lds_dwordx4 v[226:227], off
	s_waitcnt vmcnt(8)
	s_waitcnt lgkmcnt(0)
	s_barrier
	s_setprio 1
	s_waitcnt lgkmcnt(0)
	v_mfma_f32_16x16x32_bf16 v[62:65], v[148:151], v[188:191], v[62:65]
	v_mfma_f32_16x16x32_bf16 v[62:65], v[152:155], v[192:195], v[62:65]
	v_mfma_f32_16x16x32_bf16 v[58:61], v[156:159], v[188:191], v[58:61]
	v_mfma_f32_16x16x32_bf16 v[58:61], v[160:163], v[192:195], v[58:61]
	v_mfma_f32_16x16x32_bf16 v[46:49], v[148:151], v[196:199], v[46:49]
	v_mfma_f32_16x16x32_bf16 v[46:49], v[152:155], v[200:203], v[46:49]
	v_mfma_f32_16x16x32_bf16 v[42:45], v[156:159], v[196:199], v[42:45]
	v_mfma_f32_16x16x32_bf16 v[42:45], v[160:163], v[200:203], v[42:45]
	v_mfma_f32_16x16x32_bf16 v[30:33], v[148:151], v[204:207], v[30:33]
	v_mfma_f32_16x16x32_bf16 v[30:33], v[152:155], v[208:211], v[30:33]
	v_mfma_f32_16x16x32_bf16 v[26:29], v[156:159], v[204:207], v[26:29]
	v_mfma_f32_16x16x32_bf16 v[26:29], v[160:163], v[208:211], v[26:29]
	v_mfma_f32_16x16x32_bf16 v[14:17], v[148:151], v[212:215], v[14:17]
	v_mfma_f32_16x16x32_bf16 v[14:17], v[152:155], v[216:219], v[14:17]
	v_mfma_f32_16x16x32_bf16 v[10:13], v[156:159], v[212:215], v[10:13]
	v_mfma_f32_16x16x32_bf16 v[10:13], v[160:163], v[216:219], v[10:13]
	s_setprio 0
	s_setprio 1
	v_mfma_f32_16x16x32_bf16 v[54:57], v[172:175], v[188:191], v[54:57]
	v_mfma_f32_16x16x32_bf16 v[54:57], v[176:179], v[192:195], v[54:57]
	v_mfma_f32_16x16x32_bf16 v[50:53], v[180:183], v[188:191], v[50:53]
	v_mfma_f32_16x16x32_bf16 v[50:53], v[184:187], v[192:195], v[50:53]
	v_mfma_f32_16x16x32_bf16 v[38:41], v[172:175], v[196:199], v[38:41]
	v_mfma_f32_16x16x32_bf16 v[38:41], v[176:179], v[200:203], v[38:41]
	v_mfma_f32_16x16x32_bf16 v[34:37], v[180:183], v[196:199], v[34:37]
	v_mfma_f32_16x16x32_bf16 v[34:37], v[184:187], v[200:203], v[34:37]
	v_mfma_f32_16x16x32_bf16 v[22:25], v[172:175], v[204:207], v[22:25]
	v_mfma_f32_16x16x32_bf16 v[22:25], v[176:179], v[208:211], v[22:25]
	v_mfma_f32_16x16x32_bf16 v[18:21], v[180:183], v[204:207], v[18:21]
	v_mfma_f32_16x16x32_bf16 v[18:21], v[184:187], v[208:211], v[18:21]
	v_mfma_f32_16x16x32_bf16 v[6:9], v[172:175], v[212:215], v[6:9]
	v_mfma_f32_16x16x32_bf16 v[6:9], v[176:179], v[216:219], v[6:9]
	v_mfma_f32_16x16x32_bf16 v[2:5], v[180:183], v[212:215], v[2:5]
	v_mfma_f32_16x16x32_bf16 v[2:5], v[184:187], v[216:219], v[2:5]
	s_setprio 0
	s_barrier
	s_add_i32 s52, 0, 0x18000
	s_add_i32 s53, 0, 0x1c000
	v_add_u32_e32 v160, s52, v166
	v_add_u32_e32 v164, s53, v166
	ds_read_b128 v[148:151], v160
	ds_read_b128 v[152:155], v160 offset:1024
	ds_read_b128 v[156:159], v160 offset:2048
	ds_read_b128 v[160:163], v160 offset:3072
	ds_read_b128 v[172:175], v164
	ds_read_b128 v[176:179], v164 offset:1024
	ds_read_b128 v[180:183], v164 offset:2048
	ds_read_b128 v[184:187], v164 offset:3072
	s_add_u32 s0, s30, 0x40000
	s_addc_u32 s1, s31, 0
	s_mov_b32 m0, s38
	v_lshl_add_u64 v[228:229], s[0:1], 0, v[130:131]
	ds_read_b128 v[188:191], v169 offset:32768
	ds_read_b128 v[192:195], v169 offset:33792
	ds_read_b128 v[196:199], v169 offset:34816
	ds_read_b128 v[200:203], v169 offset:35840
	ds_read_b128 v[204:207], v169 offset:36864
	ds_read_b128 v[208:211], v169 offset:37888
	ds_read_b128 v[212:215], v169 offset:38912
	ds_read_b128 v[216:219], v169 offset:39936
	global_load_lds_dwordx4 v[228:229], off
	v_lshl_add_u64 v[228:229], s[0:1], 0, v[134:135]
	s_mov_b32 m0, s39
	s_nop 0
	global_load_lds_dwordx4 v[228:229], off
	s_waitcnt vmcnt(8)
	s_waitcnt lgkmcnt(0)
	s_barrier
	s_setprio 1
	s_waitcnt lgkmcnt(0)
	v_mfma_f32_16x16x32_bf16 v[126:129], v[148:151], v[188:191], v[126:129]
	v_mfma_f32_16x16x32_bf16 v[126:129], v[152:155], v[192:195], v[126:129]
	v_mfma_f32_16x16x32_bf16 v[118:121], v[156:159], v[188:191], v[118:121]
	v_mfma_f32_16x16x32_bf16 v[118:121], v[160:163], v[192:195], v[118:121]
	v_mfma_f32_16x16x32_bf16 v[110:113], v[148:151], v[196:199], v[110:113]
	v_mfma_f32_16x16x32_bf16 v[110:113], v[152:155], v[200:203], v[110:113]
	v_mfma_f32_16x16x32_bf16 v[106:109], v[156:159], v[196:199], v[106:109]
	v_mfma_f32_16x16x32_bf16 v[106:109], v[160:163], v[200:203], v[106:109]
	v_mfma_f32_16x16x32_bf16 v[94:97], v[148:151], v[204:207], v[94:97]
	v_mfma_f32_16x16x32_bf16 v[94:97], v[152:155], v[208:211], v[94:97]
	v_mfma_f32_16x16x32_bf16 v[90:93], v[156:159], v[204:207], v[90:93]
	v_mfma_f32_16x16x32_bf16 v[90:93], v[160:163], v[208:211], v[90:93]
	v_mfma_f32_16x16x32_bf16 v[78:81], v[148:151], v[212:215], v[78:81]
	v_mfma_f32_16x16x32_bf16 v[78:81], v[152:155], v[216:219], v[78:81]
	v_mfma_f32_16x16x32_bf16 v[74:77], v[156:159], v[212:215], v[74:77]
	v_mfma_f32_16x16x32_bf16 v[74:77], v[160:163], v[216:219], v[74:77]
	s_setprio 0
	s_setprio 1
	v_mfma_f32_16x16x32_bf16 v[122:125], v[172:175], v[188:191], v[122:125]
	v_mfma_f32_16x16x32_bf16 v[122:125], v[176:179], v[192:195], v[122:125]
	v_mfma_f32_16x16x32_bf16 v[114:117], v[180:183], v[188:191], v[114:117]
	v_mfma_f32_16x16x32_bf16 v[114:117], v[184:187], v[192:195], v[114:117]
	v_mfma_f32_16x16x32_bf16 v[102:105], v[172:175], v[196:199], v[102:105]
	v_mfma_f32_16x16x32_bf16 v[102:105], v[176:179], v[200:203], v[102:105]
	v_mfma_f32_16x16x32_bf16 v[98:101], v[180:183], v[196:199], v[98:101]
	v_mfma_f32_16x16x32_bf16 v[98:101], v[184:187], v[200:203], v[98:101]
	v_mfma_f32_16x16x32_bf16 v[86:89], v[172:175], v[204:207], v[86:89]
	v_mfma_f32_16x16x32_bf16 v[86:89], v[176:179], v[208:211], v[86:89]
	v_mfma_f32_16x16x32_bf16 v[82:85], v[180:183], v[204:207], v[82:85]
	v_mfma_f32_16x16x32_bf16 v[82:85], v[184:187], v[208:211], v[82:85]
	v_mfma_f32_16x16x32_bf16 v[70:73], v[172:175], v[212:215], v[70:73]
	v_mfma_f32_16x16x32_bf16 v[70:73], v[176:179], v[216:219], v[70:73]
	v_mfma_f32_16x16x32_bf16 v[66:69], v[180:183], v[212:215], v[66:69]
	v_mfma_f32_16x16x32_bf16 v[66:69], v[184:187], v[216:219], v[66:69]
	s_setprio 0
	s_barrier
	s_add_i32 s0, s52, s36
	v_lshl_add_u64 v[220:221], v[220:221], 0, s[14:15]
	s_mov_b32 m0, s0
	ds_read_b128 v[188:191], v169 offset:49152
	ds_read_b128 v[192:195], v169 offset:50176
	ds_read_b128 v[196:199], v169 offset:51200
	ds_read_b128 v[200:203], v169 offset:52224
	ds_read_b128 v[204:207], v169 offset:53248
	ds_read_b128 v[208:211], v169 offset:54272
	ds_read_b128 v[212:215], v169 offset:55296
	ds_read_b128 v[216:219], v169 offset:56320
	global_load_lds_dwordx4 v[220:221], off
	s_add_i32 m0, s0, 0x2000
	s_add_u32 s0, s2, 0x40080
	v_lshl_add_u64 v[220:221], v[222:223], 0, s[14:15]
	s_addc_u32 s1, s3, 0
	s_add_i32 s2, s53, s36
	global_load_lds_dwordx4 v[220:221], off
	v_lshl_add_u64 v[220:221], s[0:1], 0, v[132:133]
	s_mov_b32 m0, s2
	s_nop 0
	global_load_lds_dwordx4 v[220:221], off
	v_lshl_add_u64 v[220:221], s[0:1], 0, v[136:137]
	s_add_i32 m0, s2, 0x2000
	s_nop 0
	global_load_lds_dwordx4 v[220:221], off
	v_lshl_add_u64 v[220:221], v[224:225], 0, s[14:15]
	s_mov_b32 m0, s40
	s_nop 0
	global_load_lds_dwordx4 v[220:221], off
	v_lshl_add_u64 v[220:221], v[226:227], 0, s[14:15]
	s_mov_b32 m0, s41
	s_nop 0
	global_load_lds_dwordx4 v[220:221], off
	s_waitcnt vmcnt(8)
	s_waitcnt lgkmcnt(0)
	s_barrier
	s_setprio 1
	s_waitcnt lgkmcnt(0)
	v_mfma_f32_16x16x32_bf16 v[62:65], v[148:151], v[188:191], v[62:65]
	v_mfma_f32_16x16x32_bf16 v[62:65], v[152:155], v[192:195], v[62:65]
	v_mfma_f32_16x16x32_bf16 v[58:61], v[156:159], v[188:191], v[58:61]
	v_mfma_f32_16x16x32_bf16 v[58:61], v[160:163], v[192:195], v[58:61]
	v_mfma_f32_16x16x32_bf16 v[46:49], v[148:151], v[196:199], v[46:49]
	v_mfma_f32_16x16x32_bf16 v[46:49], v[152:155], v[200:203], v[46:49]
	v_mfma_f32_16x16x32_bf16 v[42:45], v[156:159], v[196:199], v[42:45]
	v_mfma_f32_16x16x32_bf16 v[42:45], v[160:163], v[200:203], v[42:45]
	v_mfma_f32_16x16x32_bf16 v[30:33], v[148:151], v[204:207], v[30:33]
	v_mfma_f32_16x16x32_bf16 v[30:33], v[152:155], v[208:211], v[30:33]
	v_mfma_f32_16x16x32_bf16 v[26:29], v[156:159], v[204:207], v[26:29]
	v_mfma_f32_16x16x32_bf16 v[26:29], v[160:163], v[208:211], v[26:29]
	v_mfma_f32_16x16x32_bf16 v[14:17], v[148:151], v[212:215], v[14:17]
	v_mfma_f32_16x16x32_bf16 v[14:17], v[152:155], v[216:219], v[14:17]
	v_mfma_f32_16x16x32_bf16 v[10:13], v[156:159], v[212:215], v[10:13]
	v_mfma_f32_16x16x32_bf16 v[10:13], v[160:163], v[216:219], v[10:13]
	s_setprio 0
	s_setprio 1
	v_mfma_f32_16x16x32_bf16 v[54:57], v[172:175], v[188:191], v[54:57]
	s_add_i32 s51, s51, 2
	s_add_u32 s28, s28, 0x100
	s_addc_u32 s29, s29, 0
	s_add_u32 s49, s49, 0x100
	s_addc_u32 s50, s50, 0
	s_cmp_gt_u32 s51, 13
	v_mfma_f32_16x16x32_bf16 v[54:57], v[176:179], v[192:195], v[54:57]
	v_mfma_f32_16x16x32_bf16 v[50:53], v[180:183], v[188:191], v[50:53]
	v_mfma_f32_16x16x32_bf16 v[50:53], v[184:187], v[192:195], v[50:53]
	v_mfma_f32_16x16x32_bf16 v[38:41], v[172:175], v[196:199], v[38:41]
	v_mfma_f32_16x16x32_bf16 v[38:41], v[176:179], v[200:203], v[38:41]
	v_mfma_f32_16x16x32_bf16 v[34:37], v[180:183], v[196:199], v[34:37]
	v_mfma_f32_16x16x32_bf16 v[34:37], v[184:187], v[200:203], v[34:37]
	v_mfma_f32_16x16x32_bf16 v[22:25], v[172:175], v[204:207], v[22:25]
	v_mfma_f32_16x16x32_bf16 v[22:25], v[176:179], v[208:211], v[22:25]
	v_mfma_f32_16x16x32_bf16 v[18:21], v[180:183], v[204:207], v[18:21]
	v_mfma_f32_16x16x32_bf16 v[18:21], v[184:187], v[208:211], v[18:21]
	v_mfma_f32_16x16x32_bf16 v[6:9], v[172:175], v[212:215], v[6:9]
	v_mfma_f32_16x16x32_bf16 v[6:9], v[176:179], v[216:219], v[6:9]
	v_mfma_f32_16x16x32_bf16 v[2:5], v[180:183], v[212:215], v[2:5]
	v_mfma_f32_16x16x32_bf16 v[2:5], v[184:187], v[216:219], v[2:5]
	s_setprio 0
	s_barrier
	s_cbranch_scc0 .LBB0_202
	s_and_b64 vcc, exec, s[16:17]
	s_cbranch_vccz .LBB0_205
	s_barrier

.LBB0_283:
	ds_read_b128 v[114:117], v228
	ds_read_b128 v[118:121], v228 offset:1024
	ds_read_b128 v[122:125], v228 offset:2048
	ds_read_b128 v[126:129], v228 offset:3072
	ds_read_b128 v[146:149], v229
	ds_read_b128 v[150:153], v229 offset:1024
	ds_read_b128 v[154:157], v229 offset:2048
	ds_read_b128 v[158:161], v229 offset:3072
	s_add_u32 s0, s10, 0xfffc0080
	s_addc_u32 s1, s11, -1
	s_cmp_eq_u32 s51, 12
	s_cselect_b32 s13, s7, s1
	s_cselect_b32 s12, s9, s0
	s_cselect_b32 s3, s27, s37
	s_cselect_b32 s2, s29, s36
	v_lshl_add_u64 v[212:213], s[10:11], 0, v[180:181]
	s_add_i32 m0, s40, 0xc000
	ds_read_b128 v[162:165], v230
	ds_read_b128 v[166:169], v230 offset:1024
	ds_read_b128 v[188:191], v230 offset:2048
	ds_read_b128 v[192:195], v230 offset:3072
	ds_read_b128 v[196:199], v230 offset:4096
	ds_read_b128 v[200:203], v230 offset:5120
	ds_read_b128 v[204:207], v230 offset:6144
	ds_read_b128 v[208:211], v230 offset:7168
	global_load_lds_dwordx4 v[212:213], off
	v_lshl_add_u64 v[212:213], s[10:11], 0, v[182:183]
	s_add_i32 m0, s40, 0xe000
	s_nop 0
	global_load_lds_dwordx4 v[212:213], off
	s_waitcnt vmcnt(8)
	s_waitcnt lgkmcnt(0)
	s_barrier
	s_setprio 1
	s_waitcnt lgkmcnt(0)
	v_mfma_f32_16x16x32_bf16 v[142:145], v[114:117], v[162:165], v[142:145]
	v_mfma_f32_16x16x32_bf16 v[142:145], v[118:121], v[166:169], v[142:145]
	v_mfma_f32_16x16x32_bf16 v[138:141], v[122:125], v[162:165], v[138:141]
	v_mfma_f32_16x16x32_bf16 v[138:141], v[126:129], v[166:169], v[138:141]
	v_mfma_f32_16x16x32_bf16 v[134:137], v[114:117], v[188:191], v[134:137]
	v_mfma_f32_16x16x32_bf16 v[134:137], v[118:121], v[192:195], v[134:137]
	v_mfma_f32_16x16x32_bf16 v[130:133], v[122:125], v[188:191], v[130:133]
	v_mfma_f32_16x16x32_bf16 v[130:133], v[126:129], v[192:195], v[130:133]
	v_mfma_f32_16x16x32_bf16 v[110:113], v[114:117], v[196:199], v[110:113]
	v_mfma_f32_16x16x32_bf16 v[110:113], v[118:121], v[200:203], v[110:113]
	v_mfma_f32_16x16x32_bf16 v[106:109], v[122:125], v[196:199], v[106:109]
	v_mfma_f32_16x16x32_bf16 v[106:109], v[126:129], v[200:203], v[106:109]
	v_mfma_f32_16x16x32_bf16 v[102:105], v[114:117], v[204:207], v[102:105]
	v_mfma_f32_16x16x32_bf16 v[102:105], v[118:121], v[208:211], v[102:105]
	v_mfma_f32_16x16x32_bf16 v[98:101], v[122:125], v[204:207], v[98:101]
	v_mfma_f32_16x16x32_bf16 v[98:101], v[126:129], v[208:211], v[98:101]
	s_setprio 0
	s_setprio 1
	v_mfma_f32_16x16x32_bf16 v[62:65], v[146:149], v[162:165], v[62:65]
	v_mfma_f32_16x16x32_bf16 v[62:65], v[150:153], v[166:169], v[62:65]
	v_mfma_f32_16x16x32_bf16 v[58:61], v[154:157], v[162:165], v[58:61]
	v_mfma_f32_16x16x32_bf16 v[58:61], v[158:161], v[166:169], v[58:61]
	v_mfma_f32_16x16x32_bf16 v[54:57], v[146:149], v[188:191], v[54:57]
	v_mfma_f32_16x16x32_bf16 v[54:57], v[150:153], v[192:195], v[54:57]
	v_mfma_f32_16x16x32_bf16 v[50:53], v[154:157], v[188:191], v[50:53]
	v_mfma_f32_16x16x32_bf16 v[50:53], v[158:161], v[192:195], v[50:53]
	v_mfma_f32_16x16x32_bf16 v[46:49], v[146:149], v[196:199], v[46:49]
	v_mfma_f32_16x16x32_bf16 v[46:49], v[150:153], v[200:203], v[46:49]
	v_mfma_f32_16x16x32_bf16 v[42:45], v[154:157], v[196:199], v[42:45]
	v_mfma_f32_16x16x32_bf16 v[42:45], v[158:161], v[200:203], v[42:45]
	v_mfma_f32_16x16x32_bf16 v[38:41], v[146:149], v[204:207], v[38:41]
	v_mfma_f32_16x16x32_bf16 v[38:41], v[150:153], v[208:211], v[38:41]
	v_mfma_f32_16x16x32_bf16 v[34:37], v[154:157], v[204:207], v[34:37]
	v_mfma_f32_16x16x32_bf16 v[34:37], v[158:161], v[208:211], v[34:37]
	s_setprio 0
	s_barrier
	s_add_i32 s0, s49, s39
	v_lshl_add_u64 v[212:213], s[2:3], 0, v[172:173]
	s_mov_b32 m0, s0
	ds_read_b128 v[162:165], v230 offset:16384
	ds_read_b128 v[166:169], v230 offset:17408
	ds_read_b128 v[188:191], v230 offset:18432
	ds_read_b128 v[192:195], v230 offset:19456
	ds_read_b128 v[196:199], v230 offset:20480
	ds_read_b128 v[200:203], v230 offset:21504
	ds_read_b128 v[204:207], v230 offset:22528
	ds_read_b128 v[208:211], v230 offset:23552
	global_load_lds_dwordx4 v[212:213], off
	s_add_i32 m0, s0, 0x2000
	s_add_u32 s0, s2, 0x40000
	v_lshl_add_u64 v[214:215], s[2:3], 0, v[176:177]
	s_addc_u32 s1, s3, 0
	s_add_i32 s52, s50, s39
	global_load_lds_dwordx4 v[214:215], off
	v_lshl_add_u64 v[216:217], s[0:1], 0, v[172:173]
	s_mov_b32 m0, s52
	v_lshl_add_u64 v[218:219], s[12:13], 0, v[174:175]
	global_load_lds_dwordx4 v[216:217], off
	v_lshl_add_u64 v[216:217], s[0:1], 0, v[176:177]
	s_add_i32 m0, s52, 0x2000
	s_nop 0
	global_load_lds_dwordx4 v[216:217], off
	v_lshl_add_u64 v[216:217], s[12:13], 0, v[170:171]
	s_mov_b32 m0, s40
	s_nop 0
	global_load_lds_dwordx4 v[216:217], off
	s_mov_b32 m0, s41
	s_nop 0
	global_load_lds_dwordx4 v[218:219], off
	s_waitcnt vmcnt(8)
	s_waitcnt lgkmcnt(0)
	s_barrier
	s_setprio 1
	s_waitcnt lgkmcnt(0)
	v_mfma_f32_16x16x32_bf16 v[94:97], v[114:117], v[162:165], v[94:97]
	v_mfma_f32_16x16x32_bf16 v[94:97], v[118:121], v[166:169], v[94:97]
	v_mfma_f32_16x16x32_bf16 v[90:93], v[122:125], v[162:165], v[90:93]
	v_mfma_f32_16x16x32_bf16 v[90:93], v[126:129], v[166:169], v[90:93]
	v_mfma_f32_16x16x32_bf16 v[86:89], v[114:117], v[188:191], v[86:89]
	v_mfma_f32_16x16x32_bf16 v[86:89], v[118:121], v[192:195], v[86:89]
	v_mfma_f32_16x16x32_bf16 v[82:85], v[122:125], v[188:191], v[82:85]
	v_mfma_f32_16x16x32_bf16 v[82:85], v[126:129], v[192:195], v[82:85]
	v_mfma_f32_16x16x32_bf16 v[78:81], v[114:117], v[196:199], v[78:81]
	v_mfma_f32_16x16x32_bf16 v[78:81], v[118:121], v[200:203], v[78:81]
	v_mfma_f32_16x16x32_bf16 v[74:77], v[122:125], v[196:199], v[74:77]
	v_mfma_f32_16x16x32_bf16 v[74:77], v[126:129], v[200:203], v[74:77]
	v_mfma_f32_16x16x32_bf16 v[70:73], v[114:117], v[204:207], v[70:73]
	v_mfma_f32_16x16x32_bf16 v[70:73], v[118:121], v[208:211], v[70:73]
	v_mfma_f32_16x16x32_bf16 v[66:69], v[122:125], v[204:207], v[66:69]
	v_mfma_f32_16x16x32_bf16 v[66:69], v[126:129], v[208:211], v[66:69]
	s_setprio 0
	s_setprio 1
	v_mfma_f32_16x16x32_bf16 v[30:33], v[146:149], v[162:165], v[30:33]
	v_mfma_f32_16x16x32_bf16 v[30:33], v[150:153], v[166:169], v[30:33]
	v_mfma_f32_16x16x32_bf16 v[26:29], v[154:157], v[162:165], v[26:29]
	v_mfma_f32_16x16x32_bf16 v[26:29], v[158:161], v[166:169], v[26:29]
	v_mfma_f32_16x16x32_bf16 v[22:25], v[146:149], v[188:191], v[22:25]
	v_mfma_f32_16x16x32_bf16 v[22:25], v[150:153], v[192:195], v[22:25]
	v_mfma_f32_16x16x32_bf16 v[18:21], v[154:157], v[188:191], v[18:21]
	v_mfma_f32_16x16x32_bf16 v[18:21], v[158:161], v[192:195], v[18:21]
	v_mfma_f32_16x16x32_bf16 v[14:17], v[146:149], v[196:199], v[14:17]
	v_mfma_f32_16x16x32_bf16 v[14:17], v[150:153], v[200:203], v[14:17]
	v_mfma_f32_16x16x32_bf16 v[10:13], v[154:157], v[196:199], v[10:13]
	v_mfma_f32_16x16x32_bf16 v[10:13], v[158:161], v[200:203], v[10:13]
	v_mfma_f32_16x16x32_bf16 v[6:9], v[146:149], v[204:207], v[6:9]
	v_mfma_f32_16x16x32_bf16 v[6:9], v[150:153], v[208:211], v[6:9]
	v_mfma_f32_16x16x32_bf16 v[2:5], v[154:157], v[204:207], v[2:5]
	v_mfma_f32_16x16x32_bf16 v[2:5], v[158:161], v[208:211], v[2:5]
	s_setprio 0
	s_barrier
	s_add_i32 s52, 0, 0x18000
	s_add_i32 s53, 0, 0x1c000
	v_add_u32_e32 v126, s52, v223
	v_add_u32_e32 v158, s53, v223
	ds_read_b128 v[114:117], v126
	ds_read_b128 v[118:121], v126 offset:1024
	ds_read_b128 v[122:125], v126 offset:2048
	ds_read_b128 v[126:129], v126 offset:3072
	ds_read_b128 v[146:149], v158
	ds_read_b128 v[150:153], v158 offset:1024
	ds_read_b128 v[154:157], v158 offset:2048
	ds_read_b128 v[158:161], v158 offset:3072
	s_add_u32 s0, s12, 0x40000
	s_addc_u32 s1, s13, 0
	s_mov_b32 m0, s42
	v_lshl_add_u64 v[220:221], s[0:1], 0, v[170:171]
	ds_read_b128 v[162:165], v230 offset:32768
	ds_read_b128 v[166:169], v230 offset:33792
	ds_read_b128 v[188:191], v230 offset:34816
	ds_read_b128 v[192:195], v230 offset:35840
	ds_read_b128 v[196:199], v230 offset:36864
	ds_read_b128 v[200:203], v230 offset:37888
	ds_read_b128 v[204:207], v230 offset:38912
	ds_read_b128 v[208:211], v230 offset:39936
	global_load_lds_dwordx4 v[220:221], off
	v_lshl_add_u64 v[220:221], s[0:1], 0, v[174:175]
	s_mov_b32 m0, s43
	s_nop 0
	global_load_lds_dwordx4 v[220:221], off
	s_waitcnt vmcnt(8)
	s_waitcnt lgkmcnt(0)
	s_barrier
	s_setprio 1
	s_waitcnt lgkmcnt(0)
	v_mfma_f32_16x16x32_bf16 v[142:145], v[114:117], v[162:165], v[142:145]
	v_mfma_f32_16x16x32_bf16 v[142:145], v[118:121], v[166:169], v[142:145]
	v_mfma_f32_16x16x32_bf16 v[138:141], v[122:125], v[162:165], v[138:141]
	v_mfma_f32_16x16x32_bf16 v[138:141], v[126:129], v[166:169], v[138:141]
	v_mfma_f32_16x16x32_bf16 v[134:137], v[114:117], v[188:191], v[134:137]
	v_mfma_f32_16x16x32_bf16 v[134:137], v[118:121], v[192:195], v[134:137]
	v_mfma_f32_16x16x32_bf16 v[130:133], v[122:125], v[188:191], v[130:133]
	v_mfma_f32_16x16x32_bf16 v[130:133], v[126:129], v[192:195], v[130:133]
	v_mfma_f32_16x16x32_bf16 v[110:113], v[114:117], v[196:199], v[110:113]
	v_mfma_f32_16x16x32_bf16 v[110:113], v[118:121], v[200:203], v[110:113]
	v_mfma_f32_16x16x32_bf16 v[106:109], v[122:125], v[196:199], v[106:109]
	v_mfma_f32_16x16x32_bf16 v[106:109], v[126:129], v[200:203], v[106:109]
	v_mfma_f32_16x16x32_bf16 v[102:105], v[114:117], v[204:207], v[102:105]
	v_mfma_f32_16x16x32_bf16 v[102:105], v[118:121], v[208:211], v[102:105]
	v_mfma_f32_16x16x32_bf16 v[98:101], v[122:125], v[204:207], v[98:101]
	v_mfma_f32_16x16x32_bf16 v[98:101], v[126:129], v[208:211], v[98:101]
	s_setprio 0
	s_setprio 1
	v_mfma_f32_16x16x32_bf16 v[62:65], v[146:149], v[162:165], v[62:65]
	v_mfma_f32_16x16x32_bf16 v[62:65], v[150:153], v[166:169], v[62:65]
	v_mfma_f32_16x16x32_bf16 v[58:61], v[154:157], v[162:165], v[58:61]
	v_mfma_f32_16x16x32_bf16 v[58:61], v[158:161], v[166:169], v[58:61]
	v_mfma_f32_16x16x32_bf16 v[54:57], v[146:149], v[188:191], v[54:57]
	v_mfma_f32_16x16x32_bf16 v[54:57], v[150:153], v[192:195], v[54:57]
	v_mfma_f32_16x16x32_bf16 v[50:53], v[154:157], v[188:191], v[50:53]
	v_mfma_f32_16x16x32_bf16 v[50:53], v[158:161], v[192:195], v[50:53]
	v_mfma_f32_16x16x32_bf16 v[46:49], v[146:149], v[196:199], v[46:49]
	v_mfma_f32_16x16x32_bf16 v[46:49], v[150:153], v[200:203], v[46:49]
	v_mfma_f32_16x16x32_bf16 v[42:45], v[154:157], v[196:199], v[42:45]
	v_mfma_f32_16x16x32_bf16 v[42:45], v[158:161], v[200:203], v[42:45]
	v_mfma_f32_16x16x32_bf16 v[38:41], v[146:149], v[204:207], v[38:41]
	v_mfma_f32_16x16x32_bf16 v[38:41], v[150:153], v[208:211], v[38:41]
	v_mfma_f32_16x16x32_bf16 v[34:37], v[154:157], v[204:207], v[34:37]
	v_mfma_f32_16x16x32_bf16 v[34:37], v[158:161], v[208:211], v[34:37]
	s_setprio 0
	s_barrier
	s_add_i32 s0, s52, s39
	v_lshl_add_u64 v[212:213], v[212:213], 0, s[22:23]
	s_mov_b32 m0, s0
	ds_read_b128 v[162:165], v230 offset:49152
	ds_read_b128 v[166:169], v230 offset:50176
	ds_read_b128 v[188:191], v230 offset:51200
	ds_read_b128 v[192:195], v230 offset:52224
	ds_read_b128 v[196:199], v230 offset:53248
	ds_read_b128 v[200:203], v230 offset:54272
	ds_read_b128 v[204:207], v230 offset:55296
	ds_read_b128 v[208:211], v230 offset:56320
	global_load_lds_dwordx4 v[212:213], off
	s_add_i32 m0, s0, 0x2000
	s_add_u32 s0, s2, 0x40080
	v_lshl_add_u64 v[212:213], v[214:215], 0, s[22:23]
	s_addc_u32 s1, s3, 0
	s_add_i32 s2, s53, s39
	global_load_lds_dwordx4 v[212:213], off
	v_lshl_add_u64 v[212:213], s[0:1], 0, v[172:173]
	s_mov_b32 m0, s2
	s_nop 0
	global_load_lds_dwordx4 v[212:213], off
	v_lshl_add_u64 v[212:213], s[0:1], 0, v[176:177]
	s_add_i32 m0, s2, 0x2000
	s_nop 0
	global_load_lds_dwordx4 v[212:213], off
	v_lshl_add_u64 v[212:213], v[216:217], 0, s[22:23]
	s_mov_b32 m0, s45
	s_nop 0
	global_load_lds_dwordx4 v[212:213], off
	v_lshl_add_u64 v[212:213], v[218:219], 0, s[22:23]
	s_mov_b32 m0, s46
	s_nop 0
	global_load_lds_dwordx4 v[212:213], off
	s_waitcnt vmcnt(8)
	s_waitcnt lgkmcnt(0)
	s_barrier
	s_setprio 1
	s_waitcnt lgkmcnt(0)
	v_mfma_f32_16x16x32_bf16 v[94:97], v[114:117], v[162:165], v[94:97]
	v_mfma_f32_16x16x32_bf16 v[94:97], v[118:121], v[166:169], v[94:97]
	v_mfma_f32_16x16x32_bf16 v[90:93], v[122:125], v[162:165], v[90:93]
	v_mfma_f32_16x16x32_bf16 v[90:93], v[126:129], v[166:169], v[90:93]
	v_mfma_f32_16x16x32_bf16 v[86:89], v[114:117], v[188:191], v[86:89]
	v_mfma_f32_16x16x32_bf16 v[86:89], v[118:121], v[192:195], v[86:89]
	v_mfma_f32_16x16x32_bf16 v[82:85], v[122:125], v[188:191], v[82:85]
	v_mfma_f32_16x16x32_bf16 v[82:85], v[126:129], v[192:195], v[82:85]
	v_mfma_f32_16x16x32_bf16 v[78:81], v[114:117], v[196:199], v[78:81]
	v_mfma_f32_16x16x32_bf16 v[78:81], v[118:121], v[200:203], v[78:81]
	v_mfma_f32_16x16x32_bf16 v[74:77], v[122:125], v[196:199], v[74:77]
	v_mfma_f32_16x16x32_bf16 v[74:77], v[126:129], v[200:203], v[74:77]
	v_mfma_f32_16x16x32_bf16 v[70:73], v[114:117], v[204:207], v[70:73]
	v_mfma_f32_16x16x32_bf16 v[70:73], v[118:121], v[208:211], v[70:73]
	v_mfma_f32_16x16x32_bf16 v[66:69], v[122:125], v[204:207], v[66:69]
	v_mfma_f32_16x16x32_bf16 v[66:69], v[126:129], v[208:211], v[66:69]
	s_setprio 0
	s_setprio 1
	v_mfma_f32_16x16x32_bf16 v[30:33], v[146:149], v[162:165], v[30:33]
	s_add_i32 s51, s51, 2
	s_add_u32 s10, s10, 0x100
	s_addc_u32 s11, s11, 0
	s_add_u32 s36, s36, 0x100
	s_addc_u32 s37, s37, 0
	s_cmp_gt_u32 s51, 13
	v_mfma_f32_16x16x32_bf16 v[30:33], v[150:153], v[166:169], v[30:33]
	v_mfma_f32_16x16x32_bf16 v[26:29], v[154:157], v[162:165], v[26:29]
	v_mfma_f32_16x16x32_bf16 v[26:29], v[158:161], v[166:169], v[26:29]
	v_mfma_f32_16x16x32_bf16 v[22:25], v[146:149], v[188:191], v[22:25]
	v_mfma_f32_16x16x32_bf16 v[22:25], v[150:153], v[192:195], v[22:25]
	v_mfma_f32_16x16x32_bf16 v[18:21], v[154:157], v[188:191], v[18:21]
	v_mfma_f32_16x16x32_bf16 v[18:21], v[158:161], v[192:195], v[18:21]
	v_mfma_f32_16x16x32_bf16 v[14:17], v[146:149], v[196:199], v[14:17]
	v_mfma_f32_16x16x32_bf16 v[14:17], v[150:153], v[200:203], v[14:17]
	v_mfma_f32_16x16x32_bf16 v[10:13], v[154:157], v[196:199], v[10:13]
	v_mfma_f32_16x16x32_bf16 v[10:13], v[158:161], v[200:203], v[10:13]
	v_mfma_f32_16x16x32_bf16 v[6:9], v[146:149], v[204:207], v[6:9]
	v_mfma_f32_16x16x32_bf16 v[6:9], v[150:153], v[208:211], v[6:9]
	v_mfma_f32_16x16x32_bf16 v[2:5], v[154:157], v[204:207], v[2:5]
	v_mfma_f32_16x16x32_bf16 v[2:5], v[158:161], v[208:211], v[2:5]
	s_setprio 0
	s_barrier
	s_cbranch_scc0 .LBB0_283
	s_and_b64 vcc, exec, s[24:25]
	s_cbranch_vccz .LBB0_286
	s_barrier

.LBB0_382:
	ds_read_b128 v[130:133], v211
	ds_read_b128 v[134:137], v211 offset:1024
	ds_read_b128 v[138:141], v211 offset:2048
	ds_read_b128 v[142:145], v211 offset:3072
	ds_read_b128 v[146:149], v212
	ds_read_b128 v[150:153], v212 offset:1024
	ds_read_b128 v[154:157], v212 offset:2048
	ds_read_b128 v[158:161], v212 offset:3072
	s_add_u32 s0, s28, 0xfffc0080
	s_addc_u32 s1, s29, -1
	s_cmp_eq_u32 s51, 12
	s_cselect_b32 s31, s11, s1
	s_cselect_b32 s30, s21, s0
	s_cselect_b32 s3, s19, s50
	s_cselect_b32 s2, s48, s49
	v_lshl_add_u64 v[220:221], s[28:29], 0, v[186:187]
	s_add_i32 m0, s27, 0xc000
	ds_read_b128 v[162:165], v213
	ds_read_b128 v[166:169], v213 offset:1024
	ds_read_b128 v[170:173], v213 offset:2048
	ds_read_b128 v[174:177], v213 offset:3072
	ds_read_b128 v[194:197], v213 offset:4096
	ds_read_b128 v[198:201], v213 offset:5120
	ds_read_b128 v[202:205], v213 offset:6144
	ds_read_b128 v[216:219], v213 offset:7168
	global_load_lds_dwordx4 v[220:221], off
	v_lshl_add_u64 v[220:221], s[28:29], 0, v[188:189]
	s_add_i32 m0, s27, 0xe000
	s_nop 0
	global_load_lds_dwordx4 v[220:221], off
	s_waitcnt vmcnt(8)
	s_waitcnt lgkmcnt(0)
	s_barrier
	s_setprio 1
	s_waitcnt lgkmcnt(0)
	v_mfma_f32_16x16x32_bf16 v[126:129], v[130:133], v[162:165], v[126:129]
	v_mfma_f32_16x16x32_bf16 v[126:129], v[134:137], v[166:169], v[126:129]
	v_mfma_f32_16x16x32_bf16 v[122:125], v[138:141], v[162:165], v[122:125]
	v_mfma_f32_16x16x32_bf16 v[122:125], v[142:145], v[166:169], v[122:125]
	v_mfma_f32_16x16x32_bf16 v[110:113], v[130:133], v[170:173], v[110:113]
	v_mfma_f32_16x16x32_bf16 v[110:113], v[134:137], v[174:177], v[110:113]
	v_mfma_f32_16x16x32_bf16 v[106:109], v[138:141], v[170:173], v[106:109]
	v_mfma_f32_16x16x32_bf16 v[106:109], v[142:145], v[174:177], v[106:109]
	v_mfma_f32_16x16x32_bf16 v[94:97], v[130:133], v[194:197], v[94:97]
	v_mfma_f32_16x16x32_bf16 v[94:97], v[134:137], v[198:201], v[94:97]
	v_mfma_f32_16x16x32_bf16 v[90:93], v[138:141], v[194:197], v[90:93]
	v_mfma_f32_16x16x32_bf16 v[90:93], v[142:145], v[198:201], v[90:93]
	v_mfma_f32_16x16x32_bf16 v[78:81], v[130:133], v[202:205], v[78:81]
	v_mfma_f32_16x16x32_bf16 v[78:81], v[134:137], v[216:219], v[78:81]
	v_mfma_f32_16x16x32_bf16 v[74:77], v[138:141], v[202:205], v[74:77]
	v_mfma_f32_16x16x32_bf16 v[74:77], v[142:145], v[216:219], v[74:77]
	s_setprio 0
	s_setprio 1
	v_mfma_f32_16x16x32_bf16 v[118:121], v[146:149], v[162:165], v[118:121]
	v_mfma_f32_16x16x32_bf16 v[118:121], v[150:153], v[166:169], v[118:121]
	v_mfma_f32_16x16x32_bf16 v[114:117], v[154:157], v[162:165], v[114:117]
	v_mfma_f32_16x16x32_bf16 v[114:117], v[158:161], v[166:169], v[114:117]
	v_mfma_f32_16x16x32_bf16 v[102:105], v[146:149], v[170:173], v[102:105]
	v_mfma_f32_16x16x32_bf16 v[102:105], v[150:153], v[174:177], v[102:105]
	v_mfma_f32_16x16x32_bf16 v[98:101], v[154:157], v[170:173], v[98:101]
	v_mfma_f32_16x16x32_bf16 v[98:101], v[158:161], v[174:177], v[98:101]
	v_mfma_f32_16x16x32_bf16 v[86:89], v[146:149], v[194:197], v[86:89]
	v_mfma_f32_16x16x32_bf16 v[86:89], v[150:153], v[198:201], v[86:89]
	v_mfma_f32_16x16x32_bf16 v[82:85], v[154:157], v[194:197], v[82:85]
	v_mfma_f32_16x16x32_bf16 v[82:85], v[158:161], v[198:201], v[82:85]
	v_mfma_f32_16x16x32_bf16 v[70:73], v[146:149], v[202:205], v[70:73]
	v_mfma_f32_16x16x32_bf16 v[70:73], v[150:153], v[216:219], v[70:73]
	v_mfma_f32_16x16x32_bf16 v[66:69], v[154:157], v[202:205], v[66:69]
	v_mfma_f32_16x16x32_bf16 v[66:69], v[158:161], v[216:219], v[66:69]
	s_setprio 0
	s_barrier
	s_add_i32 s0, s46, s37
	v_lshl_add_u64 v[220:221], s[2:3], 0, v[180:181]
	s_mov_b32 m0, s0
	ds_read_b128 v[162:165], v213 offset:16384
	ds_read_b128 v[166:169], v213 offset:17408
	ds_read_b128 v[170:173], v213 offset:18432
	ds_read_b128 v[174:177], v213 offset:19456
	ds_read_b128 v[194:197], v213 offset:20480
	ds_read_b128 v[198:201], v213 offset:21504
	ds_read_b128 v[202:205], v213 offset:22528
	ds_read_b128 v[216:219], v213 offset:23552
	global_load_lds_dwordx4 v[220:221], off
	s_add_i32 m0, s0, 0x2000
	s_add_u32 s0, s2, 0x40000
	v_lshl_add_u64 v[222:223], s[2:3], 0, v[184:185]
	s_addc_u32 s1, s3, 0
	s_add_i32 s52, s47, s37
	global_load_lds_dwordx4 v[222:223], off
	v_lshl_add_u64 v[224:225], s[0:1], 0, v[180:181]
	s_mov_b32 m0, s52
	v_lshl_add_u64 v[226:227], s[30:31], 0, v[182:183]
	global_load_lds_dwordx4 v[224:225], off
	v_lshl_add_u64 v[224:225], s[0:1], 0, v[184:185]
	s_add_i32 m0, s52, 0x2000
	s_nop 0
	global_load_lds_dwordx4 v[224:225], off
	v_lshl_add_u64 v[224:225], s[30:31], 0, v[178:179]
	s_mov_b32 m0, s27
	s_nop 0
	global_load_lds_dwordx4 v[224:225], off
	s_mov_b32 m0, s38
	s_nop 0
	global_load_lds_dwordx4 v[226:227], off
	s_waitcnt vmcnt(8)
	s_waitcnt lgkmcnt(0)
	s_barrier
	s_setprio 1
	s_waitcnt lgkmcnt(0)
	v_mfma_f32_16x16x32_bf16 v[62:65], v[130:133], v[162:165], v[62:65]
	v_mfma_f32_16x16x32_bf16 v[62:65], v[134:137], v[166:169], v[62:65]
	v_mfma_f32_16x16x32_bf16 v[58:61], v[138:141], v[162:165], v[58:61]
	v_mfma_f32_16x16x32_bf16 v[58:61], v[142:145], v[166:169], v[58:61]
	v_mfma_f32_16x16x32_bf16 v[46:49], v[130:133], v[170:173], v[46:49]
	v_mfma_f32_16x16x32_bf16 v[46:49], v[134:137], v[174:177], v[46:49]
	v_mfma_f32_16x16x32_bf16 v[42:45], v[138:141], v[170:173], v[42:45]
	v_mfma_f32_16x16x32_bf16 v[42:45], v[142:145], v[174:177], v[42:45]
	v_mfma_f32_16x16x32_bf16 v[30:33], v[130:133], v[194:197], v[30:33]
	v_mfma_f32_16x16x32_bf16 v[30:33], v[134:137], v[198:201], v[30:33]
	v_mfma_f32_16x16x32_bf16 v[26:29], v[138:141], v[194:197], v[26:29]
	v_mfma_f32_16x16x32_bf16 v[26:29], v[142:145], v[198:201], v[26:29]
	v_mfma_f32_16x16x32_bf16 v[14:17], v[130:133], v[202:205], v[14:17]
	v_mfma_f32_16x16x32_bf16 v[14:17], v[134:137], v[216:219], v[14:17]
	v_mfma_f32_16x16x32_bf16 v[10:13], v[138:141], v[202:205], v[10:13]
	v_mfma_f32_16x16x32_bf16 v[10:13], v[142:145], v[216:219], v[10:13]
	s_setprio 0
	s_setprio 1
	v_mfma_f32_16x16x32_bf16 v[54:57], v[146:149], v[162:165], v[54:57]
	v_mfma_f32_16x16x32_bf16 v[54:57], v[150:153], v[166:169], v[54:57]
	v_mfma_f32_16x16x32_bf16 v[50:53], v[154:157], v[162:165], v[50:53]
	v_mfma_f32_16x16x32_bf16 v[50:53], v[158:161], v[166:169], v[50:53]
	v_mfma_f32_16x16x32_bf16 v[38:41], v[146:149], v[170:173], v[38:41]
	v_mfma_f32_16x16x32_bf16 v[38:41], v[150:153], v[174:177], v[38:41]
	v_mfma_f32_16x16x32_bf16 v[34:37], v[154:157], v[170:173], v[34:37]
	v_mfma_f32_16x16x32_bf16 v[34:37], v[158:161], v[174:177], v[34:37]
	v_mfma_f32_16x16x32_bf16 v[22:25], v[146:149], v[194:197], v[22:25]
	v_mfma_f32_16x16x32_bf16 v[22:25], v[150:153], v[198:201], v[22:25]
	v_mfma_f32_16x16x32_bf16 v[18:21], v[154:157], v[194:197], v[18:21]
	v_mfma_f32_16x16x32_bf16 v[18:21], v[158:161], v[198:201], v[18:21]
	v_mfma_f32_16x16x32_bf16 v[6:9], v[146:149], v[202:205], v[6:9]
	v_mfma_f32_16x16x32_bf16 v[6:9], v[150:153], v[216:219], v[6:9]
	v_mfma_f32_16x16x32_bf16 v[2:5], v[154:157], v[202:205], v[2:5]
	v_mfma_f32_16x16x32_bf16 v[2:5], v[158:161], v[216:219], v[2:5]
	s_setprio 0
	s_barrier
	s_add_i32 s52, 0, 0x18000
	s_add_i32 s53, 0, 0x1c000
	v_add_u32_e32 v142, s52, v207
	v_add_u32_e32 v158, s53, v207
	ds_read_b128 v[130:133], v142
	ds_read_b128 v[134:137], v142 offset:1024
	ds_read_b128 v[138:141], v142 offset:2048
	ds_read_b128 v[142:145], v142 offset:3072
	ds_read_b128 v[146:149], v158
	ds_read_b128 v[150:153], v158 offset:1024
	ds_read_b128 v[154:157], v158 offset:2048
	ds_read_b128 v[158:161], v158 offset:3072
	s_add_u32 s0, s30, 0x40000
	s_addc_u32 s1, s31, 0
	s_mov_b32 m0, s39
	v_lshl_add_u64 v[228:229], s[0:1], 0, v[178:179]
	ds_read_b128 v[162:165], v213 offset:32768
	ds_read_b128 v[166:169], v213 offset:33792
	ds_read_b128 v[170:173], v213 offset:34816
	ds_read_b128 v[174:177], v213 offset:35840
	ds_read_b128 v[194:197], v213 offset:36864
	ds_read_b128 v[198:201], v213 offset:37888
	ds_read_b128 v[202:205], v213 offset:38912
	ds_read_b128 v[216:219], v213 offset:39936
	global_load_lds_dwordx4 v[228:229], off
	v_lshl_add_u64 v[228:229], s[0:1], 0, v[182:183]
	s_mov_b32 m0, s40
	s_nop 0
	global_load_lds_dwordx4 v[228:229], off
	s_waitcnt vmcnt(8)
	s_waitcnt lgkmcnt(0)
	s_barrier
	s_setprio 1
	s_waitcnt lgkmcnt(0)
	v_mfma_f32_16x16x32_bf16 v[126:129], v[130:133], v[162:165], v[126:129]
	v_mfma_f32_16x16x32_bf16 v[126:129], v[134:137], v[166:169], v[126:129]
	v_mfma_f32_16x16x32_bf16 v[122:125], v[138:141], v[162:165], v[122:125]
	v_mfma_f32_16x16x32_bf16 v[122:125], v[142:145], v[166:169], v[122:125]
	v_mfma_f32_16x16x32_bf16 v[110:113], v[130:133], v[170:173], v[110:113]
	v_mfma_f32_16x16x32_bf16 v[110:113], v[134:137], v[174:177], v[110:113]
	v_mfma_f32_16x16x32_bf16 v[106:109], v[138:141], v[170:173], v[106:109]
	v_mfma_f32_16x16x32_bf16 v[106:109], v[142:145], v[174:177], v[106:109]
	v_mfma_f32_16x16x32_bf16 v[94:97], v[130:133], v[194:197], v[94:97]
	v_mfma_f32_16x16x32_bf16 v[94:97], v[134:137], v[198:201], v[94:97]
	v_mfma_f32_16x16x32_bf16 v[90:93], v[138:141], v[194:197], v[90:93]
	v_mfma_f32_16x16x32_bf16 v[90:93], v[142:145], v[198:201], v[90:93]
	v_mfma_f32_16x16x32_bf16 v[78:81], v[130:133], v[202:205], v[78:81]
	v_mfma_f32_16x16x32_bf16 v[78:81], v[134:137], v[216:219], v[78:81]
	v_mfma_f32_16x16x32_bf16 v[74:77], v[138:141], v[202:205], v[74:77]
	v_mfma_f32_16x16x32_bf16 v[74:77], v[142:145], v[216:219], v[74:77]
	s_setprio 0
	s_setprio 1
	v_mfma_f32_16x16x32_bf16 v[118:121], v[146:149], v[162:165], v[118:121]
	v_mfma_f32_16x16x32_bf16 v[118:121], v[150:153], v[166:169], v[118:121]
	v_mfma_f32_16x16x32_bf16 v[114:117], v[154:157], v[162:165], v[114:117]
	v_mfma_f32_16x16x32_bf16 v[114:117], v[158:161], v[166:169], v[114:117]
	v_mfma_f32_16x16x32_bf16 v[102:105], v[146:149], v[170:173], v[102:105]
	v_mfma_f32_16x16x32_bf16 v[102:105], v[150:153], v[174:177], v[102:105]
	v_mfma_f32_16x16x32_bf16 v[98:101], v[154:157], v[170:173], v[98:101]
	v_mfma_f32_16x16x32_bf16 v[98:101], v[158:161], v[174:177], v[98:101]
	v_mfma_f32_16x16x32_bf16 v[86:89], v[146:149], v[194:197], v[86:89]
	v_mfma_f32_16x16x32_bf16 v[86:89], v[150:153], v[198:201], v[86:89]
	v_mfma_f32_16x16x32_bf16 v[82:85], v[154:157], v[194:197], v[82:85]
	v_mfma_f32_16x16x32_bf16 v[82:85], v[158:161], v[198:201], v[82:85]
	v_mfma_f32_16x16x32_bf16 v[70:73], v[146:149], v[202:205], v[70:73]
	v_mfma_f32_16x16x32_bf16 v[70:73], v[150:153], v[216:219], v[70:73]
	v_mfma_f32_16x16x32_bf16 v[66:69], v[154:157], v[202:205], v[66:69]
	v_mfma_f32_16x16x32_bf16 v[66:69], v[158:161], v[216:219], v[66:69]
	s_setprio 0
	s_barrier
	s_add_i32 s0, s52, s37
	v_lshl_add_u64 v[220:221], v[220:221], 0, s[14:15]
	s_mov_b32 m0, s0
	ds_read_b128 v[162:165], v213 offset:49152
	ds_read_b128 v[166:169], v213 offset:50176
	ds_read_b128 v[170:173], v213 offset:51200
	ds_read_b128 v[174:177], v213 offset:52224
	ds_read_b128 v[194:197], v213 offset:53248
	ds_read_b128 v[198:201], v213 offset:54272
	ds_read_b128 v[202:205], v213 offset:55296
	ds_read_b128 v[216:219], v213 offset:56320
	global_load_lds_dwordx4 v[220:221], off
	s_add_i32 m0, s0, 0x2000
	s_add_u32 s0, s2, 0x40080
	v_lshl_add_u64 v[220:221], v[222:223], 0, s[14:15]
	s_addc_u32 s1, s3, 0
	s_add_i32 s2, s53, s37
	global_load_lds_dwordx4 v[220:221], off
	v_lshl_add_u64 v[220:221], s[0:1], 0, v[180:181]
	s_mov_b32 m0, s2
	s_nop 0
	global_load_lds_dwordx4 v[220:221], off
	v_lshl_add_u64 v[220:221], s[0:1], 0, v[184:185]
	s_add_i32 m0, s2, 0x2000
	s_nop 0
	global_load_lds_dwordx4 v[220:221], off
	v_lshl_add_u64 v[220:221], v[224:225], 0, s[14:15]
	s_mov_b32 m0, s42
	s_nop 0
	global_load_lds_dwordx4 v[220:221], off
	v_lshl_add_u64 v[220:221], v[226:227], 0, s[14:15]
	s_mov_b32 m0, s43
	s_nop 0
	global_load_lds_dwordx4 v[220:221], off
	s_waitcnt vmcnt(8)
	s_waitcnt lgkmcnt(0)
	s_barrier
	s_setprio 1
	s_waitcnt lgkmcnt(0)
	v_mfma_f32_16x16x32_bf16 v[62:65], v[130:133], v[162:165], v[62:65]
	v_mfma_f32_16x16x32_bf16 v[62:65], v[134:137], v[166:169], v[62:65]
	v_mfma_f32_16x16x32_bf16 v[58:61], v[138:141], v[162:165], v[58:61]
	v_mfma_f32_16x16x32_bf16 v[58:61], v[142:145], v[166:169], v[58:61]
	v_mfma_f32_16x16x32_bf16 v[46:49], v[130:133], v[170:173], v[46:49]
	v_mfma_f32_16x16x32_bf16 v[46:49], v[134:137], v[174:177], v[46:49]
	v_mfma_f32_16x16x32_bf16 v[42:45], v[138:141], v[170:173], v[42:45]
	v_mfma_f32_16x16x32_bf16 v[42:45], v[142:145], v[174:177], v[42:45]
	v_mfma_f32_16x16x32_bf16 v[30:33], v[130:133], v[194:197], v[30:33]
	v_mfma_f32_16x16x32_bf16 v[30:33], v[134:137], v[198:201], v[30:33]
	v_mfma_f32_16x16x32_bf16 v[26:29], v[138:141], v[194:197], v[26:29]
	v_mfma_f32_16x16x32_bf16 v[26:29], v[142:145], v[198:201], v[26:29]
	v_mfma_f32_16x16x32_bf16 v[14:17], v[130:133], v[202:205], v[14:17]
	v_mfma_f32_16x16x32_bf16 v[14:17], v[134:137], v[216:219], v[14:17]
	v_mfma_f32_16x16x32_bf16 v[10:13], v[138:141], v[202:205], v[10:13]
	v_mfma_f32_16x16x32_bf16 v[10:13], v[142:145], v[216:219], v[10:13]
	s_setprio 0
	s_setprio 1
	v_mfma_f32_16x16x32_bf16 v[54:57], v[146:149], v[162:165], v[54:57]
	s_add_i32 s51, s51, 2
	s_add_u32 s28, s28, 0x100
	s_addc_u32 s29, s29, 0
	s_add_u32 s49, s49, 0x100
	s_addc_u32 s50, s50, 0
	s_cmp_gt_u32 s51, 13
	v_mfma_f32_16x16x32_bf16 v[54:57], v[150:153], v[166:169], v[54:57]
	v_mfma_f32_16x16x32_bf16 v[50:53], v[154:157], v[162:165], v[50:53]
	v_mfma_f32_16x16x32_bf16 v[50:53], v[158:161], v[166:169], v[50:53]
	v_mfma_f32_16x16x32_bf16 v[38:41], v[146:149], v[170:173], v[38:41]
	v_mfma_f32_16x16x32_bf16 v[38:41], v[150:153], v[174:177], v[38:41]
	v_mfma_f32_16x16x32_bf16 v[34:37], v[154:157], v[170:173], v[34:37]
	v_mfma_f32_16x16x32_bf16 v[34:37], v[158:161], v[174:177], v[34:37]
	v_mfma_f32_16x16x32_bf16 v[22:25], v[146:149], v[194:197], v[22:25]
	v_mfma_f32_16x16x32_bf16 v[22:25], v[150:153], v[198:201], v[22:25]
	v_mfma_f32_16x16x32_bf16 v[18:21], v[154:157], v[194:197], v[18:21]
	v_mfma_f32_16x16x32_bf16 v[18:21], v[158:161], v[198:201], v[18:21]
	v_mfma_f32_16x16x32_bf16 v[6:9], v[146:149], v[202:205], v[6:9]
	v_mfma_f32_16x16x32_bf16 v[6:9], v[150:153], v[216:219], v[6:9]
	v_mfma_f32_16x16x32_bf16 v[2:5], v[154:157], v[202:205], v[2:5]
	v_mfma_f32_16x16x32_bf16 v[2:5], v[158:161], v[216:219], v[2:5]
	s_setprio 0
	s_barrier
	s_cbranch_scc0 .LBB0_382
	s_and_b64 vcc, exec, s[16:17]
	s_cbranch_vccz .LBB0_385
	s_barrier

.LBB0_471:
	ds_read_b128 v[148:151], v167
	ds_read_b128 v[152:155], v167 offset:1024
	ds_read_b128 v[156:159], v167 offset:2048
	ds_read_b128 v[160:163], v167 offset:3072
	ds_read_b128 v[172:175], v168
	ds_read_b128 v[176:179], v168 offset:1024
	ds_read_b128 v[180:183], v168 offset:2048
	ds_read_b128 v[184:187], v168 offset:3072
	s_add_u32 s0, s28, 0xfffc0080
	s_addc_u32 s1, s29, -1
	s_cmp_eq_u32 s53, 12
	s_cselect_b32 s31, s21, s1
	s_cselect_b32 s30, s49, s0
	s_cselect_b32 s3, s19, s52
	s_cselect_b32 s2, s50, s51
	v_lshl_add_u64 v[220:221], s[28:29], 0, v[140:141]
	s_add_i32 m0, s38, 0xc000
	ds_read_b128 v[188:191], v169
	ds_read_b128 v[192:195], v169 offset:1024
	ds_read_b128 v[196:199], v169 offset:2048
	ds_read_b128 v[200:203], v169 offset:3072
	ds_read_b128 v[204:207], v169 offset:4096
	ds_read_b128 v[208:211], v169 offset:5120
	ds_read_b128 v[212:215], v169 offset:6144
	ds_read_b128 v[216:219], v169 offset:7168
	global_load_lds_dwordx4 v[220:221], off
	v_lshl_add_u64 v[220:221], s[28:29], 0, v[142:143]
	s_add_i32 m0, s38, 0xe000
	s_nop 0
	global_load_lds_dwordx4 v[220:221], off
	s_waitcnt vmcnt(8)
	s_waitcnt lgkmcnt(0)
	s_barrier
	s_setprio 1
	s_waitcnt lgkmcnt(0)
	v_mfma_f32_16x16x32_bf16 v[126:129], v[148:151], v[188:191], v[126:129]
	v_mfma_f32_16x16x32_bf16 v[126:129], v[152:155], v[192:195], v[126:129]
	v_mfma_f32_16x16x32_bf16 v[118:121], v[156:159], v[188:191], v[118:121]
	v_mfma_f32_16x16x32_bf16 v[118:121], v[160:163], v[192:195], v[118:121]
	v_mfma_f32_16x16x32_bf16 v[110:113], v[148:151], v[196:199], v[110:113]
	v_mfma_f32_16x16x32_bf16 v[110:113], v[152:155], v[200:203], v[110:113]
	v_mfma_f32_16x16x32_bf16 v[102:105], v[156:159], v[196:199], v[102:105]
	v_mfma_f32_16x16x32_bf16 v[102:105], v[160:163], v[200:203], v[102:105]
	v_mfma_f32_16x16x32_bf16 v[94:97], v[148:151], v[204:207], v[94:97]
	v_mfma_f32_16x16x32_bf16 v[94:97], v[152:155], v[208:211], v[94:97]
	v_mfma_f32_16x16x32_bf16 v[86:89], v[156:159], v[204:207], v[86:89]
	v_mfma_f32_16x16x32_bf16 v[86:89], v[160:163], v[208:211], v[86:89]
	v_mfma_f32_16x16x32_bf16 v[78:81], v[148:151], v[212:215], v[78:81]
	v_mfma_f32_16x16x32_bf16 v[78:81], v[152:155], v[216:219], v[78:81]
	v_mfma_f32_16x16x32_bf16 v[70:73], v[156:159], v[212:215], v[70:73]
	v_mfma_f32_16x16x32_bf16 v[70:73], v[160:163], v[216:219], v[70:73]
	s_setprio 0
	s_setprio 1
	v_mfma_f32_16x16x32_bf16 v[122:125], v[172:175], v[188:191], v[122:125]
	v_mfma_f32_16x16x32_bf16 v[122:125], v[176:179], v[192:195], v[122:125]
	v_mfma_f32_16x16x32_bf16 v[114:117], v[180:183], v[188:191], v[114:117]
	v_mfma_f32_16x16x32_bf16 v[114:117], v[184:187], v[192:195], v[114:117]
	v_mfma_f32_16x16x32_bf16 v[106:109], v[172:175], v[196:199], v[106:109]
	v_mfma_f32_16x16x32_bf16 v[106:109], v[176:179], v[200:203], v[106:109]
	v_mfma_f32_16x16x32_bf16 v[98:101], v[180:183], v[196:199], v[98:101]
	v_mfma_f32_16x16x32_bf16 v[98:101], v[184:187], v[200:203], v[98:101]
	v_mfma_f32_16x16x32_bf16 v[90:93], v[172:175], v[204:207], v[90:93]
	v_mfma_f32_16x16x32_bf16 v[90:93], v[176:179], v[208:211], v[90:93]
	v_mfma_f32_16x16x32_bf16 v[82:85], v[180:183], v[204:207], v[82:85]
	v_mfma_f32_16x16x32_bf16 v[82:85], v[184:187], v[208:211], v[82:85]
	v_mfma_f32_16x16x32_bf16 v[74:77], v[172:175], v[212:215], v[74:77]
	v_mfma_f32_16x16x32_bf16 v[74:77], v[176:179], v[216:219], v[74:77]
	v_mfma_f32_16x16x32_bf16 v[66:69], v[180:183], v[212:215], v[66:69]
	v_mfma_f32_16x16x32_bf16 v[66:69], v[184:187], v[216:219], v[66:69]
	s_setprio 0
	s_barrier
	s_add_i32 s0, s45, s35
	v_lshl_add_u64 v[220:221], s[2:3], 0, v[134:135]
	s_mov_b32 m0, s0
	ds_read_b128 v[188:191], v169 offset:16384
	ds_read_b128 v[192:195], v169 offset:17408
	ds_read_b128 v[196:199], v169 offset:18432
	ds_read_b128 v[200:203], v169 offset:19456
	ds_read_b128 v[204:207], v169 offset:20480
	ds_read_b128 v[208:211], v169 offset:21504
	ds_read_b128 v[212:215], v169 offset:22528
	ds_read_b128 v[216:219], v169 offset:23552
	global_load_lds_dwordx4 v[220:221], off
	s_add_i32 m0, s0, 0x2000
	s_add_u32 s0, s2, 0x40000
	v_lshl_add_u64 v[222:223], s[2:3], 0, v[130:131]
	s_addc_u32 s1, s3, 0
	s_add_i32 s54, s46, s35
	global_load_lds_dwordx4 v[222:223], off
	v_lshl_add_u64 v[224:225], s[0:1], 0, v[134:135]
	s_mov_b32 m0, s54
	v_lshl_add_u64 v[226:227], s[30:31], 0, v[132:133]
	global_load_lds_dwordx4 v[224:225], off
	v_lshl_add_u64 v[224:225], s[0:1], 0, v[130:131]
	s_add_i32 m0, s54, 0x2000
	s_nop 0
	global_load_lds_dwordx4 v[224:225], off
	v_lshl_add_u64 v[224:225], s[30:31], 0, v[136:137]
	s_mov_b32 m0, s38
	s_nop 0
	global_load_lds_dwordx4 v[224:225], off
	s_mov_b32 m0, s39
	s_nop 0
	global_load_lds_dwordx4 v[226:227], off
	s_waitcnt vmcnt(8)
	s_waitcnt lgkmcnt(0)
	s_barrier
	s_setprio 1
	s_waitcnt lgkmcnt(0)
	v_mfma_f32_16x16x32_bf16 v[62:65], v[148:151], v[188:191], v[62:65]
	v_mfma_f32_16x16x32_bf16 v[62:65], v[152:155], v[192:195], v[62:65]
	v_mfma_f32_16x16x32_bf16 v[54:57], v[156:159], v[188:191], v[54:57]
	v_mfma_f32_16x16x32_bf16 v[54:57], v[160:163], v[192:195], v[54:57]
	v_mfma_f32_16x16x32_bf16 v[46:49], v[148:151], v[196:199], v[46:49]
	v_mfma_f32_16x16x32_bf16 v[46:49], v[152:155], v[200:203], v[46:49]
	v_mfma_f32_16x16x32_bf16 v[38:41], v[156:159], v[196:199], v[38:41]
	v_mfma_f32_16x16x32_bf16 v[38:41], v[160:163], v[200:203], v[38:41]
	v_mfma_f32_16x16x32_bf16 v[30:33], v[148:151], v[204:207], v[30:33]
	v_mfma_f32_16x16x32_bf16 v[30:33], v[152:155], v[208:211], v[30:33]
	v_mfma_f32_16x16x32_bf16 v[22:25], v[156:159], v[204:207], v[22:25]
	v_mfma_f32_16x16x32_bf16 v[22:25], v[160:163], v[208:211], v[22:25]
	v_mfma_f32_16x16x32_bf16 v[14:17], v[148:151], v[212:215], v[14:17]
	v_mfma_f32_16x16x32_bf16 v[14:17], v[152:155], v[216:219], v[14:17]
	v_mfma_f32_16x16x32_bf16 v[6:9], v[156:159], v[212:215], v[6:9]
	v_mfma_f32_16x16x32_bf16 v[6:9], v[160:163], v[216:219], v[6:9]
	s_setprio 0
	s_setprio 1
	v_mfma_f32_16x16x32_bf16 v[58:61], v[172:175], v[188:191], v[58:61]
	v_mfma_f32_16x16x32_bf16 v[58:61], v[176:179], v[192:195], v[58:61]
	v_mfma_f32_16x16x32_bf16 v[50:53], v[180:183], v[188:191], v[50:53]
	v_mfma_f32_16x16x32_bf16 v[50:53], v[184:187], v[192:195], v[50:53]
	v_mfma_f32_16x16x32_bf16 v[42:45], v[172:175], v[196:199], v[42:45]
	v_mfma_f32_16x16x32_bf16 v[42:45], v[176:179], v[200:203], v[42:45]
	v_mfma_f32_16x16x32_bf16 v[34:37], v[180:183], v[196:199], v[34:37]
	v_mfma_f32_16x16x32_bf16 v[34:37], v[184:187], v[200:203], v[34:37]
	v_mfma_f32_16x16x32_bf16 v[26:29], v[172:175], v[204:207], v[26:29]
	v_mfma_f32_16x16x32_bf16 v[26:29], v[176:179], v[208:211], v[26:29]
	v_mfma_f32_16x16x32_bf16 v[18:21], v[180:183], v[204:207], v[18:21]
	v_mfma_f32_16x16x32_bf16 v[18:21], v[184:187], v[208:211], v[18:21]
	v_mfma_f32_16x16x32_bf16 v[10:13], v[172:175], v[212:215], v[10:13]
	v_mfma_f32_16x16x32_bf16 v[10:13], v[176:179], v[216:219], v[10:13]
	v_mfma_f32_16x16x32_bf16 v[2:5], v[180:183], v[212:215], v[2:5]
	v_mfma_f32_16x16x32_bf16 v[2:5], v[184:187], v[216:219], v[2:5]
	s_setprio 0
	s_barrier
	s_add_i32 s54, 0, 0x18000
	s_add_i32 s55, 0, 0x1c000
	v_add_u32_e32 v160, s54, v166
	v_add_u32_e32 v171, s55, v166
	ds_read_b128 v[148:151], v160
	ds_read_b128 v[152:155], v160 offset:1024
	ds_read_b128 v[156:159], v160 offset:2048
	ds_read_b128 v[160:163], v160 offset:3072
	ds_read_b128 v[172:175], v171
	ds_read_b128 v[176:179], v171 offset:1024
	ds_read_b128 v[180:183], v171 offset:2048
	ds_read_b128 v[184:187], v171 offset:3072
	s_add_u32 s0, s30, 0x40000
	s_addc_u32 s1, s31, 0
	s_mov_b32 m0, s40
	v_lshl_add_u64 v[228:229], s[0:1], 0, v[136:137]
	ds_read_b128 v[188:191], v169 offset:32768
	ds_read_b128 v[192:195], v169 offset:33792
	ds_read_b128 v[196:199], v169 offset:34816
	ds_read_b128 v[200:203], v169 offset:35840
	ds_read_b128 v[204:207], v169 offset:36864
	ds_read_b128 v[208:211], v169 offset:37888
	ds_read_b128 v[212:215], v169 offset:38912
	ds_read_b128 v[216:219], v169 offset:39936
	global_load_lds_dwordx4 v[228:229], off
	v_lshl_add_u64 v[228:229], s[0:1], 0, v[132:133]
	s_mov_b32 m0, s41
	s_nop 0
	global_load_lds_dwordx4 v[228:229], off
	s_waitcnt vmcnt(8)
	s_waitcnt lgkmcnt(0)
	s_barrier
	s_setprio 1
	s_waitcnt lgkmcnt(0)
	v_mfma_f32_16x16x32_bf16 v[126:129], v[148:151], v[188:191], v[126:129]
	v_mfma_f32_16x16x32_bf16 v[126:129], v[152:155], v[192:195], v[126:129]
	v_mfma_f32_16x16x32_bf16 v[118:121], v[156:159], v[188:191], v[118:121]
	v_mfma_f32_16x16x32_bf16 v[118:121], v[160:163], v[192:195], v[118:121]
	v_mfma_f32_16x16x32_bf16 v[110:113], v[148:151], v[196:199], v[110:113]
	v_mfma_f32_16x16x32_bf16 v[110:113], v[152:155], v[200:203], v[110:113]
	v_mfma_f32_16x16x32_bf16 v[102:105], v[156:159], v[196:199], v[102:105]
	v_mfma_f32_16x16x32_bf16 v[102:105], v[160:163], v[200:203], v[102:105]
	v_mfma_f32_16x16x32_bf16 v[94:97], v[148:151], v[204:207], v[94:97]
	v_mfma_f32_16x16x32_bf16 v[94:97], v[152:155], v[208:211], v[94:97]
	v_mfma_f32_16x16x32_bf16 v[86:89], v[156:159], v[204:207], v[86:89]
	v_mfma_f32_16x16x32_bf16 v[86:89], v[160:163], v[208:211], v[86:89]
	v_mfma_f32_16x16x32_bf16 v[78:81], v[148:151], v[212:215], v[78:81]
	v_mfma_f32_16x16x32_bf16 v[78:81], v[152:155], v[216:219], v[78:81]
	v_mfma_f32_16x16x32_bf16 v[70:73], v[156:159], v[212:215], v[70:73]
	v_mfma_f32_16x16x32_bf16 v[70:73], v[160:163], v[216:219], v[70:73]
	s_setprio 0
	s_setprio 1
	v_mfma_f32_16x16x32_bf16 v[122:125], v[172:175], v[188:191], v[122:125]
	v_mfma_f32_16x16x32_bf16 v[122:125], v[176:179], v[192:195], v[122:125]
	v_mfma_f32_16x16x32_bf16 v[114:117], v[180:183], v[188:191], v[114:117]
	v_mfma_f32_16x16x32_bf16 v[114:117], v[184:187], v[192:195], v[114:117]
	v_mfma_f32_16x16x32_bf16 v[106:109], v[172:175], v[196:199], v[106:109]
	v_mfma_f32_16x16x32_bf16 v[106:109], v[176:179], v[200:203], v[106:109]
	v_mfma_f32_16x16x32_bf16 v[98:101], v[180:183], v[196:199], v[98:101]
	v_mfma_f32_16x16x32_bf16 v[98:101], v[184:187], v[200:203], v[98:101]
	v_mfma_f32_16x16x32_bf16 v[90:93], v[172:175], v[204:207], v[90:93]
	v_mfma_f32_16x16x32_bf16 v[90:93], v[176:179], v[208:211], v[90:93]
	v_mfma_f32_16x16x32_bf16 v[82:85], v[180:183], v[204:207], v[82:85]
	v_mfma_f32_16x16x32_bf16 v[82:85], v[184:187], v[208:211], v[82:85]
	v_mfma_f32_16x16x32_bf16 v[74:77], v[172:175], v[212:215], v[74:77]
	v_mfma_f32_16x16x32_bf16 v[74:77], v[176:179], v[216:219], v[74:77]
	v_mfma_f32_16x16x32_bf16 v[66:69], v[180:183], v[212:215], v[66:69]
	v_mfma_f32_16x16x32_bf16 v[66:69], v[184:187], v[216:219], v[66:69]
	s_setprio 0
	s_barrier
	s_add_i32 s0, s54, s35
	v_lshl_add_u64 v[220:221], v[220:221], 0, s[14:15]
	s_mov_b32 m0, s0
	ds_read_b128 v[188:191], v169 offset:49152
	ds_read_b128 v[192:195], v169 offset:50176
	ds_read_b128 v[196:199], v169 offset:51200
	ds_read_b128 v[200:203], v169 offset:52224
	ds_read_b128 v[204:207], v169 offset:53248
	ds_read_b128 v[208:211], v169 offset:54272
	ds_read_b128 v[212:215], v169 offset:55296
	ds_read_b128 v[216:219], v169 offset:56320
	global_load_lds_dwordx4 v[220:221], off
	s_add_i32 m0, s0, 0x2000
	s_add_u32 s0, s2, 0x40080
	v_lshl_add_u64 v[220:221], v[222:223], 0, s[14:15]
	s_addc_u32 s1, s3, 0
	s_add_i32 s2, s55, s35
	global_load_lds_dwordx4 v[220:221], off
	v_lshl_add_u64 v[220:221], s[0:1], 0, v[134:135]
	s_mov_b32 m0, s2
	s_nop 0
	global_load_lds_dwordx4 v[220:221], off
	v_lshl_add_u64 v[220:221], s[0:1], 0, v[130:131]
	s_add_i32 m0, s2, 0x2000
	s_nop 0
	global_load_lds_dwordx4 v[220:221], off
	v_lshl_add_u64 v[220:221], v[224:225], 0, s[14:15]
	s_mov_b32 m0, s42
	s_nop 0
	global_load_lds_dwordx4 v[220:221], off
	v_lshl_add_u64 v[220:221], v[226:227], 0, s[14:15]
	s_mov_b32 m0, s43
	s_nop 0
	global_load_lds_dwordx4 v[220:221], off
	s_waitcnt vmcnt(8)
	s_waitcnt lgkmcnt(0)
	s_barrier
	s_setprio 1
	s_waitcnt lgkmcnt(0)
	v_mfma_f32_16x16x32_bf16 v[62:65], v[148:151], v[188:191], v[62:65]
	v_mfma_f32_16x16x32_bf16 v[62:65], v[152:155], v[192:195], v[62:65]
	v_mfma_f32_16x16x32_bf16 v[54:57], v[156:159], v[188:191], v[54:57]
	v_mfma_f32_16x16x32_bf16 v[54:57], v[160:163], v[192:195], v[54:57]
	v_mfma_f32_16x16x32_bf16 v[46:49], v[148:151], v[196:199], v[46:49]
	v_mfma_f32_16x16x32_bf16 v[46:49], v[152:155], v[200:203], v[46:49]
	v_mfma_f32_16x16x32_bf16 v[38:41], v[156:159], v[196:199], v[38:41]
	v_mfma_f32_16x16x32_bf16 v[38:41], v[160:163], v[200:203], v[38:41]
	v_mfma_f32_16x16x32_bf16 v[30:33], v[148:151], v[204:207], v[30:33]
	v_mfma_f32_16x16x32_bf16 v[30:33], v[152:155], v[208:211], v[30:33]
	v_mfma_f32_16x16x32_bf16 v[22:25], v[156:159], v[204:207], v[22:25]
	v_mfma_f32_16x16x32_bf16 v[22:25], v[160:163], v[208:211], v[22:25]
	v_mfma_f32_16x16x32_bf16 v[14:17], v[148:151], v[212:215], v[14:17]
	v_mfma_f32_16x16x32_bf16 v[14:17], v[152:155], v[216:219], v[14:17]
	v_mfma_f32_16x16x32_bf16 v[6:9], v[156:159], v[212:215], v[6:9]
	v_mfma_f32_16x16x32_bf16 v[6:9], v[160:163], v[216:219], v[6:9]
	s_setprio 0
	s_setprio 1
	v_mfma_f32_16x16x32_bf16 v[58:61], v[172:175], v[188:191], v[58:61]
	s_add_i32 s53, s53, 2
	s_add_u32 s28, s28, 0x100
	s_addc_u32 s29, s29, 0
	s_add_u32 s51, s51, 0x100
	s_addc_u32 s52, s52, 0
	s_cmp_gt_u32 s53, 13
	v_mfma_f32_16x16x32_bf16 v[58:61], v[176:179], v[192:195], v[58:61]
	v_mfma_f32_16x16x32_bf16 v[50:53], v[180:183], v[188:191], v[50:53]
	v_mfma_f32_16x16x32_bf16 v[50:53], v[184:187], v[192:195], v[50:53]
	v_mfma_f32_16x16x32_bf16 v[42:45], v[172:175], v[196:199], v[42:45]
	v_mfma_f32_16x16x32_bf16 v[42:45], v[176:179], v[200:203], v[42:45]
	v_mfma_f32_16x16x32_bf16 v[34:37], v[180:183], v[196:199], v[34:37]
	v_mfma_f32_16x16x32_bf16 v[34:37], v[184:187], v[200:203], v[34:37]
	v_mfma_f32_16x16x32_bf16 v[26:29], v[172:175], v[204:207], v[26:29]
	v_mfma_f32_16x16x32_bf16 v[26:29], v[176:179], v[208:211], v[26:29]
	v_mfma_f32_16x16x32_bf16 v[18:21], v[180:183], v[204:207], v[18:21]
	v_mfma_f32_16x16x32_bf16 v[18:21], v[184:187], v[208:211], v[18:21]
	v_mfma_f32_16x16x32_bf16 v[10:13], v[172:175], v[212:215], v[10:13]
	v_mfma_f32_16x16x32_bf16 v[10:13], v[176:179], v[216:219], v[10:13]
	v_mfma_f32_16x16x32_bf16 v[2:5], v[180:183], v[212:215], v[2:5]
	v_mfma_f32_16x16x32_bf16 v[2:5], v[184:187], v[216:219], v[2:5]
	s_setprio 0
	s_barrier
	s_cbranch_scc0 .LBB0_471
	s_and_b64 vcc, exec, s[16:17]
	s_cbranch_vccz .LBB0_474
	s_barrier

.LBB0_584:
	ds_read_b128 v[130:133], v187
	ds_read_b128 v[134:137], v187 offset:1024
	ds_read_b128 v[138:141], v187 offset:2048
	ds_read_b128 v[142:145], v187 offset:3072
	ds_read_b128 v[146:149], v188
	ds_read_b128 v[150:153], v188 offset:1024
	ds_read_b128 v[170:173], v188 offset:2048
	ds_read_b128 v[174:177], v188 offset:3072
	s_add_u32 s0, s22, 0xfff50080
	s_addc_u32 s1, s23, -1
	s_cmp_eq_u32 s47, 40
	s_cselect_b32 s25, s9, s1
	s_cselect_b32 s24, s8, s0
	s_cselect_b32 s3, s21, s46
	s_cselect_b32 s2, s20, s45
	v_lshl_add_u64 v[220:221], s[22:23], 0, v[162:163]
	s_add_i32 m0, s31, 0xc000
	ds_read_b128 v[178:181], v189
	ds_read_b128 v[192:195], v189 offset:1024
	ds_read_b128 v[196:199], v189 offset:2048
	ds_read_b128 v[200:203], v189 offset:3072
	ds_read_b128 v[204:207], v189 offset:4096
	ds_read_b128 v[208:211], v189 offset:5120
	ds_read_b128 v[212:215], v189 offset:6144
	ds_read_b128 v[216:219], v189 offset:7168
	global_load_lds_dwordx4 v[220:221], off
	v_lshl_add_u64 v[220:221], s[22:23], 0, v[164:165]
	s_add_i32 m0, s31, 0xe000
	s_nop 0
	global_load_lds_dwordx4 v[220:221], off
	s_waitcnt vmcnt(8)
	s_waitcnt lgkmcnt(0)
	s_barrier
	s_setprio 1
	s_waitcnt lgkmcnt(0)
	v_mfma_f32_16x16x32_bf16 v[126:129], v[130:133], v[178:181], v[126:129]
	v_mfma_f32_16x16x32_bf16 v[126:129], v[134:137], v[192:195], v[126:129]
	v_mfma_f32_16x16x32_bf16 v[122:125], v[138:141], v[178:181], v[122:125]
	v_mfma_f32_16x16x32_bf16 v[122:125], v[142:145], v[192:195], v[122:125]
	v_mfma_f32_16x16x32_bf16 v[110:113], v[130:133], v[196:199], v[110:113]
	v_mfma_f32_16x16x32_bf16 v[110:113], v[134:137], v[200:203], v[110:113]
	v_mfma_f32_16x16x32_bf16 v[106:109], v[138:141], v[196:199], v[106:109]
	v_mfma_f32_16x16x32_bf16 v[106:109], v[142:145], v[200:203], v[106:109]
	v_mfma_f32_16x16x32_bf16 v[94:97], v[130:133], v[204:207], v[94:97]
	v_mfma_f32_16x16x32_bf16 v[94:97], v[134:137], v[208:211], v[94:97]
	v_mfma_f32_16x16x32_bf16 v[90:93], v[138:141], v[204:207], v[90:93]
	v_mfma_f32_16x16x32_bf16 v[90:93], v[142:145], v[208:211], v[90:93]
	v_mfma_f32_16x16x32_bf16 v[78:81], v[130:133], v[212:215], v[78:81]
	v_mfma_f32_16x16x32_bf16 v[78:81], v[134:137], v[216:219], v[78:81]
	v_mfma_f32_16x16x32_bf16 v[74:77], v[138:141], v[212:215], v[74:77]
	v_mfma_f32_16x16x32_bf16 v[74:77], v[142:145], v[216:219], v[74:77]
	s_setprio 0
	s_setprio 1
	v_mfma_f32_16x16x32_bf16 v[118:121], v[146:149], v[178:181], v[118:121]
	v_mfma_f32_16x16x32_bf16 v[118:121], v[150:153], v[192:195], v[118:121]
	v_mfma_f32_16x16x32_bf16 v[114:117], v[170:173], v[178:181], v[114:117]
	v_mfma_f32_16x16x32_bf16 v[114:117], v[174:177], v[192:195], v[114:117]
	v_mfma_f32_16x16x32_bf16 v[102:105], v[146:149], v[196:199], v[102:105]
	v_mfma_f32_16x16x32_bf16 v[102:105], v[150:153], v[200:203], v[102:105]
	v_mfma_f32_16x16x32_bf16 v[98:101], v[170:173], v[196:199], v[98:101]
	v_mfma_f32_16x16x32_bf16 v[98:101], v[174:177], v[200:203], v[98:101]
	v_mfma_f32_16x16x32_bf16 v[86:89], v[146:149], v[204:207], v[86:89]
	v_mfma_f32_16x16x32_bf16 v[86:89], v[150:153], v[208:211], v[86:89]
	v_mfma_f32_16x16x32_bf16 v[82:85], v[170:173], v[204:207], v[82:85]
	v_mfma_f32_16x16x32_bf16 v[82:85], v[174:177], v[208:211], v[82:85]
	v_mfma_f32_16x16x32_bf16 v[70:73], v[146:149], v[212:215], v[70:73]
	v_mfma_f32_16x16x32_bf16 v[70:73], v[150:153], v[216:219], v[70:73]
	v_mfma_f32_16x16x32_bf16 v[66:69], v[170:173], v[212:215], v[66:69]
	v_mfma_f32_16x16x32_bf16 v[66:69], v[174:177], v[216:219], v[66:69]
	s_setprio 0
	s_barrier
	s_add_i32 s0, s41, s30
	v_lshl_add_u64 v[220:221], s[2:3], 0, v[156:157]
	s_mov_b32 m0, s0
	ds_read_b128 v[178:181], v189 offset:16384
	ds_read_b128 v[192:195], v189 offset:17408
	ds_read_b128 v[196:199], v189 offset:18432
	ds_read_b128 v[200:203], v189 offset:19456
	ds_read_b128 v[204:207], v189 offset:20480
	ds_read_b128 v[208:211], v189 offset:21504
	ds_read_b128 v[212:215], v189 offset:22528
	ds_read_b128 v[216:219], v189 offset:23552
	global_load_lds_dwordx4 v[220:221], off
	s_add_i32 m0, s0, 0x2000
	s_add_u32 s0, s2, 0xb0000
	v_lshl_add_u64 v[222:223], s[2:3], 0, v[160:161]
	s_addc_u32 s1, s3, 0
	s_add_i32 s48, s42, s30
	global_load_lds_dwordx4 v[222:223], off
	v_lshl_add_u64 v[224:225], s[0:1], 0, v[156:157]
	s_mov_b32 m0, s48
	v_lshl_add_u64 v[226:227], s[24:25], 0, v[158:159]
	global_load_lds_dwordx4 v[224:225], off
	v_lshl_add_u64 v[224:225], s[0:1], 0, v[160:161]
	s_add_i32 m0, s48, 0x2000
	s_nop 0
	global_load_lds_dwordx4 v[224:225], off
	v_lshl_add_u64 v[224:225], s[24:25], 0, v[154:155]
	s_mov_b32 m0, s31
	s_nop 0
	global_load_lds_dwordx4 v[224:225], off
	s_mov_b32 m0, s33
	s_nop 0
	global_load_lds_dwordx4 v[226:227], off
	s_waitcnt vmcnt(8)
	s_waitcnt lgkmcnt(0)
	s_barrier
	s_setprio 1
	s_waitcnt lgkmcnt(0)
	v_mfma_f32_16x16x32_bf16 v[62:65], v[130:133], v[178:181], v[62:65]
	v_mfma_f32_16x16x32_bf16 v[62:65], v[134:137], v[192:195], v[62:65]
	v_mfma_f32_16x16x32_bf16 v[58:61], v[138:141], v[178:181], v[58:61]
	v_mfma_f32_16x16x32_bf16 v[58:61], v[142:145], v[192:195], v[58:61]
	v_mfma_f32_16x16x32_bf16 v[46:49], v[130:133], v[196:199], v[46:49]
	v_mfma_f32_16x16x32_bf16 v[46:49], v[134:137], v[200:203], v[46:49]
	v_mfma_f32_16x16x32_bf16 v[42:45], v[138:141], v[196:199], v[42:45]
	v_mfma_f32_16x16x32_bf16 v[42:45], v[142:145], v[200:203], v[42:45]
	v_mfma_f32_16x16x32_bf16 v[30:33], v[130:133], v[204:207], v[30:33]
	v_mfma_f32_16x16x32_bf16 v[30:33], v[134:137], v[208:211], v[30:33]
	v_mfma_f32_16x16x32_bf16 v[26:29], v[138:141], v[204:207], v[26:29]
	v_mfma_f32_16x16x32_bf16 v[26:29], v[142:145], v[208:211], v[26:29]
	v_mfma_f32_16x16x32_bf16 v[14:17], v[130:133], v[212:215], v[14:17]
	v_mfma_f32_16x16x32_bf16 v[14:17], v[134:137], v[216:219], v[14:17]
	v_mfma_f32_16x16x32_bf16 v[10:13], v[138:141], v[212:215], v[10:13]
	v_mfma_f32_16x16x32_bf16 v[10:13], v[142:145], v[216:219], v[10:13]
	s_setprio 0
	s_setprio 1
	v_mfma_f32_16x16x32_bf16 v[54:57], v[146:149], v[178:181], v[54:57]
	v_mfma_f32_16x16x32_bf16 v[54:57], v[150:153], v[192:195], v[54:57]
	v_mfma_f32_16x16x32_bf16 v[50:53], v[170:173], v[178:181], v[50:53]
	v_mfma_f32_16x16x32_bf16 v[50:53], v[174:177], v[192:195], v[50:53]
	v_mfma_f32_16x16x32_bf16 v[38:41], v[146:149], v[196:199], v[38:41]
	v_mfma_f32_16x16x32_bf16 v[38:41], v[150:153], v[200:203], v[38:41]
	v_mfma_f32_16x16x32_bf16 v[34:37], v[170:173], v[196:199], v[34:37]
	v_mfma_f32_16x16x32_bf16 v[34:37], v[174:177], v[200:203], v[34:37]
	v_mfma_f32_16x16x32_bf16 v[22:25], v[146:149], v[204:207], v[22:25]
	v_mfma_f32_16x16x32_bf16 v[22:25], v[150:153], v[208:211], v[22:25]
	v_mfma_f32_16x16x32_bf16 v[18:21], v[170:173], v[204:207], v[18:21]
	v_mfma_f32_16x16x32_bf16 v[18:21], v[174:177], v[208:211], v[18:21]
	v_mfma_f32_16x16x32_bf16 v[6:9], v[146:149], v[212:215], v[6:9]
	v_mfma_f32_16x16x32_bf16 v[6:9], v[150:153], v[216:219], v[6:9]
	v_mfma_f32_16x16x32_bf16 v[2:5], v[170:173], v[212:215], v[2:5]
	v_mfma_f32_16x16x32_bf16 v[2:5], v[174:177], v[216:219], v[2:5]
	s_setprio 0
	s_barrier
	s_add_i32 s48, 0, 0x18000
	s_add_i32 s49, 0, 0x1c000
	v_add_u32_e32 v142, s48, v183
	v_add_u32_e32 v174, s49, v183
	ds_read_b128 v[130:133], v142
	ds_read_b128 v[134:137], v142 offset:1024
	ds_read_b128 v[138:141], v142 offset:2048
	ds_read_b128 v[142:145], v142 offset:3072
	ds_read_b128 v[146:149], v174
	ds_read_b128 v[150:153], v174 offset:1024
	ds_read_b128 v[170:173], v174 offset:2048
	ds_read_b128 v[174:177], v174 offset:3072
	s_add_u32 s0, s24, 0xb0000
	s_addc_u32 s1, s25, 0
	s_mov_b32 m0, s34
	v_lshl_add_u64 v[228:229], s[0:1], 0, v[154:155]
	ds_read_b128 v[178:181], v189 offset:32768
	ds_read_b128 v[192:195], v189 offset:33792
	ds_read_b128 v[196:199], v189 offset:34816
	ds_read_b128 v[200:203], v189 offset:35840
	ds_read_b128 v[204:207], v189 offset:36864
	ds_read_b128 v[208:211], v189 offset:37888
	ds_read_b128 v[212:215], v189 offset:38912
	ds_read_b128 v[216:219], v189 offset:39936
	global_load_lds_dwordx4 v[228:229], off
	v_lshl_add_u64 v[228:229], s[0:1], 0, v[158:159]
	s_mov_b32 m0, s35
	s_nop 0
	global_load_lds_dwordx4 v[228:229], off
	s_waitcnt vmcnt(8)
	s_waitcnt lgkmcnt(0)
	s_barrier
	s_setprio 1
	s_waitcnt lgkmcnt(0)
	v_mfma_f32_16x16x32_bf16 v[126:129], v[130:133], v[178:181], v[126:129]
	v_mfma_f32_16x16x32_bf16 v[126:129], v[134:137], v[192:195], v[126:129]
	v_mfma_f32_16x16x32_bf16 v[122:125], v[138:141], v[178:181], v[122:125]
	v_mfma_f32_16x16x32_bf16 v[122:125], v[142:145], v[192:195], v[122:125]
	v_mfma_f32_16x16x32_bf16 v[110:113], v[130:133], v[196:199], v[110:113]
	v_mfma_f32_16x16x32_bf16 v[110:113], v[134:137], v[200:203], v[110:113]
	v_mfma_f32_16x16x32_bf16 v[106:109], v[138:141], v[196:199], v[106:109]
	v_mfma_f32_16x16x32_bf16 v[106:109], v[142:145], v[200:203], v[106:109]
	v_mfma_f32_16x16x32_bf16 v[94:97], v[130:133], v[204:207], v[94:97]
	v_mfma_f32_16x16x32_bf16 v[94:97], v[134:137], v[208:211], v[94:97]
	v_mfma_f32_16x16x32_bf16 v[90:93], v[138:141], v[204:207], v[90:93]
	v_mfma_f32_16x16x32_bf16 v[90:93], v[142:145], v[208:211], v[90:93]
	v_mfma_f32_16x16x32_bf16 v[78:81], v[130:133], v[212:215], v[78:81]
	v_mfma_f32_16x16x32_bf16 v[78:81], v[134:137], v[216:219], v[78:81]
	v_mfma_f32_16x16x32_bf16 v[74:77], v[138:141], v[212:215], v[74:77]
	v_mfma_f32_16x16x32_bf16 v[74:77], v[142:145], v[216:219], v[74:77]
	s_setprio 0
	s_setprio 1
	v_mfma_f32_16x16x32_bf16 v[118:121], v[146:149], v[178:181], v[118:121]
	v_mfma_f32_16x16x32_bf16 v[118:121], v[150:153], v[192:195], v[118:121]
	v_mfma_f32_16x16x32_bf16 v[114:117], v[170:173], v[178:181], v[114:117]
	v_mfma_f32_16x16x32_bf16 v[114:117], v[174:177], v[192:195], v[114:117]
	v_mfma_f32_16x16x32_bf16 v[102:105], v[146:149], v[196:199], v[102:105]
	v_mfma_f32_16x16x32_bf16 v[102:105], v[150:153], v[200:203], v[102:105]
	v_mfma_f32_16x16x32_bf16 v[98:101], v[170:173], v[196:199], v[98:101]
	v_mfma_f32_16x16x32_bf16 v[98:101], v[174:177], v[200:203], v[98:101]
	v_mfma_f32_16x16x32_bf16 v[86:89], v[146:149], v[204:207], v[86:89]
	v_mfma_f32_16x16x32_bf16 v[86:89], v[150:153], v[208:211], v[86:89]
	v_mfma_f32_16x16x32_bf16 v[82:85], v[170:173], v[204:207], v[82:85]
	v_mfma_f32_16x16x32_bf16 v[82:85], v[174:177], v[208:211], v[82:85]
	v_mfma_f32_16x16x32_bf16 v[70:73], v[146:149], v[212:215], v[70:73]
	v_mfma_f32_16x16x32_bf16 v[70:73], v[150:153], v[216:219], v[70:73]
	v_mfma_f32_16x16x32_bf16 v[66:69], v[170:173], v[212:215], v[66:69]
	v_mfma_f32_16x16x32_bf16 v[66:69], v[174:177], v[216:219], v[66:69]
	s_setprio 0
	s_barrier
	s_add_i32 s0, s48, s30
	v_lshl_add_u64 v[220:221], v[220:221], 0, s[16:17]
	s_mov_b32 m0, s0
	ds_read_b128 v[178:181], v189 offset:49152
	ds_read_b128 v[192:195], v189 offset:50176
	ds_read_b128 v[196:199], v189 offset:51200
	ds_read_b128 v[200:203], v189 offset:52224
	ds_read_b128 v[204:207], v189 offset:53248
	ds_read_b128 v[208:211], v189 offset:54272
	ds_read_b128 v[212:215], v189 offset:55296
	ds_read_b128 v[216:219], v189 offset:56320
	global_load_lds_dwordx4 v[220:221], off
	s_add_i32 m0, s0, 0x2000
	s_add_u32 s0, s2, 0xb0080
	v_lshl_add_u64 v[220:221], v[222:223], 0, s[16:17]
	s_addc_u32 s1, s3, 0
	s_add_i32 s2, s49, s30
	global_load_lds_dwordx4 v[220:221], off
	v_lshl_add_u64 v[220:221], s[0:1], 0, v[156:157]
	s_mov_b32 m0, s2
	s_nop 0
	global_load_lds_dwordx4 v[220:221], off
	v_lshl_add_u64 v[220:221], s[0:1], 0, v[160:161]
	s_add_i32 m0, s2, 0x2000
	s_nop 0
	global_load_lds_dwordx4 v[220:221], off
	v_lshl_add_u64 v[220:221], v[224:225], 0, s[16:17]
	s_mov_b32 m0, s37
	s_nop 0
	global_load_lds_dwordx4 v[220:221], off
	v_lshl_add_u64 v[220:221], v[226:227], 0, s[16:17]
	s_mov_b32 m0, s38
	s_nop 0
	global_load_lds_dwordx4 v[220:221], off
	s_waitcnt vmcnt(8)
	s_waitcnt lgkmcnt(0)
	s_barrier
	s_setprio 1
	s_waitcnt lgkmcnt(0)
	v_mfma_f32_16x16x32_bf16 v[62:65], v[130:133], v[178:181], v[62:65]
	v_mfma_f32_16x16x32_bf16 v[62:65], v[134:137], v[192:195], v[62:65]
	v_mfma_f32_16x16x32_bf16 v[58:61], v[138:141], v[178:181], v[58:61]
	v_mfma_f32_16x16x32_bf16 v[58:61], v[142:145], v[192:195], v[58:61]
	v_mfma_f32_16x16x32_bf16 v[46:49], v[130:133], v[196:199], v[46:49]
	v_mfma_f32_16x16x32_bf16 v[46:49], v[134:137], v[200:203], v[46:49]
	v_mfma_f32_16x16x32_bf16 v[42:45], v[138:141], v[196:199], v[42:45]
	v_mfma_f32_16x16x32_bf16 v[42:45], v[142:145], v[200:203], v[42:45]
	v_mfma_f32_16x16x32_bf16 v[30:33], v[130:133], v[204:207], v[30:33]
	v_mfma_f32_16x16x32_bf16 v[30:33], v[134:137], v[208:211], v[30:33]
	v_mfma_f32_16x16x32_bf16 v[26:29], v[138:141], v[204:207], v[26:29]
	v_mfma_f32_16x16x32_bf16 v[26:29], v[142:145], v[208:211], v[26:29]
	v_mfma_f32_16x16x32_bf16 v[14:17], v[130:133], v[212:215], v[14:17]
	v_mfma_f32_16x16x32_bf16 v[14:17], v[134:137], v[216:219], v[14:17]
	v_mfma_f32_16x16x32_bf16 v[10:13], v[138:141], v[212:215], v[10:13]
	v_mfma_f32_16x16x32_bf16 v[10:13], v[142:145], v[216:219], v[10:13]
	s_setprio 0
	s_setprio 1
	v_mfma_f32_16x16x32_bf16 v[54:57], v[146:149], v[178:181], v[54:57]
	s_add_i32 s47, s47, 2
	s_add_u32 s22, s22, 0x100
	s_addc_u32 s23, s23, 0
	s_add_u32 s45, s45, 0x100
	s_addc_u32 s46, s46, 0
	s_cmp_gt_u32 s47, 41
	v_mfma_f32_16x16x32_bf16 v[54:57], v[150:153], v[192:195], v[54:57]
	v_mfma_f32_16x16x32_bf16 v[50:53], v[170:173], v[178:181], v[50:53]
	v_mfma_f32_16x16x32_bf16 v[50:53], v[174:177], v[192:195], v[50:53]
	v_mfma_f32_16x16x32_bf16 v[38:41], v[146:149], v[196:199], v[38:41]
	v_mfma_f32_16x16x32_bf16 v[38:41], v[150:153], v[200:203], v[38:41]
	v_mfma_f32_16x16x32_bf16 v[34:37], v[170:173], v[196:199], v[34:37]
	v_mfma_f32_16x16x32_bf16 v[34:37], v[174:177], v[200:203], v[34:37]
	v_mfma_f32_16x16x32_bf16 v[22:25], v[146:149], v[204:207], v[22:25]
	v_mfma_f32_16x16x32_bf16 v[22:25], v[150:153], v[208:211], v[22:25]
	v_mfma_f32_16x16x32_bf16 v[18:21], v[170:173], v[204:207], v[18:21]
	v_mfma_f32_16x16x32_bf16 v[18:21], v[174:177], v[208:211], v[18:21]
	v_mfma_f32_16x16x32_bf16 v[6:9], v[146:149], v[212:215], v[6:9]
	v_mfma_f32_16x16x32_bf16 v[6:9], v[150:153], v[216:219], v[6:9]
	v_mfma_f32_16x16x32_bf16 v[2:5], v[170:173], v[212:215], v[2:5]
	v_mfma_f32_16x16x32_bf16 v[2:5], v[174:177], v[216:219], v[2:5]
	s_setprio 0
	s_barrier
	s_cbranch_scc0 .LBB0_584
	s_and_b64 vcc, exec, s[18:19]
	s_cbranch_vccz .LBB0_587
	s_barrier

.LBB0_675:
	ds_read_b128 v[82:85], v219
	ds_read_b128 v[86:89], v219 offset:1024
	ds_read_b128 v[94:97], v219 offset:2048
	ds_read_b128 v[102:105], v219 offset:3072
	ds_read_b128 v[110:113], v220
	ds_read_b128 v[118:121], v220 offset:1024
	ds_read_b128 v[138:141], v220 offset:2048
	ds_read_b128 v[158:161], v220 offset:3072
	s_add_u32 s0, s8, 0xfffc0080
	s_addc_u32 s1, s9, -1
	s_cmp_eq_u32 s51, 12
	s_cselect_b32 s31, s7, s1
	s_cselect_b32 s30, s23, s0
	s_cselect_b32 s3, s21, s50
	s_cselect_b32 s2, s34, s35
	v_lshl_add_u64 v[224:225], s[8:9], 0, v[190:191]
	s_add_i32 m0, s29, 0xc000
	ds_read_b128 v[162:165], v221
	ds_read_b128 v[166:169], v221 offset:1024
	ds_read_b128 v[170:173], v221 offset:2048
	ds_read_b128 v[174:177], v221 offset:3072
	ds_read_b128 v[198:201], v221 offset:4096
	ds_read_b128 v[202:205], v221 offset:5120
	ds_read_b128 v[206:209], v221 offset:6144
	ds_read_b128 v[210:213], v221 offset:7168
	global_load_lds_dwordx4 v[224:225], off
	v_lshl_add_u64 v[224:225], s[8:9], 0, v[192:193]
	s_add_i32 m0, s29, 0xe000
	s_nop 0
	global_load_lds_dwordx4 v[224:225], off
	s_waitcnt vmcnt(8)
	s_waitcnt lgkmcnt(0)
	s_barrier
	s_setprio 1
	s_waitcnt lgkmcnt(0)
	v_mfma_f32_16x16x32_bf16 v[154:157], v[82:85], v[162:165], v[154:157]
	v_mfma_f32_16x16x32_bf16 v[154:157], v[86:89], v[166:169], v[154:157]
	v_mfma_f32_16x16x32_bf16 v[150:153], v[94:97], v[162:165], v[150:153]
	v_mfma_f32_16x16x32_bf16 v[150:153], v[102:105], v[166:169], v[150:153]
	v_mfma_f32_16x16x32_bf16 v[134:137], v[82:85], v[170:173], v[134:137]
	v_mfma_f32_16x16x32_bf16 v[134:137], v[86:89], v[174:177], v[134:137]
	v_mfma_f32_16x16x32_bf16 v[130:133], v[94:97], v[170:173], v[130:133]
	v_mfma_f32_16x16x32_bf16 v[130:133], v[102:105], v[174:177], v[130:133]
	v_mfma_f32_16x16x32_bf16 v[114:117], v[82:85], v[198:201], v[114:117]
	v_mfma_f32_16x16x32_bf16 v[114:117], v[86:89], v[202:205], v[114:117]
	v_mfma_f32_16x16x32_bf16 v[106:109], v[94:97], v[198:201], v[106:109]
	v_mfma_f32_16x16x32_bf16 v[106:109], v[102:105], v[202:205], v[106:109]
	v_mfma_f32_16x16x32_bf16 v[78:81], v[82:85], v[206:209], v[78:81]
	v_mfma_f32_16x16x32_bf16 v[78:81], v[86:89], v[210:213], v[78:81]
	v_mfma_f32_16x16x32_bf16 v[74:77], v[94:97], v[206:209], v[74:77]
	v_mfma_f32_16x16x32_bf16 v[74:77], v[102:105], v[210:213], v[74:77]
	s_setprio 0
	s_setprio 1
	v_mfma_f32_16x16x32_bf16 v[146:149], v[110:113], v[162:165], v[146:149]
	v_mfma_f32_16x16x32_bf16 v[146:149], v[118:121], v[166:169], v[146:149]
	v_mfma_f32_16x16x32_bf16 v[142:145], v[138:141], v[162:165], v[142:145]
	v_mfma_f32_16x16x32_bf16 v[142:145], v[158:161], v[166:169], v[142:145]
	v_mfma_f32_16x16x32_bf16 v[126:129], v[110:113], v[170:173], v[126:129]
	v_mfma_f32_16x16x32_bf16 v[126:129], v[118:121], v[174:177], v[126:129]
	v_mfma_f32_16x16x32_bf16 v[122:125], v[138:141], v[170:173], v[122:125]
	v_mfma_f32_16x16x32_bf16 v[122:125], v[158:161], v[174:177], v[122:125]
	v_mfma_f32_16x16x32_bf16 v[98:101], v[110:113], v[198:201], v[98:101]
	v_mfma_f32_16x16x32_bf16 v[98:101], v[118:121], v[202:205], v[98:101]
	v_mfma_f32_16x16x32_bf16 v[90:93], v[138:141], v[198:201], v[90:93]
	v_mfma_f32_16x16x32_bf16 v[90:93], v[158:161], v[202:205], v[90:93]
	v_mfma_f32_16x16x32_bf16 v[70:73], v[110:113], v[206:209], v[70:73]
	v_mfma_f32_16x16x32_bf16 v[70:73], v[118:121], v[210:213], v[70:73]
	v_mfma_f32_16x16x32_bf16 v[66:69], v[138:141], v[206:209], v[66:69]
	v_mfma_f32_16x16x32_bf16 v[66:69], v[158:161], v[210:213], v[66:69]
	s_setprio 0
	s_barrier
	s_add_i32 s0, s48, s36
	v_lshl_add_u64 v[224:225], s[2:3], 0, v[182:183]
	s_mov_b32 m0, s0
	ds_read_b128 v[162:165], v221 offset:16384
	ds_read_b128 v[166:169], v221 offset:17408
	ds_read_b128 v[170:173], v221 offset:18432
	ds_read_b128 v[174:177], v221 offset:19456
	ds_read_b128 v[198:201], v221 offset:20480
	ds_read_b128 v[202:205], v221 offset:21504
	ds_read_b128 v[206:209], v221 offset:22528
	ds_read_b128 v[210:213], v221 offset:23552
	global_load_lds_dwordx4 v[224:225], off
	s_add_i32 m0, s0, 0x2000
	s_add_u32 s0, s2, 0x40000
	v_lshl_add_u64 v[226:227], s[2:3], 0, v[186:187]
	s_addc_u32 s1, s3, 0
	s_add_i32 s52, s49, s36
	global_load_lds_dwordx4 v[226:227], off
	v_lshl_add_u64 v[228:229], s[0:1], 0, v[182:183]
	s_mov_b32 m0, s52
	v_lshl_add_u64 v[230:231], s[30:31], 0, v[184:185]
	global_load_lds_dwordx4 v[228:229], off
	v_lshl_add_u64 v[228:229], s[0:1], 0, v[186:187]
	s_add_i32 m0, s52, 0x2000
	s_nop 0
	global_load_lds_dwordx4 v[228:229], off
	v_lshl_add_u64 v[228:229], s[30:31], 0, v[180:181]
	s_mov_b32 m0, s29
	s_nop 0
	global_load_lds_dwordx4 v[228:229], off
	s_mov_b32 m0, s37
	s_nop 0
	global_load_lds_dwordx4 v[230:231], off
	s_waitcnt vmcnt(8)
	s_waitcnt lgkmcnt(0)
	s_barrier
	s_setprio 1
	s_waitcnt lgkmcnt(0)
	v_mfma_f32_16x16x32_bf16 v[62:65], v[82:85], v[162:165], v[62:65]
	v_mfma_f32_16x16x32_bf16 v[62:65], v[86:89], v[166:169], v[62:65]
	v_mfma_f32_16x16x32_bf16 v[58:61], v[94:97], v[162:165], v[58:61]
	v_mfma_f32_16x16x32_bf16 v[58:61], v[102:105], v[166:169], v[58:61]
	v_mfma_f32_16x16x32_bf16 v[46:49], v[82:85], v[170:173], v[46:49]
	v_mfma_f32_16x16x32_bf16 v[46:49], v[86:89], v[174:177], v[46:49]
	v_mfma_f32_16x16x32_bf16 v[42:45], v[94:97], v[170:173], v[42:45]
	v_mfma_f32_16x16x32_bf16 v[42:45], v[102:105], v[174:177], v[42:45]
	v_mfma_f32_16x16x32_bf16 v[30:33], v[82:85], v[198:201], v[30:33]
	v_mfma_f32_16x16x32_bf16 v[30:33], v[86:89], v[202:205], v[30:33]
	v_mfma_f32_16x16x32_bf16 v[26:29], v[94:97], v[198:201], v[26:29]
	v_mfma_f32_16x16x32_bf16 v[26:29], v[102:105], v[202:205], v[26:29]
	v_mfma_f32_16x16x32_bf16 v[14:17], v[82:85], v[206:209], v[14:17]
	v_mfma_f32_16x16x32_bf16 v[14:17], v[86:89], v[210:213], v[14:17]
	v_mfma_f32_16x16x32_bf16 v[10:13], v[94:97], v[206:209], v[10:13]
	v_mfma_f32_16x16x32_bf16 v[10:13], v[102:105], v[210:213], v[10:13]
	s_setprio 0
	s_setprio 1
	v_mfma_f32_16x16x32_bf16 v[54:57], v[110:113], v[162:165], v[54:57]
	v_mfma_f32_16x16x32_bf16 v[54:57], v[118:121], v[166:169], v[54:57]
	v_mfma_f32_16x16x32_bf16 v[50:53], v[138:141], v[162:165], v[50:53]
	v_mfma_f32_16x16x32_bf16 v[50:53], v[158:161], v[166:169], v[50:53]
	v_mfma_f32_16x16x32_bf16 v[38:41], v[110:113], v[170:173], v[38:41]
	v_mfma_f32_16x16x32_bf16 v[38:41], v[118:121], v[174:177], v[38:41]
	v_mfma_f32_16x16x32_bf16 v[34:37], v[138:141], v[170:173], v[34:37]
	v_mfma_f32_16x16x32_bf16 v[34:37], v[158:161], v[174:177], v[34:37]
	v_mfma_f32_16x16x32_bf16 v[22:25], v[110:113], v[198:201], v[22:25]
	v_mfma_f32_16x16x32_bf16 v[22:25], v[118:121], v[202:205], v[22:25]
	v_mfma_f32_16x16x32_bf16 v[18:21], v[138:141], v[198:201], v[18:21]
	v_mfma_f32_16x16x32_bf16 v[18:21], v[158:161], v[202:205], v[18:21]
	v_mfma_f32_16x16x32_bf16 v[6:9], v[110:113], v[206:209], v[6:9]
	v_mfma_f32_16x16x32_bf16 v[6:9], v[118:121], v[210:213], v[6:9]
	v_mfma_f32_16x16x32_bf16 v[2:5], v[138:141], v[206:209], v[2:5]
	v_mfma_f32_16x16x32_bf16 v[2:5], v[158:161], v[210:213], v[2:5]
	s_setprio 0
	s_barrier
	s_add_i32 s52, 0, 0x18000
	s_add_i32 s53, 0, 0x1c000
	v_add_u32_e32 v102, s52, v218
	v_add_u32_e32 v158, s53, v218
	ds_read_b128 v[82:85], v102
	ds_read_b128 v[86:89], v102 offset:1024
	ds_read_b128 v[94:97], v102 offset:2048
	ds_read_b128 v[102:105], v102 offset:3072
	ds_read_b128 v[110:113], v158
	ds_read_b128 v[118:121], v158 offset:1024
	ds_read_b128 v[138:141], v158 offset:2048
	ds_read_b128 v[158:161], v158 offset:3072
	s_add_u32 s0, s30, 0x40000
	s_addc_u32 s1, s31, 0
	s_mov_b32 m0, s38
	v_lshl_add_u64 v[232:233], s[0:1], 0, v[180:181]
	ds_read_b128 v[162:165], v221 offset:32768
	ds_read_b128 v[166:169], v221 offset:33792
	ds_read_b128 v[170:173], v221 offset:34816
	ds_read_b128 v[174:177], v221 offset:35840
	ds_read_b128 v[198:201], v221 offset:36864
	ds_read_b128 v[202:205], v221 offset:37888
	ds_read_b128 v[206:209], v221 offset:38912
	ds_read_b128 v[210:213], v221 offset:39936
	global_load_lds_dwordx4 v[232:233], off
	v_lshl_add_u64 v[232:233], s[0:1], 0, v[184:185]
	s_mov_b32 m0, s39
	s_nop 0
	global_load_lds_dwordx4 v[232:233], off
	s_waitcnt vmcnt(8)
	s_waitcnt lgkmcnt(0)
	s_barrier
	s_setprio 1
	s_waitcnt lgkmcnt(0)
	v_mfma_f32_16x16x32_bf16 v[154:157], v[82:85], v[162:165], v[154:157]
	v_mfma_f32_16x16x32_bf16 v[154:157], v[86:89], v[166:169], v[154:157]
	v_mfma_f32_16x16x32_bf16 v[150:153], v[94:97], v[162:165], v[150:153]
	v_mfma_f32_16x16x32_bf16 v[150:153], v[102:105], v[166:169], v[150:153]
	v_mfma_f32_16x16x32_bf16 v[134:137], v[82:85], v[170:173], v[134:137]
	v_mfma_f32_16x16x32_bf16 v[134:137], v[86:89], v[174:177], v[134:137]
	v_mfma_f32_16x16x32_bf16 v[130:133], v[94:97], v[170:173], v[130:133]
	v_mfma_f32_16x16x32_bf16 v[130:133], v[102:105], v[174:177], v[130:133]
	v_mfma_f32_16x16x32_bf16 v[114:117], v[82:85], v[198:201], v[114:117]
	v_mfma_f32_16x16x32_bf16 v[114:117], v[86:89], v[202:205], v[114:117]
	v_mfma_f32_16x16x32_bf16 v[106:109], v[94:97], v[198:201], v[106:109]
	v_mfma_f32_16x16x32_bf16 v[106:109], v[102:105], v[202:205], v[106:109]
	v_mfma_f32_16x16x32_bf16 v[78:81], v[82:85], v[206:209], v[78:81]
	v_mfma_f32_16x16x32_bf16 v[78:81], v[86:89], v[210:213], v[78:81]
	v_mfma_f32_16x16x32_bf16 v[74:77], v[94:97], v[206:209], v[74:77]
	v_mfma_f32_16x16x32_bf16 v[74:77], v[102:105], v[210:213], v[74:77]
	s_setprio 0
	s_setprio 1
	v_mfma_f32_16x16x32_bf16 v[146:149], v[110:113], v[162:165], v[146:149]
	v_mfma_f32_16x16x32_bf16 v[146:149], v[118:121], v[166:169], v[146:149]
	v_mfma_f32_16x16x32_bf16 v[142:145], v[138:141], v[162:165], v[142:145]
	v_mfma_f32_16x16x32_bf16 v[142:145], v[158:161], v[166:169], v[142:145]
	v_mfma_f32_16x16x32_bf16 v[126:129], v[110:113], v[170:173], v[126:129]
	v_mfma_f32_16x16x32_bf16 v[126:129], v[118:121], v[174:177], v[126:129]
	v_mfma_f32_16x16x32_bf16 v[122:125], v[138:141], v[170:173], v[122:125]
	v_mfma_f32_16x16x32_bf16 v[122:125], v[158:161], v[174:177], v[122:125]
	v_mfma_f32_16x16x32_bf16 v[98:101], v[110:113], v[198:201], v[98:101]
	v_mfma_f32_16x16x32_bf16 v[98:101], v[118:121], v[202:205], v[98:101]
	v_mfma_f32_16x16x32_bf16 v[90:93], v[138:141], v[198:201], v[90:93]
	v_mfma_f32_16x16x32_bf16 v[90:93], v[158:161], v[202:205], v[90:93]
	v_mfma_f32_16x16x32_bf16 v[70:73], v[110:113], v[206:209], v[70:73]
	v_mfma_f32_16x16x32_bf16 v[70:73], v[118:121], v[210:213], v[70:73]
	v_mfma_f32_16x16x32_bf16 v[66:69], v[138:141], v[206:209], v[66:69]
	v_mfma_f32_16x16x32_bf16 v[66:69], v[158:161], v[210:213], v[66:69]
	s_setprio 0
	s_barrier
	s_add_i32 s0, s52, s36
	v_lshl_add_u64 v[224:225], v[224:225], 0, s[12:13]
	s_mov_b32 m0, s0
	ds_read_b128 v[162:165], v221 offset:49152
	ds_read_b128 v[166:169], v221 offset:50176
	ds_read_b128 v[170:173], v221 offset:51200
	ds_read_b128 v[174:177], v221 offset:52224
	ds_read_b128 v[198:201], v221 offset:53248
	ds_read_b128 v[202:205], v221 offset:54272
	ds_read_b128 v[206:209], v221 offset:55296
	ds_read_b128 v[210:213], v221 offset:56320
	global_load_lds_dwordx4 v[224:225], off
	s_add_i32 m0, s0, 0x2000
	s_add_u32 s0, s2, 0x40080
	v_lshl_add_u64 v[224:225], v[226:227], 0, s[12:13]
	s_addc_u32 s1, s3, 0
	s_add_i32 s2, s53, s36
	global_load_lds_dwordx4 v[224:225], off
	v_lshl_add_u64 v[224:225], s[0:1], 0, v[182:183]
	s_mov_b32 m0, s2
	s_nop 0
	global_load_lds_dwordx4 v[224:225], off
	v_lshl_add_u64 v[224:225], s[0:1], 0, v[186:187]
	s_add_i32 m0, s2, 0x2000
	s_nop 0
	global_load_lds_dwordx4 v[224:225], off
	v_lshl_add_u64 v[224:225], v[228:229], 0, s[12:13]
	s_mov_b32 m0, s44
	s_nop 0
	global_load_lds_dwordx4 v[224:225], off
	v_lshl_add_u64 v[224:225], v[230:231], 0, s[12:13]
	s_mov_b32 m0, s45
	s_nop 0
	global_load_lds_dwordx4 v[224:225], off
	s_waitcnt vmcnt(8)
	s_waitcnt lgkmcnt(0)
	s_barrier
	s_setprio 1
	s_waitcnt lgkmcnt(0)
	v_mfma_f32_16x16x32_bf16 v[62:65], v[82:85], v[162:165], v[62:65]
	v_mfma_f32_16x16x32_bf16 v[62:65], v[86:89], v[166:169], v[62:65]
	v_mfma_f32_16x16x32_bf16 v[58:61], v[94:97], v[162:165], v[58:61]
	v_mfma_f32_16x16x32_bf16 v[58:61], v[102:105], v[166:169], v[58:61]
	v_mfma_f32_16x16x32_bf16 v[46:49], v[82:85], v[170:173], v[46:49]
	v_mfma_f32_16x16x32_bf16 v[46:49], v[86:89], v[174:177], v[46:49]
	v_mfma_f32_16x16x32_bf16 v[42:45], v[94:97], v[170:173], v[42:45]
	v_mfma_f32_16x16x32_bf16 v[42:45], v[102:105], v[174:177], v[42:45]
	v_mfma_f32_16x16x32_bf16 v[30:33], v[82:85], v[198:201], v[30:33]
	v_mfma_f32_16x16x32_bf16 v[30:33], v[86:89], v[202:205], v[30:33]
	v_mfma_f32_16x16x32_bf16 v[26:29], v[94:97], v[198:201], v[26:29]
	v_mfma_f32_16x16x32_bf16 v[26:29], v[102:105], v[202:205], v[26:29]
	v_mfma_f32_16x16x32_bf16 v[14:17], v[82:85], v[206:209], v[14:17]
	v_mfma_f32_16x16x32_bf16 v[14:17], v[86:89], v[210:213], v[14:17]
	v_mfma_f32_16x16x32_bf16 v[10:13], v[94:97], v[206:209], v[10:13]
	v_mfma_f32_16x16x32_bf16 v[10:13], v[102:105], v[210:213], v[10:13]
	s_setprio 0
	s_setprio 1
	v_mfma_f32_16x16x32_bf16 v[54:57], v[110:113], v[162:165], v[54:57]
	s_add_i32 s51, s51, 2
	s_add_u32 s8, s8, 0x100
	s_addc_u32 s9, s9, 0
	s_add_u32 s35, s35, 0x100
	s_addc_u32 s50, s50, 0
	s_cmp_gt_u32 s51, 13
	v_mfma_f32_16x16x32_bf16 v[54:57], v[118:121], v[166:169], v[54:57]
	v_mfma_f32_16x16x32_bf16 v[50:53], v[138:141], v[162:165], v[50:53]
	v_mfma_f32_16x16x32_bf16 v[50:53], v[158:161], v[166:169], v[50:53]
	v_mfma_f32_16x16x32_bf16 v[38:41], v[110:113], v[170:173], v[38:41]
	v_mfma_f32_16x16x32_bf16 v[38:41], v[118:121], v[174:177], v[38:41]
	v_mfma_f32_16x16x32_bf16 v[34:37], v[138:141], v[170:173], v[34:37]
	v_mfma_f32_16x16x32_bf16 v[34:37], v[158:161], v[174:177], v[34:37]
	v_mfma_f32_16x16x32_bf16 v[22:25], v[110:113], v[198:201], v[22:25]
	v_mfma_f32_16x16x32_bf16 v[22:25], v[118:121], v[202:205], v[22:25]
	v_mfma_f32_16x16x32_bf16 v[18:21], v[138:141], v[198:201], v[18:21]
	v_mfma_f32_16x16x32_bf16 v[18:21], v[158:161], v[202:205], v[18:21]
	v_mfma_f32_16x16x32_bf16 v[6:9], v[110:113], v[206:209], v[6:9]
	v_mfma_f32_16x16x32_bf16 v[6:9], v[118:121], v[210:213], v[6:9]
	v_mfma_f32_16x16x32_bf16 v[2:5], v[138:141], v[206:209], v[2:5]
	v_mfma_f32_16x16x32_bf16 v[2:5], v[158:161], v[210:213], v[2:5]
	s_setprio 0
	s_barrier
	s_cbranch_scc0 .LBB0_675
	s_and_b64 vcc, exec, s[14:15]
	s_cbranch_vccz .LBB0_678
	s_barrier

.LBB0_920:
	ds_read_b128 v[130:133], v187
	ds_read_b128 v[134:137], v187 offset:1024
	ds_read_b128 v[138:141], v187 offset:2048
	ds_read_b128 v[142:145], v187 offset:3072
	ds_read_b128 v[146:149], v188
	ds_read_b128 v[150:153], v188 offset:1024
	ds_read_b128 v[170:173], v188 offset:2048
	ds_read_b128 v[174:177], v188 offset:3072
	s_add_u32 s0, s28, 0xfffc0080
	s_addc_u32 s1, s29, -1
	s_cmp_eq_u32 s51, 12
	s_cselect_b32 s31, s11, s1
	s_cselect_b32 s30, s21, s0
	s_cselect_b32 s3, s19, s50
	s_cselect_b32 s2, s48, s49
	v_lshl_add_u64 v[220:221], s[28:29], 0, v[162:163]
	s_add_i32 m0, s27, 0xc000
	ds_read_b128 v[178:181], v189
	ds_read_b128 v[192:195], v189 offset:1024
	ds_read_b128 v[196:199], v189 offset:2048
	ds_read_b128 v[200:203], v189 offset:3072
	ds_read_b128 v[204:207], v189 offset:4096
	ds_read_b128 v[208:211], v189 offset:5120
	ds_read_b128 v[212:215], v189 offset:6144
	ds_read_b128 v[216:219], v189 offset:7168
	global_load_lds_dwordx4 v[220:221], off
	v_lshl_add_u64 v[220:221], s[28:29], 0, v[164:165]
	s_add_i32 m0, s27, 0xe000
	s_nop 0
	global_load_lds_dwordx4 v[220:221], off
	s_waitcnt vmcnt(8)
	s_waitcnt lgkmcnt(0)
	s_barrier
	s_setprio 1
	s_waitcnt lgkmcnt(0)
	v_mfma_f32_16x16x32_bf16 v[126:129], v[130:133], v[178:181], v[126:129]
	v_mfma_f32_16x16x32_bf16 v[126:129], v[134:137], v[192:195], v[126:129]
	v_mfma_f32_16x16x32_bf16 v[122:125], v[138:141], v[178:181], v[122:125]
	v_mfma_f32_16x16x32_bf16 v[122:125], v[142:145], v[192:195], v[122:125]
	v_mfma_f32_16x16x32_bf16 v[110:113], v[130:133], v[196:199], v[110:113]
	v_mfma_f32_16x16x32_bf16 v[110:113], v[134:137], v[200:203], v[110:113]
	v_mfma_f32_16x16x32_bf16 v[106:109], v[138:141], v[196:199], v[106:109]
	v_mfma_f32_16x16x32_bf16 v[106:109], v[142:145], v[200:203], v[106:109]
	v_mfma_f32_16x16x32_bf16 v[94:97], v[130:133], v[204:207], v[94:97]
	v_mfma_f32_16x16x32_bf16 v[94:97], v[134:137], v[208:211], v[94:97]
	v_mfma_f32_16x16x32_bf16 v[90:93], v[138:141], v[204:207], v[90:93]
	v_mfma_f32_16x16x32_bf16 v[90:93], v[142:145], v[208:211], v[90:93]
	v_mfma_f32_16x16x32_bf16 v[78:81], v[130:133], v[212:215], v[78:81]
	v_mfma_f32_16x16x32_bf16 v[78:81], v[134:137], v[216:219], v[78:81]
	v_mfma_f32_16x16x32_bf16 v[74:77], v[138:141], v[212:215], v[74:77]
	v_mfma_f32_16x16x32_bf16 v[74:77], v[142:145], v[216:219], v[74:77]
	s_setprio 0
	s_setprio 1
	v_mfma_f32_16x16x32_bf16 v[118:121], v[146:149], v[178:181], v[118:121]
	v_mfma_f32_16x16x32_bf16 v[118:121], v[150:153], v[192:195], v[118:121]
	v_mfma_f32_16x16x32_bf16 v[114:117], v[170:173], v[178:181], v[114:117]
	v_mfma_f32_16x16x32_bf16 v[114:117], v[174:177], v[192:195], v[114:117]
	v_mfma_f32_16x16x32_bf16 v[102:105], v[146:149], v[196:199], v[102:105]
	v_mfma_f32_16x16x32_bf16 v[102:105], v[150:153], v[200:203], v[102:105]
	v_mfma_f32_16x16x32_bf16 v[98:101], v[170:173], v[196:199], v[98:101]
	v_mfma_f32_16x16x32_bf16 v[98:101], v[174:177], v[200:203], v[98:101]
	v_mfma_f32_16x16x32_bf16 v[86:89], v[146:149], v[204:207], v[86:89]
	v_mfma_f32_16x16x32_bf16 v[86:89], v[150:153], v[208:211], v[86:89]
	v_mfma_f32_16x16x32_bf16 v[82:85], v[170:173], v[204:207], v[82:85]
	v_mfma_f32_16x16x32_bf16 v[82:85], v[174:177], v[208:211], v[82:85]
	v_mfma_f32_16x16x32_bf16 v[70:73], v[146:149], v[212:215], v[70:73]
	v_mfma_f32_16x16x32_bf16 v[70:73], v[150:153], v[216:219], v[70:73]
	v_mfma_f32_16x16x32_bf16 v[66:69], v[170:173], v[212:215], v[66:69]
	v_mfma_f32_16x16x32_bf16 v[66:69], v[174:177], v[216:219], v[66:69]
	s_setprio 0
	s_barrier
	s_add_i32 s0, s46, s37
	v_lshl_add_u64 v[220:221], s[2:3], 0, v[156:157]
	s_mov_b32 m0, s0
	ds_read_b128 v[178:181], v189 offset:16384
	ds_read_b128 v[192:195], v189 offset:17408
	ds_read_b128 v[196:199], v189 offset:18432
	ds_read_b128 v[200:203], v189 offset:19456
	ds_read_b128 v[204:207], v189 offset:20480
	ds_read_b128 v[208:211], v189 offset:21504
	ds_read_b128 v[212:215], v189 offset:22528
	ds_read_b128 v[216:219], v189 offset:23552
	global_load_lds_dwordx4 v[220:221], off
	s_add_i32 m0, s0, 0x2000
	s_add_u32 s0, s2, 0x40000
	v_lshl_add_u64 v[222:223], s[2:3], 0, v[160:161]
	s_addc_u32 s1, s3, 0
	s_add_i32 s52, s47, s37
	global_load_lds_dwordx4 v[222:223], off
	v_lshl_add_u64 v[224:225], s[0:1], 0, v[156:157]
	s_mov_b32 m0, s52
	v_lshl_add_u64 v[226:227], s[30:31], 0, v[158:159]
	global_load_lds_dwordx4 v[224:225], off
	v_lshl_add_u64 v[224:225], s[0:1], 0, v[160:161]
	s_add_i32 m0, s52, 0x2000
	s_nop 0
	global_load_lds_dwordx4 v[224:225], off
	v_lshl_add_u64 v[224:225], s[30:31], 0, v[154:155]
	s_mov_b32 m0, s27
	s_nop 0
	global_load_lds_dwordx4 v[224:225], off
	s_mov_b32 m0, s38
	s_nop 0
	global_load_lds_dwordx4 v[226:227], off
	s_waitcnt vmcnt(8)
	s_waitcnt lgkmcnt(0)
	s_barrier
	s_setprio 1
	s_waitcnt lgkmcnt(0)
	v_mfma_f32_16x16x32_bf16 v[62:65], v[130:133], v[178:181], v[62:65]
	v_mfma_f32_16x16x32_bf16 v[62:65], v[134:137], v[192:195], v[62:65]
	v_mfma_f32_16x16x32_bf16 v[58:61], v[138:141], v[178:181], v[58:61]
	v_mfma_f32_16x16x32_bf16 v[58:61], v[142:145], v[192:195], v[58:61]
	v_mfma_f32_16x16x32_bf16 v[46:49], v[130:133], v[196:199], v[46:49]
	v_mfma_f32_16x16x32_bf16 v[46:49], v[134:137], v[200:203], v[46:49]
	v_mfma_f32_16x16x32_bf16 v[42:45], v[138:141], v[196:199], v[42:45]
	v_mfma_f32_16x16x32_bf16 v[42:45], v[142:145], v[200:203], v[42:45]
	v_mfma_f32_16x16x32_bf16 v[30:33], v[130:133], v[204:207], v[30:33]
	v_mfma_f32_16x16x32_bf16 v[30:33], v[134:137], v[208:211], v[30:33]
	v_mfma_f32_16x16x32_bf16 v[26:29], v[138:141], v[204:207], v[26:29]
	v_mfma_f32_16x16x32_bf16 v[26:29], v[142:145], v[208:211], v[26:29]
	v_mfma_f32_16x16x32_bf16 v[14:17], v[130:133], v[212:215], v[14:17]
	v_mfma_f32_16x16x32_bf16 v[14:17], v[134:137], v[216:219], v[14:17]
	v_mfma_f32_16x16x32_bf16 v[10:13], v[138:141], v[212:215], v[10:13]
	v_mfma_f32_16x16x32_bf16 v[10:13], v[142:145], v[216:219], v[10:13]
	s_setprio 0
	s_setprio 1
	v_mfma_f32_16x16x32_bf16 v[54:57], v[146:149], v[178:181], v[54:57]
	v_mfma_f32_16x16x32_bf16 v[54:57], v[150:153], v[192:195], v[54:57]
	v_mfma_f32_16x16x32_bf16 v[50:53], v[170:173], v[178:181], v[50:53]
	v_mfma_f32_16x16x32_bf16 v[50:53], v[174:177], v[192:195], v[50:53]
	v_mfma_f32_16x16x32_bf16 v[38:41], v[146:149], v[196:199], v[38:41]
	v_mfma_f32_16x16x32_bf16 v[38:41], v[150:153], v[200:203], v[38:41]
	v_mfma_f32_16x16x32_bf16 v[34:37], v[170:173], v[196:199], v[34:37]
	v_mfma_f32_16x16x32_bf16 v[34:37], v[174:177], v[200:203], v[34:37]
	v_mfma_f32_16x16x32_bf16 v[22:25], v[146:149], v[204:207], v[22:25]
	v_mfma_f32_16x16x32_bf16 v[22:25], v[150:153], v[208:211], v[22:25]
	v_mfma_f32_16x16x32_bf16 v[18:21], v[170:173], v[204:207], v[18:21]
	v_mfma_f32_16x16x32_bf16 v[18:21], v[174:177], v[208:211], v[18:21]
	v_mfma_f32_16x16x32_bf16 v[6:9], v[146:149], v[212:215], v[6:9]
	v_mfma_f32_16x16x32_bf16 v[6:9], v[150:153], v[216:219], v[6:9]
	v_mfma_f32_16x16x32_bf16 v[2:5], v[170:173], v[212:215], v[2:5]
	v_mfma_f32_16x16x32_bf16 v[2:5], v[174:177], v[216:219], v[2:5]
	s_setprio 0
	s_barrier
	s_add_i32 s52, 0, 0x18000
	s_add_i32 s53, 0, 0x1c000
	v_add_u32_e32 v142, s52, v183
	v_add_u32_e32 v174, s53, v183
	ds_read_b128 v[130:133], v142
	ds_read_b128 v[134:137], v142 offset:1024
	ds_read_b128 v[138:141], v142 offset:2048
	ds_read_b128 v[142:145], v142 offset:3072
	ds_read_b128 v[146:149], v174
	ds_read_b128 v[150:153], v174 offset:1024
	ds_read_b128 v[170:173], v174 offset:2048
	ds_read_b128 v[174:177], v174 offset:3072
	s_add_u32 s0, s30, 0x40000
	s_addc_u32 s1, s31, 0
	s_mov_b32 m0, s39
	v_lshl_add_u64 v[228:229], s[0:1], 0, v[154:155]
	ds_read_b128 v[178:181], v189 offset:32768
	ds_read_b128 v[192:195], v189 offset:33792
	ds_read_b128 v[196:199], v189 offset:34816
	ds_read_b128 v[200:203], v189 offset:35840
	ds_read_b128 v[204:207], v189 offset:36864
	ds_read_b128 v[208:211], v189 offset:37888
	ds_read_b128 v[212:215], v189 offset:38912
	ds_read_b128 v[216:219], v189 offset:39936
	global_load_lds_dwordx4 v[228:229], off
	v_lshl_add_u64 v[228:229], s[0:1], 0, v[158:159]
	s_mov_b32 m0, s40
	s_nop 0
	global_load_lds_dwordx4 v[228:229], off
	s_waitcnt vmcnt(8)
	s_waitcnt lgkmcnt(0)
	s_barrier
	s_setprio 1
	s_waitcnt lgkmcnt(0)
	v_mfma_f32_16x16x32_bf16 v[126:129], v[130:133], v[178:181], v[126:129]
	v_mfma_f32_16x16x32_bf16 v[126:129], v[134:137], v[192:195], v[126:129]
	v_mfma_f32_16x16x32_bf16 v[122:125], v[138:141], v[178:181], v[122:125]
	v_mfma_f32_16x16x32_bf16 v[122:125], v[142:145], v[192:195], v[122:125]
	v_mfma_f32_16x16x32_bf16 v[110:113], v[130:133], v[196:199], v[110:113]
	v_mfma_f32_16x16x32_bf16 v[110:113], v[134:137], v[200:203], v[110:113]
	v_mfma_f32_16x16x32_bf16 v[106:109], v[138:141], v[196:199], v[106:109]
	v_mfma_f32_16x16x32_bf16 v[106:109], v[142:145], v[200:203], v[106:109]
	v_mfma_f32_16x16x32_bf16 v[94:97], v[130:133], v[204:207], v[94:97]
	v_mfma_f32_16x16x32_bf16 v[94:97], v[134:137], v[208:211], v[94:97]
	v_mfma_f32_16x16x32_bf16 v[90:93], v[138:141], v[204:207], v[90:93]
	v_mfma_f32_16x16x32_bf16 v[90:93], v[142:145], v[208:211], v[90:93]
	v_mfma_f32_16x16x32_bf16 v[78:81], v[130:133], v[212:215], v[78:81]
	v_mfma_f32_16x16x32_bf16 v[78:81], v[134:137], v[216:219], v[78:81]
	v_mfma_f32_16x16x32_bf16 v[74:77], v[138:141], v[212:215], v[74:77]
	v_mfma_f32_16x16x32_bf16 v[74:77], v[142:145], v[216:219], v[74:77]
	s_setprio 0
	s_setprio 1
	v_mfma_f32_16x16x32_bf16 v[118:121], v[146:149], v[178:181], v[118:121]
	v_mfma_f32_16x16x32_bf16 v[118:121], v[150:153], v[192:195], v[118:121]
	v_mfma_f32_16x16x32_bf16 v[114:117], v[170:173], v[178:181], v[114:117]
	v_mfma_f32_16x16x32_bf16 v[114:117], v[174:177], v[192:195], v[114:117]
	v_mfma_f32_16x16x32_bf16 v[102:105], v[146:149], v[196:199], v[102:105]
	v_mfma_f32_16x16x32_bf16 v[102:105], v[150:153], v[200:203], v[102:105]
	v_mfma_f32_16x16x32_bf16 v[98:101], v[170:173], v[196:199], v[98:101]
	v_mfma_f32_16x16x32_bf16 v[98:101], v[174:177], v[200:203], v[98:101]
	v_mfma_f32_16x16x32_bf16 v[86:89], v[146:149], v[204:207], v[86:89]
	v_mfma_f32_16x16x32_bf16 v[86:89], v[150:153], v[208:211], v[86:89]
	v_mfma_f32_16x16x32_bf16 v[82:85], v[170:173], v[204:207], v[82:85]
	v_mfma_f32_16x16x32_bf16 v[82:85], v[174:177], v[208:211], v[82:85]
	v_mfma_f32_16x16x32_bf16 v[70:73], v[146:149], v[212:215], v[70:73]
	v_mfma_f32_16x16x32_bf16 v[70:73], v[150:153], v[216:219], v[70:73]
	v_mfma_f32_16x16x32_bf16 v[66:69], v[170:173], v[212:215], v[66:69]
	v_mfma_f32_16x16x32_bf16 v[66:69], v[174:177], v[216:219], v[66:69]
	s_setprio 0
	s_barrier
	s_add_i32 s0, s52, s37
	v_lshl_add_u64 v[220:221], v[220:221], 0, s[14:15]
	s_mov_b32 m0, s0
	ds_read_b128 v[178:181], v189 offset:49152
	ds_read_b128 v[192:195], v189 offset:50176
	ds_read_b128 v[196:199], v189 offset:51200
	ds_read_b128 v[200:203], v189 offset:52224
	ds_read_b128 v[204:207], v189 offset:53248
	ds_read_b128 v[208:211], v189 offset:54272
	ds_read_b128 v[212:215], v189 offset:55296
	ds_read_b128 v[216:219], v189 offset:56320
	global_load_lds_dwordx4 v[220:221], off
	s_add_i32 m0, s0, 0x2000
	s_add_u32 s0, s2, 0x40080
	v_lshl_add_u64 v[220:221], v[222:223], 0, s[14:15]
	s_addc_u32 s1, s3, 0
	s_add_i32 s2, s53, s37
	global_load_lds_dwordx4 v[220:221], off
	v_lshl_add_u64 v[220:221], s[0:1], 0, v[156:157]
	s_mov_b32 m0, s2
	s_nop 0
	global_load_lds_dwordx4 v[220:221], off
	v_lshl_add_u64 v[220:221], s[0:1], 0, v[160:161]
	s_add_i32 m0, s2, 0x2000
	s_nop 0
	global_load_lds_dwordx4 v[220:221], off
	v_lshl_add_u64 v[220:221], v[224:225], 0, s[14:15]
	s_mov_b32 m0, s42
	s_nop 0
	global_load_lds_dwordx4 v[220:221], off
	v_lshl_add_u64 v[220:221], v[226:227], 0, s[14:15]
	s_mov_b32 m0, s43
	s_nop 0
	global_load_lds_dwordx4 v[220:221], off
	s_waitcnt vmcnt(8)
	s_waitcnt lgkmcnt(0)
	s_barrier
	s_setprio 1
	s_waitcnt lgkmcnt(0)
	v_mfma_f32_16x16x32_bf16 v[62:65], v[130:133], v[178:181], v[62:65]
	v_mfma_f32_16x16x32_bf16 v[62:65], v[134:137], v[192:195], v[62:65]
	v_mfma_f32_16x16x32_bf16 v[58:61], v[138:141], v[178:181], v[58:61]
	v_mfma_f32_16x16x32_bf16 v[58:61], v[142:145], v[192:195], v[58:61]
	v_mfma_f32_16x16x32_bf16 v[46:49], v[130:133], v[196:199], v[46:49]
	v_mfma_f32_16x16x32_bf16 v[46:49], v[134:137], v[200:203], v[46:49]
	v_mfma_f32_16x16x32_bf16 v[42:45], v[138:141], v[196:199], v[42:45]
	v_mfma_f32_16x16x32_bf16 v[42:45], v[142:145], v[200:203], v[42:45]
	v_mfma_f32_16x16x32_bf16 v[30:33], v[130:133], v[204:207], v[30:33]
	v_mfma_f32_16x16x32_bf16 v[30:33], v[134:137], v[208:211], v[30:33]
	v_mfma_f32_16x16x32_bf16 v[26:29], v[138:141], v[204:207], v[26:29]
	v_mfma_f32_16x16x32_bf16 v[26:29], v[142:145], v[208:211], v[26:29]
	v_mfma_f32_16x16x32_bf16 v[14:17], v[130:133], v[212:215], v[14:17]
	v_mfma_f32_16x16x32_bf16 v[14:17], v[134:137], v[216:219], v[14:17]
	v_mfma_f32_16x16x32_bf16 v[10:13], v[138:141], v[212:215], v[10:13]
	v_mfma_f32_16x16x32_bf16 v[10:13], v[142:145], v[216:219], v[10:13]
	s_setprio 0
	s_setprio 1
	v_mfma_f32_16x16x32_bf16 v[54:57], v[146:149], v[178:181], v[54:57]
	s_add_i32 s51, s51, 2
	s_add_u32 s28, s28, 0x100
	s_addc_u32 s29, s29, 0
	s_add_u32 s49, s49, 0x100
	s_addc_u32 s50, s50, 0
	s_cmp_gt_u32 s51, 13
	v_mfma_f32_16x16x32_bf16 v[54:57], v[150:153], v[192:195], v[54:57]
	v_mfma_f32_16x16x32_bf16 v[50:53], v[170:173], v[178:181], v[50:53]
	v_mfma_f32_16x16x32_bf16 v[50:53], v[174:177], v[192:195], v[50:53]
	v_mfma_f32_16x16x32_bf16 v[38:41], v[146:149], v[196:199], v[38:41]
	v_mfma_f32_16x16x32_bf16 v[38:41], v[150:153], v[200:203], v[38:41]
	v_mfma_f32_16x16x32_bf16 v[34:37], v[170:173], v[196:199], v[34:37]
	v_mfma_f32_16x16x32_bf16 v[34:37], v[174:177], v[200:203], v[34:37]
	v_mfma_f32_16x16x32_bf16 v[22:25], v[146:149], v[204:207], v[22:25]
	v_mfma_f32_16x16x32_bf16 v[22:25], v[150:153], v[208:211], v[22:25]
	v_mfma_f32_16x16x32_bf16 v[18:21], v[170:173], v[204:207], v[18:21]
	v_mfma_f32_16x16x32_bf16 v[18:21], v[174:177], v[208:211], v[18:21]
	v_mfma_f32_16x16x32_bf16 v[6:9], v[146:149], v[212:215], v[6:9]
	v_mfma_f32_16x16x32_bf16 v[6:9], v[150:153], v[216:219], v[6:9]
	v_mfma_f32_16x16x32_bf16 v[2:5], v[170:173], v[212:215], v[2:5]
	v_mfma_f32_16x16x32_bf16 v[2:5], v[174:177], v[216:219], v[2:5]
	s_setprio 0
	s_barrier
	s_cbranch_scc0 .LBB0_920
	s_and_b64 vcc, exec, s[16:17]
	s_cbranch_vccz .LBB0_923
	s_barrier

.LBB0_1009:
	ds_read_b128 v[148:151], v167
	ds_read_b128 v[152:155], v167 offset:1024
	ds_read_b128 v[156:159], v167 offset:2048
	ds_read_b128 v[160:163], v167 offset:3072
	ds_read_b128 v[172:175], v168
	ds_read_b128 v[176:179], v168 offset:1024
	ds_read_b128 v[180:183], v168 offset:2048
	ds_read_b128 v[184:187], v168 offset:3072
	s_add_u32 s0, s28, 0xfffc0080
	s_addc_u32 s1, s29, -1
	s_cmp_eq_u32 s53, 12
	s_cselect_b32 s31, s21, s1
	s_cselect_b32 s30, s49, s0
	s_cselect_b32 s3, s19, s52
	s_cselect_b32 s2, s50, s51
	v_lshl_add_u64 v[220:221], s[28:29], 0, v[140:141]
	s_add_i32 m0, s27, 0xc000
	ds_read_b128 v[188:191], v169
	ds_read_b128 v[192:195], v169 offset:1024
	ds_read_b128 v[196:199], v169 offset:2048
	ds_read_b128 v[200:203], v169 offset:3072
	ds_read_b128 v[204:207], v169 offset:4096
	ds_read_b128 v[208:211], v169 offset:5120
	ds_read_b128 v[212:215], v169 offset:6144
	ds_read_b128 v[216:219], v169 offset:7168
	global_load_lds_dwordx4 v[220:221], off
	v_lshl_add_u64 v[220:221], s[28:29], 0, v[142:143]
	s_add_i32 m0, s27, 0xe000
	s_nop 0
	global_load_lds_dwordx4 v[220:221], off
	s_waitcnt vmcnt(8)
	s_waitcnt lgkmcnt(0)
	s_barrier
	s_setprio 1
	s_waitcnt lgkmcnt(0)
	v_mfma_f32_16x16x32_bf16 v[126:129], v[148:151], v[188:191], v[126:129]
	v_mfma_f32_16x16x32_bf16 v[126:129], v[152:155], v[192:195], v[126:129]
	v_mfma_f32_16x16x32_bf16 v[118:121], v[156:159], v[188:191], v[118:121]
	v_mfma_f32_16x16x32_bf16 v[118:121], v[160:163], v[192:195], v[118:121]
	v_mfma_f32_16x16x32_bf16 v[110:113], v[148:151], v[196:199], v[110:113]
	v_mfma_f32_16x16x32_bf16 v[110:113], v[152:155], v[200:203], v[110:113]
	v_mfma_f32_16x16x32_bf16 v[102:105], v[156:159], v[196:199], v[102:105]
	v_mfma_f32_16x16x32_bf16 v[102:105], v[160:163], v[200:203], v[102:105]
	v_mfma_f32_16x16x32_bf16 v[94:97], v[148:151], v[204:207], v[94:97]
	v_mfma_f32_16x16x32_bf16 v[94:97], v[152:155], v[208:211], v[94:97]
	v_mfma_f32_16x16x32_bf16 v[86:89], v[156:159], v[204:207], v[86:89]
	v_mfma_f32_16x16x32_bf16 v[86:89], v[160:163], v[208:211], v[86:89]
	v_mfma_f32_16x16x32_bf16 v[78:81], v[148:151], v[212:215], v[78:81]
	v_mfma_f32_16x16x32_bf16 v[78:81], v[152:155], v[216:219], v[78:81]
	v_mfma_f32_16x16x32_bf16 v[70:73], v[156:159], v[212:215], v[70:73]
	v_mfma_f32_16x16x32_bf16 v[70:73], v[160:163], v[216:219], v[70:73]
	s_setprio 0
	s_setprio 1
	v_mfma_f32_16x16x32_bf16 v[122:125], v[172:175], v[188:191], v[122:125]
	v_mfma_f32_16x16x32_bf16 v[122:125], v[176:179], v[192:195], v[122:125]
	v_mfma_f32_16x16x32_bf16 v[114:117], v[180:183], v[188:191], v[114:117]
	v_mfma_f32_16x16x32_bf16 v[114:117], v[184:187], v[192:195], v[114:117]
	v_mfma_f32_16x16x32_bf16 v[106:109], v[172:175], v[196:199], v[106:109]
	v_mfma_f32_16x16x32_bf16 v[106:109], v[176:179], v[200:203], v[106:109]
	v_mfma_f32_16x16x32_bf16 v[98:101], v[180:183], v[196:199], v[98:101]
	v_mfma_f32_16x16x32_bf16 v[98:101], v[184:187], v[200:203], v[98:101]
	v_mfma_f32_16x16x32_bf16 v[90:93], v[172:175], v[204:207], v[90:93]
	v_mfma_f32_16x16x32_bf16 v[90:93], v[176:179], v[208:211], v[90:93]
	v_mfma_f32_16x16x32_bf16 v[82:85], v[180:183], v[204:207], v[82:85]
	v_mfma_f32_16x16x32_bf16 v[82:85], v[184:187], v[208:211], v[82:85]
	v_mfma_f32_16x16x32_bf16 v[74:77], v[172:175], v[212:215], v[74:77]
	v_mfma_f32_16x16x32_bf16 v[74:77], v[176:179], v[216:219], v[74:77]
	v_mfma_f32_16x16x32_bf16 v[66:69], v[180:183], v[212:215], v[66:69]
	v_mfma_f32_16x16x32_bf16 v[66:69], v[184:187], v[216:219], v[66:69]
	s_setprio 0
	s_barrier
	s_add_i32 s0, s44, s35
	v_lshl_add_u64 v[220:221], s[2:3], 0, v[134:135]
	s_mov_b32 m0, s0
	ds_read_b128 v[188:191], v169 offset:16384
	ds_read_b128 v[192:195], v169 offset:17408
	ds_read_b128 v[196:199], v169 offset:18432
	ds_read_b128 v[200:203], v169 offset:19456
	ds_read_b128 v[204:207], v169 offset:20480
	ds_read_b128 v[208:211], v169 offset:21504
	ds_read_b128 v[212:215], v169 offset:22528
	ds_read_b128 v[216:219], v169 offset:23552
	global_load_lds_dwordx4 v[220:221], off
	s_add_i32 m0, s0, 0x2000
	s_add_u32 s0, s2, 0x40000
	v_lshl_add_u64 v[222:223], s[2:3], 0, v[130:131]
	s_addc_u32 s1, s3, 0
	s_add_i32 s54, s45, s35
	global_load_lds_dwordx4 v[222:223], off
	v_lshl_add_u64 v[224:225], s[0:1], 0, v[134:135]
	s_mov_b32 m0, s54
	v_lshl_add_u64 v[226:227], s[30:31], 0, v[132:133]
	global_load_lds_dwordx4 v[224:225], off
	v_lshl_add_u64 v[224:225], s[0:1], 0, v[130:131]
	s_add_i32 m0, s54, 0x2000
	s_nop 0
	global_load_lds_dwordx4 v[224:225], off
	v_lshl_add_u64 v[224:225], s[30:31], 0, v[136:137]
	s_mov_b32 m0, s27
	s_nop 0
	global_load_lds_dwordx4 v[224:225], off
	s_mov_b32 m0, s38
	s_nop 0
	global_load_lds_dwordx4 v[226:227], off
	s_waitcnt vmcnt(8)
	s_waitcnt lgkmcnt(0)
	s_barrier
	s_setprio 1
	s_waitcnt lgkmcnt(0)
	v_mfma_f32_16x16x32_bf16 v[62:65], v[148:151], v[188:191], v[62:65]
	v_mfma_f32_16x16x32_bf16 v[62:65], v[152:155], v[192:195], v[62:65]
	v_mfma_f32_16x16x32_bf16 v[54:57], v[156:159], v[188:191], v[54:57]
	v_mfma_f32_16x16x32_bf16 v[54:57], v[160:163], v[192:195], v[54:57]
	v_mfma_f32_16x16x32_bf16 v[46:49], v[148:151], v[196:199], v[46:49]
	v_mfma_f32_16x16x32_bf16 v[46:49], v[152:155], v[200:203], v[46:49]
	v_mfma_f32_16x16x32_bf16 v[38:41], v[156:159], v[196:199], v[38:41]
	v_mfma_f32_16x16x32_bf16 v[38:41], v[160:163], v[200:203], v[38:41]
	v_mfma_f32_16x16x32_bf16 v[30:33], v[148:151], v[204:207], v[30:33]
	v_mfma_f32_16x16x32_bf16 v[30:33], v[152:155], v[208:211], v[30:33]
	v_mfma_f32_16x16x32_bf16 v[22:25], v[156:159], v[204:207], v[22:25]
	v_mfma_f32_16x16x32_bf16 v[22:25], v[160:163], v[208:211], v[22:25]
	v_mfma_f32_16x16x32_bf16 v[14:17], v[148:151], v[212:215], v[14:17]
	v_mfma_f32_16x16x32_bf16 v[14:17], v[152:155], v[216:219], v[14:17]
	v_mfma_f32_16x16x32_bf16 v[6:9], v[156:159], v[212:215], v[6:9]
	v_mfma_f32_16x16x32_bf16 v[6:9], v[160:163], v[216:219], v[6:9]
	s_setprio 0
	s_setprio 1
	v_mfma_f32_16x16x32_bf16 v[58:61], v[172:175], v[188:191], v[58:61]
	v_mfma_f32_16x16x32_bf16 v[58:61], v[176:179], v[192:195], v[58:61]
	v_mfma_f32_16x16x32_bf16 v[50:53], v[180:183], v[188:191], v[50:53]
	v_mfma_f32_16x16x32_bf16 v[50:53], v[184:187], v[192:195], v[50:53]
	v_mfma_f32_16x16x32_bf16 v[42:45], v[172:175], v[196:199], v[42:45]
	v_mfma_f32_16x16x32_bf16 v[42:45], v[176:179], v[200:203], v[42:45]
	v_mfma_f32_16x16x32_bf16 v[34:37], v[180:183], v[196:199], v[34:37]
	v_mfma_f32_16x16x32_bf16 v[34:37], v[184:187], v[200:203], v[34:37]
	v_mfma_f32_16x16x32_bf16 v[26:29], v[172:175], v[204:207], v[26:29]
	v_mfma_f32_16x16x32_bf16 v[26:29], v[176:179], v[208:211], v[26:29]
	v_mfma_f32_16x16x32_bf16 v[18:21], v[180:183], v[204:207], v[18:21]
	v_mfma_f32_16x16x32_bf16 v[18:21], v[184:187], v[208:211], v[18:21]
	v_mfma_f32_16x16x32_bf16 v[10:13], v[172:175], v[212:215], v[10:13]
	v_mfma_f32_16x16x32_bf16 v[10:13], v[176:179], v[216:219], v[10:13]
	v_mfma_f32_16x16x32_bf16 v[2:5], v[180:183], v[212:215], v[2:5]
	v_mfma_f32_16x16x32_bf16 v[2:5], v[184:187], v[216:219], v[2:5]
	s_setprio 0
	s_barrier
	s_add_i32 s54, 0, 0x18000
	s_add_i32 s55, 0, 0x1c000
	v_add_u32_e32 v160, s54, v166
	v_add_u32_e32 v171, s55, v166
	ds_read_b128 v[148:151], v160
	ds_read_b128 v[152:155], v160 offset:1024
	ds_read_b128 v[156:159], v160 offset:2048
	ds_read_b128 v[160:163], v160 offset:3072
	ds_read_b128 v[172:175], v171
	ds_read_b128 v[176:179], v171 offset:1024
	ds_read_b128 v[180:183], v171 offset:2048
	ds_read_b128 v[184:187], v171 offset:3072
	s_add_u32 s0, s30, 0x40000
	s_addc_u32 s1, s31, 0
	s_mov_b32 m0, s39
	v_lshl_add_u64 v[228:229], s[0:1], 0, v[136:137]
	ds_read_b128 v[188:191], v169 offset:32768
	ds_read_b128 v[192:195], v169 offset:33792
	ds_read_b128 v[196:199], v169 offset:34816
	ds_read_b128 v[200:203], v169 offset:35840
	ds_read_b128 v[204:207], v169 offset:36864
	ds_read_b128 v[208:211], v169 offset:37888
	ds_read_b128 v[212:215], v169 offset:38912
	ds_read_b128 v[216:219], v169 offset:39936
	global_load_lds_dwordx4 v[228:229], off
	v_lshl_add_u64 v[228:229], s[0:1], 0, v[132:133]
	s_mov_b32 m0, s40
	s_nop 0
	global_load_lds_dwordx4 v[228:229], off
	s_waitcnt vmcnt(8)
	s_waitcnt lgkmcnt(0)
	s_barrier
	s_setprio 1
	s_waitcnt lgkmcnt(0)
	v_mfma_f32_16x16x32_bf16 v[126:129], v[148:151], v[188:191], v[126:129]
	v_mfma_f32_16x16x32_bf16 v[126:129], v[152:155], v[192:195], v[126:129]
	v_mfma_f32_16x16x32_bf16 v[118:121], v[156:159], v[188:191], v[118:121]
	v_mfma_f32_16x16x32_bf16 v[118:121], v[160:163], v[192:195], v[118:121]
	v_mfma_f32_16x16x32_bf16 v[110:113], v[148:151], v[196:199], v[110:113]
	v_mfma_f32_16x16x32_bf16 v[110:113], v[152:155], v[200:203], v[110:113]
	v_mfma_f32_16x16x32_bf16 v[102:105], v[156:159], v[196:199], v[102:105]
	v_mfma_f32_16x16x32_bf16 v[102:105], v[160:163], v[200:203], v[102:105]
	v_mfma_f32_16x16x32_bf16 v[94:97], v[148:151], v[204:207], v[94:97]
	v_mfma_f32_16x16x32_bf16 v[94:97], v[152:155], v[208:211], v[94:97]
	v_mfma_f32_16x16x32_bf16 v[86:89], v[156:159], v[204:207], v[86:89]
	v_mfma_f32_16x16x32_bf16 v[86:89], v[160:163], v[208:211], v[86:89]
	v_mfma_f32_16x16x32_bf16 v[78:81], v[148:151], v[212:215], v[78:81]
	v_mfma_f32_16x16x32_bf16 v[78:81], v[152:155], v[216:219], v[78:81]
	v_mfma_f32_16x16x32_bf16 v[70:73], v[156:159], v[212:215], v[70:73]
	v_mfma_f32_16x16x32_bf16 v[70:73], v[160:163], v[216:219], v[70:73]
	s_setprio 0
	s_setprio 1
	v_mfma_f32_16x16x32_bf16 v[122:125], v[172:175], v[188:191], v[122:125]
	v_mfma_f32_16x16x32_bf16 v[122:125], v[176:179], v[192:195], v[122:125]
	v_mfma_f32_16x16x32_bf16 v[114:117], v[180:183], v[188:191], v[114:117]
	v_mfma_f32_16x16x32_bf16 v[114:117], v[184:187], v[192:195], v[114:117]
	v_mfma_f32_16x16x32_bf16 v[106:109], v[172:175], v[196:199], v[106:109]
	v_mfma_f32_16x16x32_bf16 v[106:109], v[176:179], v[200:203], v[106:109]
	v_mfma_f32_16x16x32_bf16 v[98:101], v[180:183], v[196:199], v[98:101]
	v_mfma_f32_16x16x32_bf16 v[98:101], v[184:187], v[200:203], v[98:101]
	v_mfma_f32_16x16x32_bf16 v[90:93], v[172:175], v[204:207], v[90:93]
	v_mfma_f32_16x16x32_bf16 v[90:93], v[176:179], v[208:211], v[90:93]
	v_mfma_f32_16x16x32_bf16 v[82:85], v[180:183], v[204:207], v[82:85]
	v_mfma_f32_16x16x32_bf16 v[82:85], v[184:187], v[208:211], v[82:85]
	v_mfma_f32_16x16x32_bf16 v[74:77], v[172:175], v[212:215], v[74:77]
	v_mfma_f32_16x16x32_bf16 v[74:77], v[176:179], v[216:219], v[74:77]
	v_mfma_f32_16x16x32_bf16 v[66:69], v[180:183], v[212:215], v[66:69]
	v_mfma_f32_16x16x32_bf16 v[66:69], v[184:187], v[216:219], v[66:69]
	s_setprio 0
	s_barrier
	s_add_i32 s0, s54, s35
	v_lshl_add_u64 v[220:221], v[220:221], 0, s[14:15]
	s_mov_b32 m0, s0
	ds_read_b128 v[188:191], v169 offset:49152
	ds_read_b128 v[192:195], v169 offset:50176
	ds_read_b128 v[196:199], v169 offset:51200
	ds_read_b128 v[200:203], v169 offset:52224
	ds_read_b128 v[204:207], v169 offset:53248
	ds_read_b128 v[208:211], v169 offset:54272
	ds_read_b128 v[212:215], v169 offset:55296
	ds_read_b128 v[216:219], v169 offset:56320
	global_load_lds_dwordx4 v[220:221], off
	s_add_i32 m0, s0, 0x2000
	s_add_u32 s0, s2, 0x40080
	v_lshl_add_u64 v[220:221], v[222:223], 0, s[14:15]
	s_addc_u32 s1, s3, 0
	s_add_i32 s2, s55, s35
	global_load_lds_dwordx4 v[220:221], off
	v_lshl_add_u64 v[220:221], s[0:1], 0, v[134:135]
	s_mov_b32 m0, s2
	s_nop 0
	global_load_lds_dwordx4 v[220:221], off
	v_lshl_add_u64 v[220:221], s[0:1], 0, v[130:131]
	s_add_i32 m0, s2, 0x2000
	s_nop 0
	global_load_lds_dwordx4 v[220:221], off
	v_lshl_add_u64 v[220:221], v[224:225], 0, s[14:15]
	s_mov_b32 m0, s41
	s_nop 0
	global_load_lds_dwordx4 v[220:221], off
	v_lshl_add_u64 v[220:221], v[226:227], 0, s[14:15]
	s_mov_b32 m0, s42
	s_nop 0
	global_load_lds_dwordx4 v[220:221], off
	s_waitcnt vmcnt(8)
	s_waitcnt lgkmcnt(0)
	s_barrier
	s_setprio 1
	s_waitcnt lgkmcnt(0)
	v_mfma_f32_16x16x32_bf16 v[62:65], v[148:151], v[188:191], v[62:65]
	v_mfma_f32_16x16x32_bf16 v[62:65], v[152:155], v[192:195], v[62:65]
	v_mfma_f32_16x16x32_bf16 v[54:57], v[156:159], v[188:191], v[54:57]
	v_mfma_f32_16x16x32_bf16 v[54:57], v[160:163], v[192:195], v[54:57]
	v_mfma_f32_16x16x32_bf16 v[46:49], v[148:151], v[196:199], v[46:49]
	v_mfma_f32_16x16x32_bf16 v[46:49], v[152:155], v[200:203], v[46:49]
	v_mfma_f32_16x16x32_bf16 v[38:41], v[156:159], v[196:199], v[38:41]
	v_mfma_f32_16x16x32_bf16 v[38:41], v[160:163], v[200:203], v[38:41]
	v_mfma_f32_16x16x32_bf16 v[30:33], v[148:151], v[204:207], v[30:33]
	v_mfma_f32_16x16x32_bf16 v[30:33], v[152:155], v[208:211], v[30:33]
	v_mfma_f32_16x16x32_bf16 v[22:25], v[156:159], v[204:207], v[22:25]
	v_mfma_f32_16x16x32_bf16 v[22:25], v[160:163], v[208:211], v[22:25]
	v_mfma_f32_16x16x32_bf16 v[14:17], v[148:151], v[212:215], v[14:17]
	v_mfma_f32_16x16x32_bf16 v[14:17], v[152:155], v[216:219], v[14:17]
	v_mfma_f32_16x16x32_bf16 v[6:9], v[156:159], v[212:215], v[6:9]
	v_mfma_f32_16x16x32_bf16 v[6:9], v[160:163], v[216:219], v[6:9]
	s_setprio 0
	s_setprio 1
	v_mfma_f32_16x16x32_bf16 v[58:61], v[172:175], v[188:191], v[58:61]
	s_add_i32 s53, s53, 2
	s_add_u32 s28, s28, 0x100
	s_addc_u32 s29, s29, 0
	s_add_u32 s51, s51, 0x100
	s_addc_u32 s52, s52, 0
	s_cmp_gt_u32 s53, 13
	v_mfma_f32_16x16x32_bf16 v[58:61], v[176:179], v[192:195], v[58:61]
	v_mfma_f32_16x16x32_bf16 v[50:53], v[180:183], v[188:191], v[50:53]
	v_mfma_f32_16x16x32_bf16 v[50:53], v[184:187], v[192:195], v[50:53]
	v_mfma_f32_16x16x32_bf16 v[42:45], v[172:175], v[196:199], v[42:45]
	v_mfma_f32_16x16x32_bf16 v[42:45], v[176:179], v[200:203], v[42:45]
	v_mfma_f32_16x16x32_bf16 v[34:37], v[180:183], v[196:199], v[34:37]
	v_mfma_f32_16x16x32_bf16 v[34:37], v[184:187], v[200:203], v[34:37]
	v_mfma_f32_16x16x32_bf16 v[26:29], v[172:175], v[204:207], v[26:29]
	v_mfma_f32_16x16x32_bf16 v[26:29], v[176:179], v[208:211], v[26:29]
	v_mfma_f32_16x16x32_bf16 v[18:21], v[180:183], v[204:207], v[18:21]
	v_mfma_f32_16x16x32_bf16 v[18:21], v[184:187], v[208:211], v[18:21]
	v_mfma_f32_16x16x32_bf16 v[10:13], v[172:175], v[212:215], v[10:13]
	v_mfma_f32_16x16x32_bf16 v[10:13], v[176:179], v[216:219], v[10:13]
	v_mfma_f32_16x16x32_bf16 v[2:5], v[180:183], v[212:215], v[2:5]
	v_mfma_f32_16x16x32_bf16 v[2:5], v[184:187], v[216:219], v[2:5]
	s_setprio 0
	s_barrier
	s_cbranch_scc0 .LBB0_1009
	s_and_b64 vcc, exec, s[16:17]
	s_cbranch_vccz .LBB0_1012
	s_barrier

.LBB0_1123:
	ds_read_b128 v[130:133], v187
	ds_read_b128 v[134:137], v187 offset:1024
	ds_read_b128 v[138:141], v187 offset:2048
	ds_read_b128 v[142:145], v187 offset:3072
	ds_read_b128 v[146:149], v188
	ds_read_b128 v[150:153], v188 offset:1024
	ds_read_b128 v[170:173], v188 offset:2048
	ds_read_b128 v[174:177], v188 offset:3072
	s_add_u32 s0, s24, 0xfff50080
	s_addc_u32 s1, s25, -1
	s_cmp_eq_u32 s49, 40
	s_cselect_b32 s27, s9, s1
	s_cselect_b32 s26, s8, s0
	s_cselect_b32 s3, s23, s48
	s_cselect_b32 s2, s22, s47
	v_lshl_add_u64 v[220:221], s[24:25], 0, v[162:163]
	s_add_i32 m0, s34, 0xc000
	ds_read_b128 v[178:181], v189
	ds_read_b128 v[192:195], v189 offset:1024
	ds_read_b128 v[196:199], v189 offset:2048
	ds_read_b128 v[200:203], v189 offset:3072
	ds_read_b128 v[204:207], v189 offset:4096
	ds_read_b128 v[208:211], v189 offset:5120
	ds_read_b128 v[212:215], v189 offset:6144
	ds_read_b128 v[216:219], v189 offset:7168
	global_load_lds_dwordx4 v[220:221], off
	v_lshl_add_u64 v[220:221], s[24:25], 0, v[164:165]
	s_add_i32 m0, s34, 0xe000
	s_nop 0
	global_load_lds_dwordx4 v[220:221], off
	s_waitcnt vmcnt(8)
	s_waitcnt lgkmcnt(0)
	s_barrier
	s_setprio 1
	s_waitcnt lgkmcnt(0)
	v_mfma_f32_16x16x32_bf16 v[126:129], v[130:133], v[178:181], v[126:129]
	v_mfma_f32_16x16x32_bf16 v[126:129], v[134:137], v[192:195], v[126:129]
	v_mfma_f32_16x16x32_bf16 v[122:125], v[138:141], v[178:181], v[122:125]
	v_mfma_f32_16x16x32_bf16 v[122:125], v[142:145], v[192:195], v[122:125]
	v_mfma_f32_16x16x32_bf16 v[110:113], v[130:133], v[196:199], v[110:113]
	v_mfma_f32_16x16x32_bf16 v[110:113], v[134:137], v[200:203], v[110:113]
	v_mfma_f32_16x16x32_bf16 v[106:109], v[138:141], v[196:199], v[106:109]
	v_mfma_f32_16x16x32_bf16 v[106:109], v[142:145], v[200:203], v[106:109]
	v_mfma_f32_16x16x32_bf16 v[94:97], v[130:133], v[204:207], v[94:97]
	v_mfma_f32_16x16x32_bf16 v[94:97], v[134:137], v[208:211], v[94:97]
	v_mfma_f32_16x16x32_bf16 v[90:93], v[138:141], v[204:207], v[90:93]
	v_mfma_f32_16x16x32_bf16 v[90:93], v[142:145], v[208:211], v[90:93]
	v_mfma_f32_16x16x32_bf16 v[78:81], v[130:133], v[212:215], v[78:81]
	v_mfma_f32_16x16x32_bf16 v[78:81], v[134:137], v[216:219], v[78:81]
	v_mfma_f32_16x16x32_bf16 v[74:77], v[138:141], v[212:215], v[74:77]
	v_mfma_f32_16x16x32_bf16 v[74:77], v[142:145], v[216:219], v[74:77]
	s_setprio 0
	s_setprio 1
	v_mfma_f32_16x16x32_bf16 v[118:121], v[146:149], v[178:181], v[118:121]
	v_mfma_f32_16x16x32_bf16 v[118:121], v[150:153], v[192:195], v[118:121]
	v_mfma_f32_16x16x32_bf16 v[114:117], v[170:173], v[178:181], v[114:117]
	v_mfma_f32_16x16x32_bf16 v[114:117], v[174:177], v[192:195], v[114:117]
	v_mfma_f32_16x16x32_bf16 v[102:105], v[146:149], v[196:199], v[102:105]
	v_mfma_f32_16x16x32_bf16 v[102:105], v[150:153], v[200:203], v[102:105]
	v_mfma_f32_16x16x32_bf16 v[98:101], v[170:173], v[196:199], v[98:101]
	v_mfma_f32_16x16x32_bf16 v[98:101], v[174:177], v[200:203], v[98:101]
	v_mfma_f32_16x16x32_bf16 v[86:89], v[146:149], v[204:207], v[86:89]
	v_mfma_f32_16x16x32_bf16 v[86:89], v[150:153], v[208:211], v[86:89]
	v_mfma_f32_16x16x32_bf16 v[82:85], v[170:173], v[204:207], v[82:85]
	v_mfma_f32_16x16x32_bf16 v[82:85], v[174:177], v[208:211], v[82:85]
	v_mfma_f32_16x16x32_bf16 v[70:73], v[146:149], v[212:215], v[70:73]
	v_mfma_f32_16x16x32_bf16 v[70:73], v[150:153], v[216:219], v[70:73]
	v_mfma_f32_16x16x32_bf16 v[66:69], v[170:173], v[212:215], v[66:69]
	v_mfma_f32_16x16x32_bf16 v[66:69], v[174:177], v[216:219], v[66:69]
	s_setprio 0
	s_barrier
	s_add_i32 s0, s43, s33
	v_lshl_add_u64 v[220:221], s[2:3], 0, v[156:157]
	s_mov_b32 m0, s0
	ds_read_b128 v[178:181], v189 offset:16384
	ds_read_b128 v[192:195], v189 offset:17408
	ds_read_b128 v[196:199], v189 offset:18432
	ds_read_b128 v[200:203], v189 offset:19456
	ds_read_b128 v[204:207], v189 offset:20480
	ds_read_b128 v[208:211], v189 offset:21504
	ds_read_b128 v[212:215], v189 offset:22528
	ds_read_b128 v[216:219], v189 offset:23552
	global_load_lds_dwordx4 v[220:221], off
	s_add_i32 m0, s0, 0x2000
	s_add_u32 s0, s2, 0xb0000
	v_lshl_add_u64 v[222:223], s[2:3], 0, v[160:161]
	s_addc_u32 s1, s3, 0
	s_add_i32 s50, s44, s33
	global_load_lds_dwordx4 v[222:223], off
	v_lshl_add_u64 v[224:225], s[0:1], 0, v[156:157]
	s_mov_b32 m0, s50
	v_lshl_add_u64 v[226:227], s[26:27], 0, v[158:159]
	global_load_lds_dwordx4 v[224:225], off
	v_lshl_add_u64 v[224:225], s[0:1], 0, v[160:161]
	s_add_i32 m0, s50, 0x2000
	s_nop 0
	global_load_lds_dwordx4 v[224:225], off
	v_lshl_add_u64 v[224:225], s[26:27], 0, v[154:155]
	s_mov_b32 m0, s34
	s_nop 0
	global_load_lds_dwordx4 v[224:225], off
	s_mov_b32 m0, s35
	s_nop 0
	global_load_lds_dwordx4 v[226:227], off
	s_waitcnt vmcnt(8)
	s_waitcnt lgkmcnt(0)
	s_barrier
	s_setprio 1
	s_waitcnt lgkmcnt(0)
	v_mfma_f32_16x16x32_bf16 v[62:65], v[130:133], v[178:181], v[62:65]
	v_mfma_f32_16x16x32_bf16 v[62:65], v[134:137], v[192:195], v[62:65]
	v_mfma_f32_16x16x32_bf16 v[58:61], v[138:141], v[178:181], v[58:61]
	v_mfma_f32_16x16x32_bf16 v[58:61], v[142:145], v[192:195], v[58:61]
	v_mfma_f32_16x16x32_bf16 v[46:49], v[130:133], v[196:199], v[46:49]
	v_mfma_f32_16x16x32_bf16 v[46:49], v[134:137], v[200:203], v[46:49]
	v_mfma_f32_16x16x32_bf16 v[42:45], v[138:141], v[196:199], v[42:45]
	v_mfma_f32_16x16x32_bf16 v[42:45], v[142:145], v[200:203], v[42:45]
	v_mfma_f32_16x16x32_bf16 v[30:33], v[130:133], v[204:207], v[30:33]
	v_mfma_f32_16x16x32_bf16 v[30:33], v[134:137], v[208:211], v[30:33]
	v_mfma_f32_16x16x32_bf16 v[26:29], v[138:141], v[204:207], v[26:29]
	v_mfma_f32_16x16x32_bf16 v[26:29], v[142:145], v[208:211], v[26:29]
	v_mfma_f32_16x16x32_bf16 v[14:17], v[130:133], v[212:215], v[14:17]
	v_mfma_f32_16x16x32_bf16 v[14:17], v[134:137], v[216:219], v[14:17]
	v_mfma_f32_16x16x32_bf16 v[10:13], v[138:141], v[212:215], v[10:13]
	v_mfma_f32_16x16x32_bf16 v[10:13], v[142:145], v[216:219], v[10:13]
	s_setprio 0
	s_setprio 1
	v_mfma_f32_16x16x32_bf16 v[54:57], v[146:149], v[178:181], v[54:57]
	v_mfma_f32_16x16x32_bf16 v[54:57], v[150:153], v[192:195], v[54:57]
	v_mfma_f32_16x16x32_bf16 v[50:53], v[170:173], v[178:181], v[50:53]
	v_mfma_f32_16x16x32_bf16 v[50:53], v[174:177], v[192:195], v[50:53]
	v_mfma_f32_16x16x32_bf16 v[38:41], v[146:149], v[196:199], v[38:41]
	v_mfma_f32_16x16x32_bf16 v[38:41], v[150:153], v[200:203], v[38:41]
	v_mfma_f32_16x16x32_bf16 v[34:37], v[170:173], v[196:199], v[34:37]
	v_mfma_f32_16x16x32_bf16 v[34:37], v[174:177], v[200:203], v[34:37]
	v_mfma_f32_16x16x32_bf16 v[22:25], v[146:149], v[204:207], v[22:25]
	v_mfma_f32_16x16x32_bf16 v[22:25], v[150:153], v[208:211], v[22:25]
	v_mfma_f32_16x16x32_bf16 v[18:21], v[170:173], v[204:207], v[18:21]
	v_mfma_f32_16x16x32_bf16 v[18:21], v[174:177], v[208:211], v[18:21]
	v_mfma_f32_16x16x32_bf16 v[6:9], v[146:149], v[212:215], v[6:9]
	v_mfma_f32_16x16x32_bf16 v[6:9], v[150:153], v[216:219], v[6:9]
	v_mfma_f32_16x16x32_bf16 v[2:5], v[170:173], v[212:215], v[2:5]
	v_mfma_f32_16x16x32_bf16 v[2:5], v[174:177], v[216:219], v[2:5]
	s_setprio 0
	s_barrier
	s_add_i32 s50, 0, 0x18000
	s_add_i32 s51, 0, 0x1c000
	v_add_u32_e32 v142, s50, v183
	v_add_u32_e32 v174, s51, v183
	ds_read_b128 v[130:133], v142
	ds_read_b128 v[134:137], v142 offset:1024
	ds_read_b128 v[138:141], v142 offset:2048
	ds_read_b128 v[142:145], v142 offset:3072
	ds_read_b128 v[146:149], v174
	ds_read_b128 v[150:153], v174 offset:1024
	ds_read_b128 v[170:173], v174 offset:2048
	ds_read_b128 v[174:177], v174 offset:3072
	s_add_u32 s0, s26, 0xb0000
	s_addc_u32 s1, s27, 0
	s_mov_b32 m0, s36
	v_lshl_add_u64 v[228:229], s[0:1], 0, v[154:155]
	ds_read_b128 v[178:181], v189 offset:32768
	ds_read_b128 v[192:195], v189 offset:33792
	ds_read_b128 v[196:199], v189 offset:34816
	ds_read_b128 v[200:203], v189 offset:35840
	ds_read_b128 v[204:207], v189 offset:36864
	ds_read_b128 v[208:211], v189 offset:37888
	ds_read_b128 v[212:215], v189 offset:38912
	ds_read_b128 v[216:219], v189 offset:39936
	global_load_lds_dwordx4 v[228:229], off
	v_lshl_add_u64 v[228:229], s[0:1], 0, v[158:159]
	s_mov_b32 m0, s37
	s_nop 0
	global_load_lds_dwordx4 v[228:229], off
	s_waitcnt vmcnt(8)
	s_waitcnt lgkmcnt(0)
	s_barrier
	s_setprio 1
	s_waitcnt lgkmcnt(0)
	v_mfma_f32_16x16x32_bf16 v[126:129], v[130:133], v[178:181], v[126:129]
	v_mfma_f32_16x16x32_bf16 v[126:129], v[134:137], v[192:195], v[126:129]
	v_mfma_f32_16x16x32_bf16 v[122:125], v[138:141], v[178:181], v[122:125]
	v_mfma_f32_16x16x32_bf16 v[122:125], v[142:145], v[192:195], v[122:125]
	v_mfma_f32_16x16x32_bf16 v[110:113], v[130:133], v[196:199], v[110:113]
	v_mfma_f32_16x16x32_bf16 v[110:113], v[134:137], v[200:203], v[110:113]
	v_mfma_f32_16x16x32_bf16 v[106:109], v[138:141], v[196:199], v[106:109]
	v_mfma_f32_16x16x32_bf16 v[106:109], v[142:145], v[200:203], v[106:109]
	v_mfma_f32_16x16x32_bf16 v[94:97], v[130:133], v[204:207], v[94:97]
	v_mfma_f32_16x16x32_bf16 v[94:97], v[134:137], v[208:211], v[94:97]
	v_mfma_f32_16x16x32_bf16 v[90:93], v[138:141], v[204:207], v[90:93]
	v_mfma_f32_16x16x32_bf16 v[90:93], v[142:145], v[208:211], v[90:93]
	v_mfma_f32_16x16x32_bf16 v[78:81], v[130:133], v[212:215], v[78:81]
	v_mfma_f32_16x16x32_bf16 v[78:81], v[134:137], v[216:219], v[78:81]
	v_mfma_f32_16x16x32_bf16 v[74:77], v[138:141], v[212:215], v[74:77]
	v_mfma_f32_16x16x32_bf16 v[74:77], v[142:145], v[216:219], v[74:77]
	s_setprio 0
	s_setprio 1
	v_mfma_f32_16x16x32_bf16 v[118:121], v[146:149], v[178:181], v[118:121]
	v_mfma_f32_16x16x32_bf16 v[118:121], v[150:153], v[192:195], v[118:121]
	v_mfma_f32_16x16x32_bf16 v[114:117], v[170:173], v[178:181], v[114:117]
	v_mfma_f32_16x16x32_bf16 v[114:117], v[174:177], v[192:195], v[114:117]
	v_mfma_f32_16x16x32_bf16 v[102:105], v[146:149], v[196:199], v[102:105]
	v_mfma_f32_16x16x32_bf16 v[102:105], v[150:153], v[200:203], v[102:105]
	v_mfma_f32_16x16x32_bf16 v[98:101], v[170:173], v[196:199], v[98:101]
	v_mfma_f32_16x16x32_bf16 v[98:101], v[174:177], v[200:203], v[98:101]
	v_mfma_f32_16x16x32_bf16 v[86:89], v[146:149], v[204:207], v[86:89]
	v_mfma_f32_16x16x32_bf16 v[86:89], v[150:153], v[208:211], v[86:89]
	v_mfma_f32_16x16x32_bf16 v[82:85], v[170:173], v[204:207], v[82:85]
	v_mfma_f32_16x16x32_bf16 v[82:85], v[174:177], v[208:211], v[82:85]
	v_mfma_f32_16x16x32_bf16 v[70:73], v[146:149], v[212:215], v[70:73]
	v_mfma_f32_16x16x32_bf16 v[70:73], v[150:153], v[216:219], v[70:73]
	v_mfma_f32_16x16x32_bf16 v[66:69], v[170:173], v[212:215], v[66:69]
	v_mfma_f32_16x16x32_bf16 v[66:69], v[174:177], v[216:219], v[66:69]
	s_setprio 0
	s_barrier
	s_add_i32 s0, s50, s33
	v_lshl_add_u64 v[220:221], v[220:221], 0, s[16:17]
	s_mov_b32 m0, s0
	ds_read_b128 v[178:181], v189 offset:49152
	ds_read_b128 v[192:195], v189 offset:50176
	ds_read_b128 v[196:199], v189 offset:51200
	ds_read_b128 v[200:203], v189 offset:52224
	ds_read_b128 v[204:207], v189 offset:53248
	ds_read_b128 v[208:211], v189 offset:54272
	ds_read_b128 v[212:215], v189 offset:55296
	ds_read_b128 v[216:219], v189 offset:56320
	global_load_lds_dwordx4 v[220:221], off
	s_add_i32 m0, s0, 0x2000
	s_add_u32 s0, s2, 0xb0080
	v_lshl_add_u64 v[220:221], v[222:223], 0, s[16:17]
	s_addc_u32 s1, s3, 0
	s_add_i32 s2, s51, s33
	global_load_lds_dwordx4 v[220:221], off
	v_lshl_add_u64 v[220:221], s[0:1], 0, v[156:157]
	s_mov_b32 m0, s2
	s_nop 0
	global_load_lds_dwordx4 v[220:221], off
	v_lshl_add_u64 v[220:221], s[0:1], 0, v[160:161]
	s_add_i32 m0, s2, 0x2000
	s_nop 0
	global_load_lds_dwordx4 v[220:221], off
	v_lshl_add_u64 v[220:221], v[224:225], 0, s[16:17]
	s_mov_b32 m0, s39
	s_nop 0
	global_load_lds_dwordx4 v[220:221], off
	v_lshl_add_u64 v[220:221], v[226:227], 0, s[16:17]
	s_mov_b32 m0, s40
	s_nop 0
	global_load_lds_dwordx4 v[220:221], off
	s_waitcnt vmcnt(8)
	s_waitcnt lgkmcnt(0)
	s_barrier
	s_setprio 1
	s_waitcnt lgkmcnt(0)
	v_mfma_f32_16x16x32_bf16 v[62:65], v[130:133], v[178:181], v[62:65]
	v_mfma_f32_16x16x32_bf16 v[62:65], v[134:137], v[192:195], v[62:65]
	v_mfma_f32_16x16x32_bf16 v[58:61], v[138:141], v[178:181], v[58:61]
	v_mfma_f32_16x16x32_bf16 v[58:61], v[142:145], v[192:195], v[58:61]
	v_mfma_f32_16x16x32_bf16 v[46:49], v[130:133], v[196:199], v[46:49]
	v_mfma_f32_16x16x32_bf16 v[46:49], v[134:137], v[200:203], v[46:49]
	v_mfma_f32_16x16x32_bf16 v[42:45], v[138:141], v[196:199], v[42:45]
	v_mfma_f32_16x16x32_bf16 v[42:45], v[142:145], v[200:203], v[42:45]
	v_mfma_f32_16x16x32_bf16 v[30:33], v[130:133], v[204:207], v[30:33]
	v_mfma_f32_16x16x32_bf16 v[30:33], v[134:137], v[208:211], v[30:33]
	v_mfma_f32_16x16x32_bf16 v[26:29], v[138:141], v[204:207], v[26:29]
	v_mfma_f32_16x16x32_bf16 v[26:29], v[142:145], v[208:211], v[26:29]
	v_mfma_f32_16x16x32_bf16 v[14:17], v[130:133], v[212:215], v[14:17]
	v_mfma_f32_16x16x32_bf16 v[14:17], v[134:137], v[216:219], v[14:17]
	v_mfma_f32_16x16x32_bf16 v[10:13], v[138:141], v[212:215], v[10:13]
	v_mfma_f32_16x16x32_bf16 v[10:13], v[142:145], v[216:219], v[10:13]
	s_setprio 0
	s_setprio 1
	v_mfma_f32_16x16x32_bf16 v[54:57], v[146:149], v[178:181], v[54:57]
	s_add_i32 s49, s49, 2
	s_add_u32 s24, s24, 0x100
	s_addc_u32 s25, s25, 0
	s_add_u32 s47, s47, 0x100
	s_addc_u32 s48, s48, 0
	s_cmp_gt_u32 s49, 41
	v_mfma_f32_16x16x32_bf16 v[54:57], v[150:153], v[192:195], v[54:57]
	v_mfma_f32_16x16x32_bf16 v[50:53], v[170:173], v[178:181], v[50:53]
	v_mfma_f32_16x16x32_bf16 v[50:53], v[174:177], v[192:195], v[50:53]
	v_mfma_f32_16x16x32_bf16 v[38:41], v[146:149], v[196:199], v[38:41]
	v_mfma_f32_16x16x32_bf16 v[38:41], v[150:153], v[200:203], v[38:41]
	v_mfma_f32_16x16x32_bf16 v[34:37], v[170:173], v[196:199], v[34:37]
	v_mfma_f32_16x16x32_bf16 v[34:37], v[174:177], v[200:203], v[34:37]
	v_mfma_f32_16x16x32_bf16 v[22:25], v[146:149], v[204:207], v[22:25]
	v_mfma_f32_16x16x32_bf16 v[22:25], v[150:153], v[208:211], v[22:25]
	v_mfma_f32_16x16x32_bf16 v[18:21], v[170:173], v[204:207], v[18:21]
	v_mfma_f32_16x16x32_bf16 v[18:21], v[174:177], v[208:211], v[18:21]
	v_mfma_f32_16x16x32_bf16 v[6:9], v[146:149], v[212:215], v[6:9]
	v_mfma_f32_16x16x32_bf16 v[6:9], v[150:153], v[216:219], v[6:9]
	v_mfma_f32_16x16x32_bf16 v[2:5], v[170:173], v[212:215], v[2:5]
	v_mfma_f32_16x16x32_bf16 v[2:5], v[174:177], v[216:219], v[2:5]
	s_setprio 0
	s_barrier
	s_cbranch_scc0 .LBB0_1123
	s_and_b64 vcc, exec, s[18:19]
	s_cbranch_vccz .LBB0_1126
	s_barrier

.LBB0_1214:
	ds_read_b128 v[62:65], v208
	ds_read_b128 v[78:81], v208 offset:1024
	ds_read_b128 v[98:101], v208 offset:2048
	ds_read_b128 v[118:121], v208 offset:3072
	ds_read_b128 v[138:141], v209
	ds_read_b128 v[150:153], v209 offset:1024
	ds_read_b128 v[154:157], v209 offset:2048
	ds_read_b128 v[178:181], v209 offset:3072
	s_add_u32 s0, s38, 0xfffc0080
	s_addc_u32 s1, s39, -1
	s_cmp_eq_u32 s58, 12
	s_cselect_b32 s41, s7, s1
	s_cselect_b32 s40, s9, s0
	s_cselect_b32 s3, s10, s57
	s_cselect_b32 s2, s29, s31
	v_lshl_add_u64 v[202:203], s[38:39], 0, v[170:171]
	s_add_i32 m0, s43, 0xc000
	ds_read_b128 v[182:185], v210
	ds_read_b128 v[186:189], v210 offset:1024
	ds_read_b128 v[190:193], v210 offset:2048
	ds_read_b128 v[194:197], v210 offset:3072
	ds_read_b128 v[198:201], v210 offset:4096
	ds_read_b128 v[212:215], v210 offset:5120
	ds_read_b128 v[216:219], v210 offset:6144
	ds_read_b128 v[220:223], v210 offset:7168
	global_load_lds_dwordx4 v[202:203], off
	v_lshl_add_u64 v[202:203], s[38:39], 0, v[172:173]
	s_add_i32 m0, s43, 0xe000
	s_nop 0
	global_load_lds_dwordx4 v[202:203], off
	s_waitcnt vmcnt(8)
	s_waitcnt lgkmcnt(0)
	s_barrier
	s_setprio 1
	s_waitcnt lgkmcnt(0)
	v_mfma_f32_16x16x32_bf16 v[146:149], v[62:65], v[182:185], v[146:149]
	v_mfma_f32_16x16x32_bf16 v[146:149], v[78:81], v[186:189], v[146:149]
	v_mfma_f32_16x16x32_bf16 v[142:145], v[98:101], v[182:185], v[142:145]
	v_mfma_f32_16x16x32_bf16 v[142:145], v[118:121], v[186:189], v[142:145]
	v_mfma_f32_16x16x32_bf16 v[126:129], v[62:65], v[190:193], v[126:129]
	v_mfma_f32_16x16x32_bf16 v[126:129], v[78:81], v[194:197], v[126:129]
	v_mfma_f32_16x16x32_bf16 v[122:125], v[98:101], v[190:193], v[122:125]
	v_mfma_f32_16x16x32_bf16 v[122:125], v[118:121], v[194:197], v[122:125]
	v_mfma_f32_16x16x32_bf16 v[106:109], v[62:65], v[198:201], v[106:109]
	v_mfma_f32_16x16x32_bf16 v[106:109], v[78:81], v[212:215], v[106:109]
	v_mfma_f32_16x16x32_bf16 v[102:105], v[98:101], v[198:201], v[102:105]
	v_mfma_f32_16x16x32_bf16 v[102:105], v[118:121], v[212:215], v[102:105]
	v_mfma_f32_16x16x32_bf16 v[86:89], v[62:65], v[216:219], v[86:89]
	v_mfma_f32_16x16x32_bf16 v[86:89], v[78:81], v[220:223], v[86:89]
	v_mfma_f32_16x16x32_bf16 v[82:85], v[98:101], v[216:219], v[82:85]
	v_mfma_f32_16x16x32_bf16 v[82:85], v[118:121], v[220:223], v[82:85]
	s_setprio 0
	s_setprio 1
	v_mfma_f32_16x16x32_bf16 v[134:137], v[138:141], v[182:185], v[134:137]
	v_mfma_f32_16x16x32_bf16 v[134:137], v[150:153], v[186:189], v[134:137]
	v_mfma_f32_16x16x32_bf16 v[130:133], v[154:157], v[182:185], v[130:133]
	v_mfma_f32_16x16x32_bf16 v[130:133], v[178:181], v[186:189], v[130:133]
	v_mfma_f32_16x16x32_bf16 v[114:117], v[138:141], v[190:193], v[114:117]
	v_mfma_f32_16x16x32_bf16 v[114:117], v[150:153], v[194:197], v[114:117]
	v_mfma_f32_16x16x32_bf16 v[110:113], v[154:157], v[190:193], v[110:113]
	v_mfma_f32_16x16x32_bf16 v[110:113], v[178:181], v[194:197], v[110:113]
	v_mfma_f32_16x16x32_bf16 v[94:97], v[138:141], v[198:201], v[94:97]
	v_mfma_f32_16x16x32_bf16 v[94:97], v[150:153], v[212:215], v[94:97]
	v_mfma_f32_16x16x32_bf16 v[90:93], v[154:157], v[198:201], v[90:93]
	v_mfma_f32_16x16x32_bf16 v[90:93], v[178:181], v[212:215], v[90:93]
	v_mfma_f32_16x16x32_bf16 v[74:77], v[138:141], v[216:219], v[74:77]
	v_mfma_f32_16x16x32_bf16 v[74:77], v[150:153], v[220:223], v[74:77]
	v_mfma_f32_16x16x32_bf16 v[70:73], v[154:157], v[216:219], v[70:73]
	v_mfma_f32_16x16x32_bf16 v[70:73], v[178:181], v[220:223], v[70:73]
	s_setprio 0
	s_barrier
	s_add_i32 s0, s53, s42
	v_lshl_add_u64 v[202:203], s[2:3], 0, v[162:163]
	s_mov_b32 m0, s0
	ds_read_b128 v[182:185], v210 offset:16384
	ds_read_b128 v[186:189], v210 offset:17408
	ds_read_b128 v[190:193], v210 offset:18432
	ds_read_b128 v[194:197], v210 offset:19456
	ds_read_b128 v[198:201], v210 offset:20480
	ds_read_b128 v[212:215], v210 offset:21504
	ds_read_b128 v[216:219], v210 offset:22528
	ds_read_b128 v[220:223], v210 offset:23552
	global_load_lds_dwordx4 v[202:203], off
	s_add_i32 m0, s0, 0x2000
	s_add_u32 s0, s2, 0x40000
	v_lshl_add_u64 v[224:225], s[2:3], 0, v[166:167]
	s_addc_u32 s1, s3, 0
	s_add_i32 s59, s54, s42
	global_load_lds_dwordx4 v[224:225], off
	v_lshl_add_u64 v[226:227], s[0:1], 0, v[162:163]
	s_mov_b32 m0, s59
	v_lshl_add_u64 v[228:229], s[40:41], 0, v[164:165]
	global_load_lds_dwordx4 v[226:227], off
	v_lshl_add_u64 v[226:227], s[0:1], 0, v[166:167]
	s_add_i32 m0, s59, 0x2000
	s_nop 0
	global_load_lds_dwordx4 v[226:227], off
	v_lshl_add_u64 v[226:227], s[40:41], 0, v[160:161]
	s_mov_b32 m0, s43
	s_nop 0
	global_load_lds_dwordx4 v[226:227], off
	s_mov_b32 m0, s44
	s_nop 0
	global_load_lds_dwordx4 v[228:229], off
	s_waitcnt vmcnt(8)
	s_waitcnt lgkmcnt(0)
	s_barrier
	s_setprio 1
	s_waitcnt lgkmcnt(0)
	v_mfma_f32_16x16x32_bf16 v[66:69], v[62:65], v[182:185], v[66:69]
	v_mfma_f32_16x16x32_bf16 v[66:69], v[78:81], v[186:189], v[66:69]
	v_mfma_f32_16x16x32_bf16 v[58:61], v[98:101], v[182:185], v[58:61]
	v_mfma_f32_16x16x32_bf16 v[58:61], v[118:121], v[186:189], v[58:61]
	v_mfma_f32_16x16x32_bf16 v[46:49], v[62:65], v[190:193], v[46:49]
	v_mfma_f32_16x16x32_bf16 v[46:49], v[78:81], v[194:197], v[46:49]
	v_mfma_f32_16x16x32_bf16 v[42:45], v[98:101], v[190:193], v[42:45]
	v_mfma_f32_16x16x32_bf16 v[42:45], v[118:121], v[194:197], v[42:45]
	v_mfma_f32_16x16x32_bf16 v[30:33], v[62:65], v[198:201], v[30:33]
	v_mfma_f32_16x16x32_bf16 v[30:33], v[78:81], v[212:215], v[30:33]
	v_mfma_f32_16x16x32_bf16 v[26:29], v[98:101], v[198:201], v[26:29]
	v_mfma_f32_16x16x32_bf16 v[26:29], v[118:121], v[212:215], v[26:29]
	v_mfma_f32_16x16x32_bf16 v[14:17], v[62:65], v[216:219], v[14:17]
	v_mfma_f32_16x16x32_bf16 v[14:17], v[78:81], v[220:223], v[14:17]
	v_mfma_f32_16x16x32_bf16 v[10:13], v[98:101], v[216:219], v[10:13]
	v_mfma_f32_16x16x32_bf16 v[10:13], v[118:121], v[220:223], v[10:13]
	s_setprio 0
	s_setprio 1
	v_mfma_f32_16x16x32_bf16 v[54:57], v[138:141], v[182:185], v[54:57]
	v_mfma_f32_16x16x32_bf16 v[54:57], v[150:153], v[186:189], v[54:57]
	v_mfma_f32_16x16x32_bf16 v[50:53], v[154:157], v[182:185], v[50:53]
	v_mfma_f32_16x16x32_bf16 v[50:53], v[178:181], v[186:189], v[50:53]
	v_mfma_f32_16x16x32_bf16 v[38:41], v[138:141], v[190:193], v[38:41]
	v_mfma_f32_16x16x32_bf16 v[38:41], v[150:153], v[194:197], v[38:41]
	v_mfma_f32_16x16x32_bf16 v[34:37], v[154:157], v[190:193], v[34:37]
	v_mfma_f32_16x16x32_bf16 v[34:37], v[178:181], v[194:197], v[34:37]
	v_mfma_f32_16x16x32_bf16 v[22:25], v[138:141], v[198:201], v[22:25]
	v_mfma_f32_16x16x32_bf16 v[22:25], v[150:153], v[212:215], v[22:25]
	v_mfma_f32_16x16x32_bf16 v[18:21], v[154:157], v[198:201], v[18:21]
	v_mfma_f32_16x16x32_bf16 v[18:21], v[178:181], v[212:215], v[18:21]
	v_mfma_f32_16x16x32_bf16 v[6:9], v[138:141], v[216:219], v[6:9]
	v_mfma_f32_16x16x32_bf16 v[6:9], v[150:153], v[220:223], v[6:9]
	v_mfma_f32_16x16x32_bf16 v[2:5], v[154:157], v[216:219], v[2:5]
	v_mfma_f32_16x16x32_bf16 v[2:5], v[178:181], v[220:223], v[2:5]
	s_setprio 0
	s_barrier
	s_add_i32 s59, 0, 0x18000
	s_add_i32 s60, 0, 0x1c000
	v_add_u32_e32 v118, s59, v206
	v_add_u32_e32 v168, s60, v206
	ds_read_b128 v[62:65], v118
	ds_read_b128 v[78:81], v118 offset:1024
	ds_read_b128 v[98:101], v118 offset:2048
	ds_read_b128 v[118:121], v118 offset:3072
	ds_read_b128 v[138:141], v168
	ds_read_b128 v[150:153], v168 offset:1024
	ds_read_b128 v[154:157], v168 offset:2048
	ds_read_b128 v[178:181], v168 offset:3072
	s_add_u32 s0, s40, 0x40000
	s_addc_u32 s1, s41, 0
	s_mov_b32 m0, s45
	v_lshl_add_u64 v[230:231], s[0:1], 0, v[160:161]
	ds_read_b128 v[182:185], v210 offset:32768
	ds_read_b128 v[186:189], v210 offset:33792
	ds_read_b128 v[190:193], v210 offset:34816
	ds_read_b128 v[194:197], v210 offset:35840
	ds_read_b128 v[198:201], v210 offset:36864
	ds_read_b128 v[212:215], v210 offset:37888
	ds_read_b128 v[216:219], v210 offset:38912
	ds_read_b128 v[220:223], v210 offset:39936
	global_load_lds_dwordx4 v[230:231], off
	v_lshl_add_u64 v[230:231], s[0:1], 0, v[164:165]
	s_mov_b32 m0, s46
	s_nop 0
	global_load_lds_dwordx4 v[230:231], off
	s_waitcnt vmcnt(8)
	s_waitcnt lgkmcnt(0)
	s_barrier
	s_setprio 1
	s_waitcnt lgkmcnt(0)
	v_mfma_f32_16x16x32_bf16 v[146:149], v[62:65], v[182:185], v[146:149]
	v_mfma_f32_16x16x32_bf16 v[146:149], v[78:81], v[186:189], v[146:149]
	v_mfma_f32_16x16x32_bf16 v[142:145], v[98:101], v[182:185], v[142:145]
	v_mfma_f32_16x16x32_bf16 v[142:145], v[118:121], v[186:189], v[142:145]
	v_mfma_f32_16x16x32_bf16 v[126:129], v[62:65], v[190:193], v[126:129]
	v_mfma_f32_16x16x32_bf16 v[126:129], v[78:81], v[194:197], v[126:129]
	v_mfma_f32_16x16x32_bf16 v[122:125], v[98:101], v[190:193], v[122:125]
	v_mfma_f32_16x16x32_bf16 v[122:125], v[118:121], v[194:197], v[122:125]
	v_mfma_f32_16x16x32_bf16 v[106:109], v[62:65], v[198:201], v[106:109]
	v_mfma_f32_16x16x32_bf16 v[106:109], v[78:81], v[212:215], v[106:109]
	v_mfma_f32_16x16x32_bf16 v[102:105], v[98:101], v[198:201], v[102:105]
	v_mfma_f32_16x16x32_bf16 v[102:105], v[118:121], v[212:215], v[102:105]
	v_mfma_f32_16x16x32_bf16 v[86:89], v[62:65], v[216:219], v[86:89]
	v_mfma_f32_16x16x32_bf16 v[86:89], v[78:81], v[220:223], v[86:89]
	v_mfma_f32_16x16x32_bf16 v[82:85], v[98:101], v[216:219], v[82:85]
	v_mfma_f32_16x16x32_bf16 v[82:85], v[118:121], v[220:223], v[82:85]
	s_setprio 0
	s_setprio 1
	v_mfma_f32_16x16x32_bf16 v[134:137], v[138:141], v[182:185], v[134:137]
	v_mfma_f32_16x16x32_bf16 v[134:137], v[150:153], v[186:189], v[134:137]
	v_mfma_f32_16x16x32_bf16 v[130:133], v[154:157], v[182:185], v[130:133]
	v_mfma_f32_16x16x32_bf16 v[130:133], v[178:181], v[186:189], v[130:133]
	v_mfma_f32_16x16x32_bf16 v[114:117], v[138:141], v[190:193], v[114:117]
	v_mfma_f32_16x16x32_bf16 v[114:117], v[150:153], v[194:197], v[114:117]
	v_mfma_f32_16x16x32_bf16 v[110:113], v[154:157], v[190:193], v[110:113]
	v_mfma_f32_16x16x32_bf16 v[110:113], v[178:181], v[194:197], v[110:113]
	v_mfma_f32_16x16x32_bf16 v[94:97], v[138:141], v[198:201], v[94:97]
	v_mfma_f32_16x16x32_bf16 v[94:97], v[150:153], v[212:215], v[94:97]
	v_mfma_f32_16x16x32_bf16 v[90:93], v[154:157], v[198:201], v[90:93]
	v_mfma_f32_16x16x32_bf16 v[90:93], v[178:181], v[212:215], v[90:93]
	v_mfma_f32_16x16x32_bf16 v[74:77], v[138:141], v[216:219], v[74:77]
	v_mfma_f32_16x16x32_bf16 v[74:77], v[150:153], v[220:223], v[74:77]
	v_mfma_f32_16x16x32_bf16 v[70:73], v[154:157], v[216:219], v[70:73]
	v_mfma_f32_16x16x32_bf16 v[70:73], v[178:181], v[220:223], v[70:73]
	s_setprio 0
	s_barrier
	s_add_i32 s0, s59, s42
	v_lshl_add_u64 v[202:203], v[202:203], 0, s[22:23]
	s_mov_b32 m0, s0
	ds_read_b128 v[182:185], v210 offset:49152
	ds_read_b128 v[186:189], v210 offset:50176
	ds_read_b128 v[190:193], v210 offset:51200
	ds_read_b128 v[194:197], v210 offset:52224
	ds_read_b128 v[198:201], v210 offset:53248
	ds_read_b128 v[212:215], v210 offset:54272
	ds_read_b128 v[216:219], v210 offset:55296
	ds_read_b128 v[220:223], v210 offset:56320
	global_load_lds_dwordx4 v[202:203], off
	s_add_i32 m0, s0, 0x2000
	s_add_u32 s0, s2, 0x40080
	v_lshl_add_u64 v[202:203], v[224:225], 0, s[22:23]
	s_addc_u32 s1, s3, 0
	s_add_i32 s2, s60, s42
	global_load_lds_dwordx4 v[202:203], off
	v_lshl_add_u64 v[202:203], s[0:1], 0, v[162:163]
	s_mov_b32 m0, s2
	s_nop 0
	global_load_lds_dwordx4 v[202:203], off
	v_lshl_add_u64 v[202:203], s[0:1], 0, v[166:167]
	s_add_i32 m0, s2, 0x2000
	s_nop 0
	global_load_lds_dwordx4 v[202:203], off
	v_lshl_add_u64 v[202:203], v[226:227], 0, s[22:23]
	s_mov_b32 m0, s49
	s_nop 0
	global_load_lds_dwordx4 v[202:203], off
	v_lshl_add_u64 v[202:203], v[228:229], 0, s[22:23]
	s_mov_b32 m0, s50
	s_nop 0
	global_load_lds_dwordx4 v[202:203], off
	s_waitcnt vmcnt(8)
	s_waitcnt lgkmcnt(0)
	s_barrier
	s_setprio 1
	s_waitcnt lgkmcnt(0)
	v_mfma_f32_16x16x32_bf16 v[66:69], v[62:65], v[182:185], v[66:69]
	v_mfma_f32_16x16x32_bf16 v[66:69], v[78:81], v[186:189], v[66:69]
	v_mfma_f32_16x16x32_bf16 v[58:61], v[98:101], v[182:185], v[58:61]
	v_mfma_f32_16x16x32_bf16 v[58:61], v[118:121], v[186:189], v[58:61]
	v_mfma_f32_16x16x32_bf16 v[46:49], v[62:65], v[190:193], v[46:49]
	v_mfma_f32_16x16x32_bf16 v[46:49], v[78:81], v[194:197], v[46:49]
	v_mfma_f32_16x16x32_bf16 v[42:45], v[98:101], v[190:193], v[42:45]
	v_mfma_f32_16x16x32_bf16 v[42:45], v[118:121], v[194:197], v[42:45]
	v_mfma_f32_16x16x32_bf16 v[30:33], v[62:65], v[198:201], v[30:33]
	v_mfma_f32_16x16x32_bf16 v[30:33], v[78:81], v[212:215], v[30:33]
	v_mfma_f32_16x16x32_bf16 v[26:29], v[98:101], v[198:201], v[26:29]
	v_mfma_f32_16x16x32_bf16 v[26:29], v[118:121], v[212:215], v[26:29]
	v_mfma_f32_16x16x32_bf16 v[14:17], v[62:65], v[216:219], v[14:17]
	v_mfma_f32_16x16x32_bf16 v[14:17], v[78:81], v[220:223], v[14:17]
	v_mfma_f32_16x16x32_bf16 v[10:13], v[98:101], v[216:219], v[10:13]
	v_mfma_f32_16x16x32_bf16 v[10:13], v[118:121], v[220:223], v[10:13]
	s_setprio 0
	s_setprio 1
	v_mfma_f32_16x16x32_bf16 v[54:57], v[138:141], v[182:185], v[54:57]
	s_add_i32 s58, s58, 2
	s_add_u32 s38, s38, 0x100
	s_addc_u32 s39, s39, 0
	s_add_u32 s31, s31, 0x100
	s_addc_u32 s57, s57, 0
	s_cmp_gt_u32 s58, 13
	v_mfma_f32_16x16x32_bf16 v[54:57], v[150:153], v[186:189], v[54:57]
	v_mfma_f32_16x16x32_bf16 v[50:53], v[154:157], v[182:185], v[50:53]
	v_mfma_f32_16x16x32_bf16 v[50:53], v[178:181], v[186:189], v[50:53]
	v_mfma_f32_16x16x32_bf16 v[38:41], v[138:141], v[190:193], v[38:41]
	v_mfma_f32_16x16x32_bf16 v[38:41], v[150:153], v[194:197], v[38:41]
	v_mfma_f32_16x16x32_bf16 v[34:37], v[154:157], v[190:193], v[34:37]
	v_mfma_f32_16x16x32_bf16 v[34:37], v[178:181], v[194:197], v[34:37]
	v_mfma_f32_16x16x32_bf16 v[22:25], v[138:141], v[198:201], v[22:25]
	v_mfma_f32_16x16x32_bf16 v[22:25], v[150:153], v[212:215], v[22:25]
	v_mfma_f32_16x16x32_bf16 v[18:21], v[154:157], v[198:201], v[18:21]
	v_mfma_f32_16x16x32_bf16 v[18:21], v[178:181], v[212:215], v[18:21]
	v_mfma_f32_16x16x32_bf16 v[6:9], v[138:141], v[216:219], v[6:9]
	v_mfma_f32_16x16x32_bf16 v[6:9], v[150:153], v[220:223], v[6:9]
	v_mfma_f32_16x16x32_bf16 v[2:5], v[154:157], v[216:219], v[2:5]
	v_mfma_f32_16x16x32_bf16 v[2:5], v[178:181], v[220:223], v[2:5]
	s_setprio 0
	s_barrier
	s_cbranch_scc0 .LBB0_1214
	s_and_b64 vcc, exec, s[24:25]
	s_cbranch_vccz .LBB0_1217
	s_barrier

.LBB0_1626:
	ds_read_b128 v[130:133], v186
	ds_read_b128 v[134:137], v186 offset:1024
	ds_read_b128 v[138:141], v186 offset:2048
	ds_read_b128 v[142:145], v186 offset:3072
	ds_read_b128 v[146:149], v187
	ds_read_b128 v[150:153], v187 offset:1024
	ds_read_b128 v[170:173], v187 offset:2048
	ds_read_b128 v[174:177], v187 offset:3072
	s_add_u32 s0, s38, 0xfff80080
	s_addc_u32 s1, s39, -1
	s_cmp_eq_u32 s59, 28
	s_cselect_b32 s41, s11, s1
	s_cselect_b32 s40, s29, s0
	s_cselect_b32 s3, s27, s58
	s_cselect_b32 s2, s56, s57
	v_lshl_add_u64 v[218:219], s[38:39], 0, v[162:163]
	s_add_i32 m0, s37, 0xc000
	ds_read_b128 v[178:181], v188
	ds_read_b128 v[190:193], v188 offset:1024
	ds_read_b128 v[194:197], v188 offset:2048
	ds_read_b128 v[198:201], v188 offset:3072
	ds_read_b128 v[202:205], v188 offset:4096
	ds_read_b128 v[206:209], v188 offset:5120
	ds_read_b128 v[210:213], v188 offset:6144
	ds_read_b128 v[214:217], v188 offset:7168
	global_load_lds_dwordx4 v[218:219], off
	v_lshl_add_u64 v[218:219], s[38:39], 0, v[164:165]
	s_add_i32 m0, s37, 0xe000
	s_nop 0
	global_load_lds_dwordx4 v[218:219], off
	s_waitcnt vmcnt(8)
	s_waitcnt lgkmcnt(0)
	s_barrier
	s_setprio 1
	s_waitcnt lgkmcnt(0)
	v_mfma_f32_16x16x32_bf16 v[126:129], v[130:133], v[178:181], v[126:129]
	v_mfma_f32_16x16x32_bf16 v[126:129], v[134:137], v[190:193], v[126:129]
	v_mfma_f32_16x16x32_bf16 v[122:125], v[138:141], v[178:181], v[122:125]
	v_mfma_f32_16x16x32_bf16 v[122:125], v[142:145], v[190:193], v[122:125]
	v_mfma_f32_16x16x32_bf16 v[110:113], v[130:133], v[194:197], v[110:113]
	v_mfma_f32_16x16x32_bf16 v[110:113], v[134:137], v[198:201], v[110:113]
	v_mfma_f32_16x16x32_bf16 v[106:109], v[138:141], v[194:197], v[106:109]
	v_mfma_f32_16x16x32_bf16 v[106:109], v[142:145], v[198:201], v[106:109]
	v_mfma_f32_16x16x32_bf16 v[94:97], v[130:133], v[202:205], v[94:97]
	v_mfma_f32_16x16x32_bf16 v[94:97], v[134:137], v[206:209], v[94:97]
	v_mfma_f32_16x16x32_bf16 v[90:93], v[138:141], v[202:205], v[90:93]
	v_mfma_f32_16x16x32_bf16 v[90:93], v[142:145], v[206:209], v[90:93]
	v_mfma_f32_16x16x32_bf16 v[78:81], v[130:133], v[210:213], v[78:81]
	v_mfma_f32_16x16x32_bf16 v[78:81], v[134:137], v[214:217], v[78:81]
	v_mfma_f32_16x16x32_bf16 v[74:77], v[138:141], v[210:213], v[74:77]
	v_mfma_f32_16x16x32_bf16 v[74:77], v[142:145], v[214:217], v[74:77]
	s_setprio 0
	s_setprio 1
	v_mfma_f32_16x16x32_bf16 v[118:121], v[146:149], v[178:181], v[118:121]
	v_mfma_f32_16x16x32_bf16 v[118:121], v[150:153], v[190:193], v[118:121]
	v_mfma_f32_16x16x32_bf16 v[114:117], v[170:173], v[178:181], v[114:117]
	v_mfma_f32_16x16x32_bf16 v[114:117], v[174:177], v[190:193], v[114:117]
	v_mfma_f32_16x16x32_bf16 v[102:105], v[146:149], v[194:197], v[102:105]
	v_mfma_f32_16x16x32_bf16 v[102:105], v[150:153], v[198:201], v[102:105]
	v_mfma_f32_16x16x32_bf16 v[98:101], v[170:173], v[194:197], v[98:101]
	v_mfma_f32_16x16x32_bf16 v[98:101], v[174:177], v[198:201], v[98:101]
	v_mfma_f32_16x16x32_bf16 v[86:89], v[146:149], v[202:205], v[86:89]
	v_mfma_f32_16x16x32_bf16 v[86:89], v[150:153], v[206:209], v[86:89]
	v_mfma_f32_16x16x32_bf16 v[82:85], v[170:173], v[202:205], v[82:85]
	v_mfma_f32_16x16x32_bf16 v[82:85], v[174:177], v[206:209], v[82:85]
	v_mfma_f32_16x16x32_bf16 v[70:73], v[146:149], v[210:213], v[70:73]
	v_mfma_f32_16x16x32_bf16 v[70:73], v[150:153], v[214:217], v[70:73]
	v_mfma_f32_16x16x32_bf16 v[66:69], v[170:173], v[210:213], v[66:69]
	v_mfma_f32_16x16x32_bf16 v[66:69], v[174:177], v[214:217], v[66:69]
	s_setprio 0
	s_barrier
	s_add_i32 s0, s54, s45
	v_lshl_add_u64 v[218:219], s[2:3], 0, v[156:157]
	s_mov_b32 m0, s0
	ds_read_b128 v[178:181], v188 offset:16384
	ds_read_b128 v[190:193], v188 offset:17408
	ds_read_b128 v[194:197], v188 offset:18432
	ds_read_b128 v[198:201], v188 offset:19456
	ds_read_b128 v[202:205], v188 offset:20480
	ds_read_b128 v[206:209], v188 offset:21504
	ds_read_b128 v[210:213], v188 offset:22528
	ds_read_b128 v[214:217], v188 offset:23552
	global_load_lds_dwordx4 v[218:219], off
	s_add_i32 m0, s0, 0x2000
	s_add_u32 s0, s2, 0x80000
	v_lshl_add_u64 v[220:221], s[2:3], 0, v[160:161]
	s_addc_u32 s1, s3, 0
	s_add_i32 s60, s55, s45
	global_load_lds_dwordx4 v[220:221], off
	v_lshl_add_u64 v[222:223], s[0:1], 0, v[156:157]
	s_mov_b32 m0, s60
	v_lshl_add_u64 v[224:225], s[40:41], 0, v[158:159]
	global_load_lds_dwordx4 v[222:223], off
	v_lshl_add_u64 v[222:223], s[0:1], 0, v[160:161]
	s_add_i32 m0, s60, 0x2000
	s_nop 0
	global_load_lds_dwordx4 v[222:223], off
	v_lshl_add_u64 v[222:223], s[40:41], 0, v[154:155]
	s_mov_b32 m0, s37
	s_nop 0
	global_load_lds_dwordx4 v[222:223], off
	s_mov_b32 m0, s46
	s_nop 0
	global_load_lds_dwordx4 v[224:225], off
	s_waitcnt vmcnt(8)
	s_waitcnt lgkmcnt(0)
	s_barrier
	s_setprio 1
	s_waitcnt lgkmcnt(0)
	v_mfma_f32_16x16x32_bf16 v[62:65], v[130:133], v[178:181], v[62:65]
	v_mfma_f32_16x16x32_bf16 v[62:65], v[134:137], v[190:193], v[62:65]
	v_mfma_f32_16x16x32_bf16 v[58:61], v[138:141], v[178:181], v[58:61]
	v_mfma_f32_16x16x32_bf16 v[58:61], v[142:145], v[190:193], v[58:61]
	v_mfma_f32_16x16x32_bf16 v[46:49], v[130:133], v[194:197], v[46:49]
	v_mfma_f32_16x16x32_bf16 v[46:49], v[134:137], v[198:201], v[46:49]
	v_mfma_f32_16x16x32_bf16 v[42:45], v[138:141], v[194:197], v[42:45]
	v_mfma_f32_16x16x32_bf16 v[42:45], v[142:145], v[198:201], v[42:45]
	v_mfma_f32_16x16x32_bf16 v[30:33], v[130:133], v[202:205], v[30:33]
	v_mfma_f32_16x16x32_bf16 v[30:33], v[134:137], v[206:209], v[30:33]
	v_mfma_f32_16x16x32_bf16 v[26:29], v[138:141], v[202:205], v[26:29]
	v_mfma_f32_16x16x32_bf16 v[26:29], v[142:145], v[206:209], v[26:29]
	v_mfma_f32_16x16x32_bf16 v[14:17], v[130:133], v[210:213], v[14:17]
	v_mfma_f32_16x16x32_bf16 v[14:17], v[134:137], v[214:217], v[14:17]
	v_mfma_f32_16x16x32_bf16 v[10:13], v[138:141], v[210:213], v[10:13]
	v_mfma_f32_16x16x32_bf16 v[10:13], v[142:145], v[214:217], v[10:13]
	s_setprio 0
	s_setprio 1
	v_mfma_f32_16x16x32_bf16 v[54:57], v[146:149], v[178:181], v[54:57]
	v_mfma_f32_16x16x32_bf16 v[54:57], v[150:153], v[190:193], v[54:57]
	v_mfma_f32_16x16x32_bf16 v[50:53], v[170:173], v[178:181], v[50:53]
	v_mfma_f32_16x16x32_bf16 v[50:53], v[174:177], v[190:193], v[50:53]
	v_mfma_f32_16x16x32_bf16 v[38:41], v[146:149], v[194:197], v[38:41]
	v_mfma_f32_16x16x32_bf16 v[38:41], v[150:153], v[198:201], v[38:41]
	v_mfma_f32_16x16x32_bf16 v[34:37], v[170:173], v[194:197], v[34:37]
	v_mfma_f32_16x16x32_bf16 v[34:37], v[174:177], v[198:201], v[34:37]
	v_mfma_f32_16x16x32_bf16 v[22:25], v[146:149], v[202:205], v[22:25]
	v_mfma_f32_16x16x32_bf16 v[22:25], v[150:153], v[206:209], v[22:25]
	v_mfma_f32_16x16x32_bf16 v[18:21], v[170:173], v[202:205], v[18:21]
	v_mfma_f32_16x16x32_bf16 v[18:21], v[174:177], v[206:209], v[18:21]
	v_mfma_f32_16x16x32_bf16 v[6:9], v[146:149], v[210:213], v[6:9]
	v_mfma_f32_16x16x32_bf16 v[6:9], v[150:153], v[214:217], v[6:9]
	v_mfma_f32_16x16x32_bf16 v[2:5], v[170:173], v[210:213], v[2:5]
	v_mfma_f32_16x16x32_bf16 v[2:5], v[174:177], v[214:217], v[2:5]
	s_setprio 0
	s_barrier
	s_add_i32 s60, 0, 0x18000
	s_add_i32 s61, 0, 0x1c000
	v_add_u32_e32 v142, s60, v182
	v_add_u32_e32 v174, s61, v182
	ds_read_b128 v[130:133], v142
	ds_read_b128 v[134:137], v142 offset:1024
	ds_read_b128 v[138:141], v142 offset:2048
	ds_read_b128 v[142:145], v142 offset:3072
	ds_read_b128 v[146:149], v174
	ds_read_b128 v[150:153], v174 offset:1024
	ds_read_b128 v[170:173], v174 offset:2048
	ds_read_b128 v[174:177], v174 offset:3072
	s_add_u32 s0, s40, 0x80000
	s_addc_u32 s1, s41, 0
	s_mov_b32 m0, s47
	v_lshl_add_u64 v[226:227], s[0:1], 0, v[154:155]
	ds_read_b128 v[178:181], v188 offset:32768
	ds_read_b128 v[190:193], v188 offset:33792
	ds_read_b128 v[194:197], v188 offset:34816
	ds_read_b128 v[198:201], v188 offset:35840
	ds_read_b128 v[202:205], v188 offset:36864
	ds_read_b128 v[206:209], v188 offset:37888
	ds_read_b128 v[210:213], v188 offset:38912
	ds_read_b128 v[214:217], v188 offset:39936
	global_load_lds_dwordx4 v[226:227], off
	v_lshl_add_u64 v[226:227], s[0:1], 0, v[158:159]
	s_mov_b32 m0, s48
	s_nop 0
	global_load_lds_dwordx4 v[226:227], off
	s_waitcnt vmcnt(8)
	s_waitcnt lgkmcnt(0)
	s_barrier
	s_setprio 1
	s_waitcnt lgkmcnt(0)
	v_mfma_f32_16x16x32_bf16 v[126:129], v[130:133], v[178:181], v[126:129]
	v_mfma_f32_16x16x32_bf16 v[126:129], v[134:137], v[190:193], v[126:129]
	v_mfma_f32_16x16x32_bf16 v[122:125], v[138:141], v[178:181], v[122:125]
	v_mfma_f32_16x16x32_bf16 v[122:125], v[142:145], v[190:193], v[122:125]
	v_mfma_f32_16x16x32_bf16 v[110:113], v[130:133], v[194:197], v[110:113]
	v_mfma_f32_16x16x32_bf16 v[110:113], v[134:137], v[198:201], v[110:113]
	v_mfma_f32_16x16x32_bf16 v[106:109], v[138:141], v[194:197], v[106:109]
	v_mfma_f32_16x16x32_bf16 v[106:109], v[142:145], v[198:201], v[106:109]
	v_mfma_f32_16x16x32_bf16 v[94:97], v[130:133], v[202:205], v[94:97]
	v_mfma_f32_16x16x32_bf16 v[94:97], v[134:137], v[206:209], v[94:97]
	v_mfma_f32_16x16x32_bf16 v[90:93], v[138:141], v[202:205], v[90:93]
	v_mfma_f32_16x16x32_bf16 v[90:93], v[142:145], v[206:209], v[90:93]
	v_mfma_f32_16x16x32_bf16 v[78:81], v[130:133], v[210:213], v[78:81]
	v_mfma_f32_16x16x32_bf16 v[78:81], v[134:137], v[214:217], v[78:81]
	v_mfma_f32_16x16x32_bf16 v[74:77], v[138:141], v[210:213], v[74:77]
	v_mfma_f32_16x16x32_bf16 v[74:77], v[142:145], v[214:217], v[74:77]
	s_setprio 0
	s_setprio 1
	v_mfma_f32_16x16x32_bf16 v[118:121], v[146:149], v[178:181], v[118:121]
	v_mfma_f32_16x16x32_bf16 v[118:121], v[150:153], v[190:193], v[118:121]
	v_mfma_f32_16x16x32_bf16 v[114:117], v[170:173], v[178:181], v[114:117]
	v_mfma_f32_16x16x32_bf16 v[114:117], v[174:177], v[190:193], v[114:117]
	v_mfma_f32_16x16x32_bf16 v[102:105], v[146:149], v[194:197], v[102:105]
	v_mfma_f32_16x16x32_bf16 v[102:105], v[150:153], v[198:201], v[102:105]
	v_mfma_f32_16x16x32_bf16 v[98:101], v[170:173], v[194:197], v[98:101]
	v_mfma_f32_16x16x32_bf16 v[98:101], v[174:177], v[198:201], v[98:101]
	v_mfma_f32_16x16x32_bf16 v[86:89], v[146:149], v[202:205], v[86:89]
	v_mfma_f32_16x16x32_bf16 v[86:89], v[150:153], v[206:209], v[86:89]
	v_mfma_f32_16x16x32_bf16 v[82:85], v[170:173], v[202:205], v[82:85]
	v_mfma_f32_16x16x32_bf16 v[82:85], v[174:177], v[206:209], v[82:85]
	v_mfma_f32_16x16x32_bf16 v[70:73], v[146:149], v[210:213], v[70:73]
	v_mfma_f32_16x16x32_bf16 v[70:73], v[150:153], v[214:217], v[70:73]
	v_mfma_f32_16x16x32_bf16 v[66:69], v[170:173], v[210:213], v[66:69]
	v_mfma_f32_16x16x32_bf16 v[66:69], v[174:177], v[214:217], v[66:69]
	s_setprio 0
	s_barrier
	s_add_i32 s0, s60, s45
	v_lshl_add_u64 v[218:219], v[218:219], 0, s[14:15]
	s_mov_b32 m0, s0
	ds_read_b128 v[178:181], v188 offset:49152
	ds_read_b128 v[190:193], v188 offset:50176
	ds_read_b128 v[194:197], v188 offset:51200
	ds_read_b128 v[198:201], v188 offset:52224
	ds_read_b128 v[202:205], v188 offset:53248
	ds_read_b128 v[206:209], v188 offset:54272
	ds_read_b128 v[210:213], v188 offset:55296
	ds_read_b128 v[214:217], v188 offset:56320
	global_load_lds_dwordx4 v[218:219], off
	s_add_i32 m0, s0, 0x2000
	s_add_u32 s0, s2, 0x80080
	v_lshl_add_u64 v[218:219], v[220:221], 0, s[14:15]
	s_addc_u32 s1, s3, 0
	s_add_i32 s2, s61, s45
	global_load_lds_dwordx4 v[218:219], off
	v_lshl_add_u64 v[218:219], s[0:1], 0, v[156:157]
	s_mov_b32 m0, s2
	s_nop 0
	global_load_lds_dwordx4 v[218:219], off
	v_lshl_add_u64 v[218:219], s[0:1], 0, v[160:161]
	s_add_i32 m0, s2, 0x2000
	s_nop 0
	global_load_lds_dwordx4 v[218:219], off
	v_lshl_add_u64 v[218:219], v[222:223], 0, s[14:15]
	s_mov_b32 m0, s50
	s_nop 0
	global_load_lds_dwordx4 v[218:219], off
	v_lshl_add_u64 v[218:219], v[224:225], 0, s[14:15]
	s_mov_b32 m0, s51
	s_nop 0
	global_load_lds_dwordx4 v[218:219], off
	s_waitcnt vmcnt(8)
	s_waitcnt lgkmcnt(0)
	s_barrier
	s_setprio 1
	s_waitcnt lgkmcnt(0)
	v_mfma_f32_16x16x32_bf16 v[62:65], v[130:133], v[178:181], v[62:65]
	v_mfma_f32_16x16x32_bf16 v[62:65], v[134:137], v[190:193], v[62:65]
	v_mfma_f32_16x16x32_bf16 v[58:61], v[138:141], v[178:181], v[58:61]
	v_mfma_f32_16x16x32_bf16 v[58:61], v[142:145], v[190:193], v[58:61]
	v_mfma_f32_16x16x32_bf16 v[46:49], v[130:133], v[194:197], v[46:49]
	v_mfma_f32_16x16x32_bf16 v[46:49], v[134:137], v[198:201], v[46:49]
	v_mfma_f32_16x16x32_bf16 v[42:45], v[138:141], v[194:197], v[42:45]
	v_mfma_f32_16x16x32_bf16 v[42:45], v[142:145], v[198:201], v[42:45]
	v_mfma_f32_16x16x32_bf16 v[30:33], v[130:133], v[202:205], v[30:33]
	v_mfma_f32_16x16x32_bf16 v[30:33], v[134:137], v[206:209], v[30:33]
	v_mfma_f32_16x16x32_bf16 v[26:29], v[138:141], v[202:205], v[26:29]
	v_mfma_f32_16x16x32_bf16 v[26:29], v[142:145], v[206:209], v[26:29]
	v_mfma_f32_16x16x32_bf16 v[14:17], v[130:133], v[210:213], v[14:17]
	v_mfma_f32_16x16x32_bf16 v[14:17], v[134:137], v[214:217], v[14:17]
	v_mfma_f32_16x16x32_bf16 v[10:13], v[138:141], v[210:213], v[10:13]
	v_mfma_f32_16x16x32_bf16 v[10:13], v[142:145], v[214:217], v[10:13]
	s_setprio 0
	s_setprio 1
	v_mfma_f32_16x16x32_bf16 v[54:57], v[146:149], v[178:181], v[54:57]
	s_add_i32 s59, s59, 2
	s_add_u32 s38, s38, 0x100
	s_addc_u32 s39, s39, 0
	s_add_u32 s57, s57, 0x100
	s_addc_u32 s58, s58, 0
	s_cmp_gt_u32 s59, 29
	v_mfma_f32_16x16x32_bf16 v[54:57], v[150:153], v[190:193], v[54:57]
	v_mfma_f32_16x16x32_bf16 v[50:53], v[170:173], v[178:181], v[50:53]
	v_mfma_f32_16x16x32_bf16 v[50:53], v[174:177], v[190:193], v[50:53]
	v_mfma_f32_16x16x32_bf16 v[38:41], v[146:149], v[194:197], v[38:41]
	v_mfma_f32_16x16x32_bf16 v[38:41], v[150:153], v[198:201], v[38:41]
	v_mfma_f32_16x16x32_bf16 v[34:37], v[170:173], v[194:197], v[34:37]
	v_mfma_f32_16x16x32_bf16 v[34:37], v[174:177], v[198:201], v[34:37]
	v_mfma_f32_16x16x32_bf16 v[22:25], v[146:149], v[202:205], v[22:25]
	v_mfma_f32_16x16x32_bf16 v[22:25], v[150:153], v[206:209], v[22:25]
	v_mfma_f32_16x16x32_bf16 v[18:21], v[170:173], v[202:205], v[18:21]
	v_mfma_f32_16x16x32_bf16 v[18:21], v[174:177], v[206:209], v[18:21]
	v_mfma_f32_16x16x32_bf16 v[6:9], v[146:149], v[210:213], v[6:9]
	v_mfma_f32_16x16x32_bf16 v[6:9], v[150:153], v[214:217], v[6:9]
	v_mfma_f32_16x16x32_bf16 v[2:5], v[170:173], v[210:213], v[2:5]
	v_mfma_f32_16x16x32_bf16 v[2:5], v[174:177], v[214:217], v[2:5]
	s_setprio 0
	s_barrier
	s_cbranch_scc0 .LBB0_1626
	s_and_b64 vcc, exec, s[16:17]
	s_cbranch_vccz .LBB0_1629
	s_barrier

.LBB0_1715:
	ds_read_b128 v[148:151], v166
	ds_read_b128 v[152:155], v166 offset:1024
	ds_read_b128 v[156:159], v166 offset:2048
	ds_read_b128 v[160:163], v166 offset:3072
	ds_read_b128 v[170:173], v167
	ds_read_b128 v[174:177], v167 offset:1024
	ds_read_b128 v[178:181], v167 offset:2048
	ds_read_b128 v[182:185], v167 offset:3072
	s_add_u32 s0, s28, 0xfffc0080
	s_addc_u32 s1, s29, -1
	s_cmp_eq_u32 s53, 12
	s_cselect_b32 s31, s21, s1
	s_cselect_b32 s30, s49, s0
	s_cselect_b32 s3, s19, s52
	s_cselect_b32 s2, s50, s51
	v_lshl_add_u64 v[218:219], s[28:29], 0, v[140:141]
	s_add_i32 m0, s27, 0xc000
	ds_read_b128 v[186:189], v168
	ds_read_b128 v[190:193], v168 offset:1024
	ds_read_b128 v[194:197], v168 offset:2048
	ds_read_b128 v[198:201], v168 offset:3072
	ds_read_b128 v[202:205], v168 offset:4096
	ds_read_b128 v[206:209], v168 offset:5120
	ds_read_b128 v[210:213], v168 offset:6144
	ds_read_b128 v[214:217], v168 offset:7168
	global_load_lds_dwordx4 v[218:219], off
	v_lshl_add_u64 v[218:219], s[28:29], 0, v[142:143]
	s_add_i32 m0, s27, 0xe000
	s_nop 0
	global_load_lds_dwordx4 v[218:219], off
	s_waitcnt vmcnt(8)
	s_waitcnt lgkmcnt(0)
	s_barrier
	s_setprio 1
	s_waitcnt lgkmcnt(0)
	v_mfma_f32_16x16x32_bf16 v[126:129], v[148:151], v[186:189], v[126:129]
	v_mfma_f32_16x16x32_bf16 v[126:129], v[152:155], v[190:193], v[126:129]
	v_mfma_f32_16x16x32_bf16 v[118:121], v[156:159], v[186:189], v[118:121]
	v_mfma_f32_16x16x32_bf16 v[118:121], v[160:163], v[190:193], v[118:121]
	v_mfma_f32_16x16x32_bf16 v[110:113], v[148:151], v[194:197], v[110:113]
	v_mfma_f32_16x16x32_bf16 v[110:113], v[152:155], v[198:201], v[110:113]
	v_mfma_f32_16x16x32_bf16 v[102:105], v[156:159], v[194:197], v[102:105]
	v_mfma_f32_16x16x32_bf16 v[102:105], v[160:163], v[198:201], v[102:105]
	v_mfma_f32_16x16x32_bf16 v[94:97], v[148:151], v[202:205], v[94:97]
	v_mfma_f32_16x16x32_bf16 v[94:97], v[152:155], v[206:209], v[94:97]
	v_mfma_f32_16x16x32_bf16 v[86:89], v[156:159], v[202:205], v[86:89]
	v_mfma_f32_16x16x32_bf16 v[86:89], v[160:163], v[206:209], v[86:89]
	v_mfma_f32_16x16x32_bf16 v[78:81], v[148:151], v[210:213], v[78:81]
	v_mfma_f32_16x16x32_bf16 v[78:81], v[152:155], v[214:217], v[78:81]
	v_mfma_f32_16x16x32_bf16 v[70:73], v[156:159], v[210:213], v[70:73]
	v_mfma_f32_16x16x32_bf16 v[70:73], v[160:163], v[214:217], v[70:73]
	s_setprio 0
	s_setprio 1
	v_mfma_f32_16x16x32_bf16 v[122:125], v[170:173], v[186:189], v[122:125]
	v_mfma_f32_16x16x32_bf16 v[122:125], v[174:177], v[190:193], v[122:125]
	v_mfma_f32_16x16x32_bf16 v[114:117], v[178:181], v[186:189], v[114:117]
	v_mfma_f32_16x16x32_bf16 v[114:117], v[182:185], v[190:193], v[114:117]
	v_mfma_f32_16x16x32_bf16 v[106:109], v[170:173], v[194:197], v[106:109]
	v_mfma_f32_16x16x32_bf16 v[106:109], v[174:177], v[198:201], v[106:109]
	v_mfma_f32_16x16x32_bf16 v[98:101], v[178:181], v[194:197], v[98:101]
	v_mfma_f32_16x16x32_bf16 v[98:101], v[182:185], v[198:201], v[98:101]
	v_mfma_f32_16x16x32_bf16 v[90:93], v[170:173], v[202:205], v[90:93]
	v_mfma_f32_16x16x32_bf16 v[90:93], v[174:177], v[206:209], v[90:93]
	v_mfma_f32_16x16x32_bf16 v[82:85], v[178:181], v[202:205], v[82:85]
	v_mfma_f32_16x16x32_bf16 v[82:85], v[182:185], v[206:209], v[82:85]
	v_mfma_f32_16x16x32_bf16 v[74:77], v[170:173], v[210:213], v[74:77]
	v_mfma_f32_16x16x32_bf16 v[74:77], v[174:177], v[214:217], v[74:77]
	v_mfma_f32_16x16x32_bf16 v[66:69], v[178:181], v[210:213], v[66:69]
	v_mfma_f32_16x16x32_bf16 v[66:69], v[182:185], v[214:217], v[66:69]
	s_setprio 0
	s_barrier
	s_add_i32 s0, s44, s35
	v_lshl_add_u64 v[218:219], s[2:3], 0, v[134:135]
	s_mov_b32 m0, s0
	ds_read_b128 v[186:189], v168 offset:16384
	ds_read_b128 v[190:193], v168 offset:17408
	ds_read_b128 v[194:197], v168 offset:18432
	ds_read_b128 v[198:201], v168 offset:19456
	ds_read_b128 v[202:205], v168 offset:20480
	ds_read_b128 v[206:209], v168 offset:21504
	ds_read_b128 v[210:213], v168 offset:22528
	ds_read_b128 v[214:217], v168 offset:23552
	global_load_lds_dwordx4 v[218:219], off
	s_add_i32 m0, s0, 0x2000
	s_add_u32 s0, s2, 0x40000
	v_lshl_add_u64 v[220:221], s[2:3], 0, v[130:131]
	s_addc_u32 s1, s3, 0
	s_add_i32 s54, s45, s35
	global_load_lds_dwordx4 v[220:221], off
	v_lshl_add_u64 v[222:223], s[0:1], 0, v[134:135]
	s_mov_b32 m0, s54
	v_lshl_add_u64 v[224:225], s[30:31], 0, v[132:133]
	global_load_lds_dwordx4 v[222:223], off
	v_lshl_add_u64 v[222:223], s[0:1], 0, v[130:131]
	s_add_i32 m0, s54, 0x2000
	s_nop 0
	global_load_lds_dwordx4 v[222:223], off
	v_lshl_add_u64 v[222:223], s[30:31], 0, v[136:137]
	s_mov_b32 m0, s27
	s_nop 0
	global_load_lds_dwordx4 v[222:223], off
	s_mov_b32 m0, s38
	s_nop 0
	global_load_lds_dwordx4 v[224:225], off
	s_waitcnt vmcnt(8)
	s_waitcnt lgkmcnt(0)
	s_barrier
	s_setprio 1
	s_waitcnt lgkmcnt(0)
	v_mfma_f32_16x16x32_bf16 v[62:65], v[148:151], v[186:189], v[62:65]
	v_mfma_f32_16x16x32_bf16 v[62:65], v[152:155], v[190:193], v[62:65]
	v_mfma_f32_16x16x32_bf16 v[54:57], v[156:159], v[186:189], v[54:57]
	v_mfma_f32_16x16x32_bf16 v[54:57], v[160:163], v[190:193], v[54:57]
	v_mfma_f32_16x16x32_bf16 v[46:49], v[148:151], v[194:197], v[46:49]
	v_mfma_f32_16x16x32_bf16 v[46:49], v[152:155], v[198:201], v[46:49]
	v_mfma_f32_16x16x32_bf16 v[38:41], v[156:159], v[194:197], v[38:41]
	v_mfma_f32_16x16x32_bf16 v[38:41], v[160:163], v[198:201], v[38:41]
	v_mfma_f32_16x16x32_bf16 v[30:33], v[148:151], v[202:205], v[30:33]
	v_mfma_f32_16x16x32_bf16 v[30:33], v[152:155], v[206:209], v[30:33]
	v_mfma_f32_16x16x32_bf16 v[22:25], v[156:159], v[202:205], v[22:25]
	v_mfma_f32_16x16x32_bf16 v[22:25], v[160:163], v[206:209], v[22:25]
	v_mfma_f32_16x16x32_bf16 v[14:17], v[148:151], v[210:213], v[14:17]
	v_mfma_f32_16x16x32_bf16 v[14:17], v[152:155], v[214:217], v[14:17]
	v_mfma_f32_16x16x32_bf16 v[6:9], v[156:159], v[210:213], v[6:9]
	v_mfma_f32_16x16x32_bf16 v[6:9], v[160:163], v[214:217], v[6:9]
	s_setprio 0
	s_setprio 1
	v_mfma_f32_16x16x32_bf16 v[58:61], v[170:173], v[186:189], v[58:61]
	v_mfma_f32_16x16x32_bf16 v[58:61], v[174:177], v[190:193], v[58:61]
	v_mfma_f32_16x16x32_bf16 v[50:53], v[178:181], v[186:189], v[50:53]
	v_mfma_f32_16x16x32_bf16 v[50:53], v[182:185], v[190:193], v[50:53]
	v_mfma_f32_16x16x32_bf16 v[42:45], v[170:173], v[194:197], v[42:45]
	v_mfma_f32_16x16x32_bf16 v[42:45], v[174:177], v[198:201], v[42:45]
	v_mfma_f32_16x16x32_bf16 v[34:37], v[178:181], v[194:197], v[34:37]
	v_mfma_f32_16x16x32_bf16 v[34:37], v[182:185], v[198:201], v[34:37]
	v_mfma_f32_16x16x32_bf16 v[26:29], v[170:173], v[202:205], v[26:29]
	v_mfma_f32_16x16x32_bf16 v[26:29], v[174:177], v[206:209], v[26:29]
	v_mfma_f32_16x16x32_bf16 v[18:21], v[178:181], v[202:205], v[18:21]
	v_mfma_f32_16x16x32_bf16 v[18:21], v[182:185], v[206:209], v[18:21]
	v_mfma_f32_16x16x32_bf16 v[10:13], v[170:173], v[210:213], v[10:13]
	v_mfma_f32_16x16x32_bf16 v[10:13], v[174:177], v[214:217], v[10:13]
	v_mfma_f32_16x16x32_bf16 v[2:5], v[178:181], v[210:213], v[2:5]
	v_mfma_f32_16x16x32_bf16 v[2:5], v[182:185], v[214:217], v[2:5]
	s_setprio 0
	s_barrier
	s_add_i32 s54, 0, 0x18000
	s_add_i32 s55, 0, 0x1c000
	v_add_u32_e32 v160, s54, v165
	v_add_u32_e32 v182, s55, v165
	ds_read_b128 v[148:151], v160
	ds_read_b128 v[152:155], v160 offset:1024
	ds_read_b128 v[156:159], v160 offset:2048
	ds_read_b128 v[160:163], v160 offset:3072
	ds_read_b128 v[170:173], v182
	ds_read_b128 v[174:177], v182 offset:1024
	ds_read_b128 v[178:181], v182 offset:2048
	ds_read_b128 v[182:185], v182 offset:3072
	s_add_u32 s0, s30, 0x40000
	s_addc_u32 s1, s31, 0
	s_mov_b32 m0, s39
	v_lshl_add_u64 v[226:227], s[0:1], 0, v[136:137]
	ds_read_b128 v[186:189], v168 offset:32768
	ds_read_b128 v[190:193], v168 offset:33792
	ds_read_b128 v[194:197], v168 offset:34816
	ds_read_b128 v[198:201], v168 offset:35840
	ds_read_b128 v[202:205], v168 offset:36864
	ds_read_b128 v[206:209], v168 offset:37888
	ds_read_b128 v[210:213], v168 offset:38912
	ds_read_b128 v[214:217], v168 offset:39936
	global_load_lds_dwordx4 v[226:227], off
	v_lshl_add_u64 v[226:227], s[0:1], 0, v[132:133]
	s_mov_b32 m0, s40
	s_nop 0
	global_load_lds_dwordx4 v[226:227], off
	s_waitcnt vmcnt(8)
	s_waitcnt lgkmcnt(0)
	s_barrier
	s_setprio 1
	s_waitcnt lgkmcnt(0)
	v_mfma_f32_16x16x32_bf16 v[126:129], v[148:151], v[186:189], v[126:129]
	v_mfma_f32_16x16x32_bf16 v[126:129], v[152:155], v[190:193], v[126:129]
	v_mfma_f32_16x16x32_bf16 v[118:121], v[156:159], v[186:189], v[118:121]
	v_mfma_f32_16x16x32_bf16 v[118:121], v[160:163], v[190:193], v[118:121]
	v_mfma_f32_16x16x32_bf16 v[110:113], v[148:151], v[194:197], v[110:113]
	v_mfma_f32_16x16x32_bf16 v[110:113], v[152:155], v[198:201], v[110:113]
	v_mfma_f32_16x16x32_bf16 v[102:105], v[156:159], v[194:197], v[102:105]
	v_mfma_f32_16x16x32_bf16 v[102:105], v[160:163], v[198:201], v[102:105]
	v_mfma_f32_16x16x32_bf16 v[94:97], v[148:151], v[202:205], v[94:97]
	v_mfma_f32_16x16x32_bf16 v[94:97], v[152:155], v[206:209], v[94:97]
	v_mfma_f32_16x16x32_bf16 v[86:89], v[156:159], v[202:205], v[86:89]
	v_mfma_f32_16x16x32_bf16 v[86:89], v[160:163], v[206:209], v[86:89]
	v_mfma_f32_16x16x32_bf16 v[78:81], v[148:151], v[210:213], v[78:81]
	v_mfma_f32_16x16x32_bf16 v[78:81], v[152:155], v[214:217], v[78:81]
	v_mfma_f32_16x16x32_bf16 v[70:73], v[156:159], v[210:213], v[70:73]
	v_mfma_f32_16x16x32_bf16 v[70:73], v[160:163], v[214:217], v[70:73]
	s_setprio 0
	s_setprio 1
	v_mfma_f32_16x16x32_bf16 v[122:125], v[170:173], v[186:189], v[122:125]
	v_mfma_f32_16x16x32_bf16 v[122:125], v[174:177], v[190:193], v[122:125]
	v_mfma_f32_16x16x32_bf16 v[114:117], v[178:181], v[186:189], v[114:117]
	v_mfma_f32_16x16x32_bf16 v[114:117], v[182:185], v[190:193], v[114:117]
	v_mfma_f32_16x16x32_bf16 v[106:109], v[170:173], v[194:197], v[106:109]
	v_mfma_f32_16x16x32_bf16 v[106:109], v[174:177], v[198:201], v[106:109]
	v_mfma_f32_16x16x32_bf16 v[98:101], v[178:181], v[194:197], v[98:101]
	v_mfma_f32_16x16x32_bf16 v[98:101], v[182:185], v[198:201], v[98:101]
	v_mfma_f32_16x16x32_bf16 v[90:93], v[170:173], v[202:205], v[90:93]
	v_mfma_f32_16x16x32_bf16 v[90:93], v[174:177], v[206:209], v[90:93]
	v_mfma_f32_16x16x32_bf16 v[82:85], v[178:181], v[202:205], v[82:85]
	v_mfma_f32_16x16x32_bf16 v[82:85], v[182:185], v[206:209], v[82:85]
	v_mfma_f32_16x16x32_bf16 v[74:77], v[170:173], v[210:213], v[74:77]
	v_mfma_f32_16x16x32_bf16 v[74:77], v[174:177], v[214:217], v[74:77]
	v_mfma_f32_16x16x32_bf16 v[66:69], v[178:181], v[210:213], v[66:69]
	v_mfma_f32_16x16x32_bf16 v[66:69], v[182:185], v[214:217], v[66:69]
	s_setprio 0
	s_barrier
	s_add_i32 s0, s54, s35
	v_lshl_add_u64 v[218:219], v[218:219], 0, s[14:15]
	s_mov_b32 m0, s0
	ds_read_b128 v[186:189], v168 offset:49152
	ds_read_b128 v[190:193], v168 offset:50176
	ds_read_b128 v[194:197], v168 offset:51200
	ds_read_b128 v[198:201], v168 offset:52224
	ds_read_b128 v[202:205], v168 offset:53248
	ds_read_b128 v[206:209], v168 offset:54272
	ds_read_b128 v[210:213], v168 offset:55296
	ds_read_b128 v[214:217], v168 offset:56320
	global_load_lds_dwordx4 v[218:219], off
	s_add_i32 m0, s0, 0x2000
	s_add_u32 s0, s2, 0x40080
	v_lshl_add_u64 v[218:219], v[220:221], 0, s[14:15]
	s_addc_u32 s1, s3, 0
	s_add_i32 s2, s55, s35
	global_load_lds_dwordx4 v[218:219], off
	v_lshl_add_u64 v[218:219], s[0:1], 0, v[134:135]
	s_mov_b32 m0, s2
	s_nop 0
	global_load_lds_dwordx4 v[218:219], off
	v_lshl_add_u64 v[218:219], s[0:1], 0, v[130:131]
	s_add_i32 m0, s2, 0x2000
	s_nop 0
	global_load_lds_dwordx4 v[218:219], off
	v_lshl_add_u64 v[218:219], v[222:223], 0, s[14:15]
	s_mov_b32 m0, s41
	s_nop 0
	global_load_lds_dwordx4 v[218:219], off
	v_lshl_add_u64 v[218:219], v[224:225], 0, s[14:15]
	s_mov_b32 m0, s42
	s_nop 0
	global_load_lds_dwordx4 v[218:219], off
	s_waitcnt vmcnt(8)
	s_waitcnt lgkmcnt(0)
	s_barrier
	s_setprio 1
	s_waitcnt lgkmcnt(0)
	v_mfma_f32_16x16x32_bf16 v[62:65], v[148:151], v[186:189], v[62:65]
	v_mfma_f32_16x16x32_bf16 v[62:65], v[152:155], v[190:193], v[62:65]
	v_mfma_f32_16x16x32_bf16 v[54:57], v[156:159], v[186:189], v[54:57]
	v_mfma_f32_16x16x32_bf16 v[54:57], v[160:163], v[190:193], v[54:57]
	v_mfma_f32_16x16x32_bf16 v[46:49], v[148:151], v[194:197], v[46:49]
	v_mfma_f32_16x16x32_bf16 v[46:49], v[152:155], v[198:201], v[46:49]
	v_mfma_f32_16x16x32_bf16 v[38:41], v[156:159], v[194:197], v[38:41]
	v_mfma_f32_16x16x32_bf16 v[38:41], v[160:163], v[198:201], v[38:41]
	v_mfma_f32_16x16x32_bf16 v[30:33], v[148:151], v[202:205], v[30:33]
	v_mfma_f32_16x16x32_bf16 v[30:33], v[152:155], v[206:209], v[30:33]
	v_mfma_f32_16x16x32_bf16 v[22:25], v[156:159], v[202:205], v[22:25]
	v_mfma_f32_16x16x32_bf16 v[22:25], v[160:163], v[206:209], v[22:25]
	v_mfma_f32_16x16x32_bf16 v[14:17], v[148:151], v[210:213], v[14:17]
	v_mfma_f32_16x16x32_bf16 v[14:17], v[152:155], v[214:217], v[14:17]
	v_mfma_f32_16x16x32_bf16 v[6:9], v[156:159], v[210:213], v[6:9]
	v_mfma_f32_16x16x32_bf16 v[6:9], v[160:163], v[214:217], v[6:9]
	s_setprio 0
	s_setprio 1
	v_mfma_f32_16x16x32_bf16 v[58:61], v[170:173], v[186:189], v[58:61]
	s_add_i32 s53, s53, 2
	s_add_u32 s28, s28, 0x100
	s_addc_u32 s29, s29, 0
	s_add_u32 s51, s51, 0x100
	s_addc_u32 s52, s52, 0
	s_cmp_gt_u32 s53, 13
	v_mfma_f32_16x16x32_bf16 v[58:61], v[174:177], v[190:193], v[58:61]
	v_mfma_f32_16x16x32_bf16 v[50:53], v[178:181], v[186:189], v[50:53]
	v_mfma_f32_16x16x32_bf16 v[50:53], v[182:185], v[190:193], v[50:53]
	v_mfma_f32_16x16x32_bf16 v[42:45], v[170:173], v[194:197], v[42:45]
	v_mfma_f32_16x16x32_bf16 v[42:45], v[174:177], v[198:201], v[42:45]
	v_mfma_f32_16x16x32_bf16 v[34:37], v[178:181], v[194:197], v[34:37]
	v_mfma_f32_16x16x32_bf16 v[34:37], v[182:185], v[198:201], v[34:37]
	v_mfma_f32_16x16x32_bf16 v[26:29], v[170:173], v[202:205], v[26:29]
	v_mfma_f32_16x16x32_bf16 v[26:29], v[174:177], v[206:209], v[26:29]
	v_mfma_f32_16x16x32_bf16 v[18:21], v[178:181], v[202:205], v[18:21]
	v_mfma_f32_16x16x32_bf16 v[18:21], v[182:185], v[206:209], v[18:21]
	v_mfma_f32_16x16x32_bf16 v[10:13], v[170:173], v[210:213], v[10:13]
	v_mfma_f32_16x16x32_bf16 v[10:13], v[174:177], v[214:217], v[10:13]
	v_mfma_f32_16x16x32_bf16 v[2:5], v[178:181], v[210:213], v[2:5]
	v_mfma_f32_16x16x32_bf16 v[2:5], v[182:185], v[214:217], v[2:5]
	s_setprio 0
	s_barrier
	s_cbranch_scc0 .LBB0_1715
	s_and_b64 vcc, exec, s[16:17]
	s_cbranch_vccz .LBB0_1718
	s_barrier

.LBB0_1841:
	ds_read_b128 v[130:133], v186
	ds_read_b128 v[134:137], v186 offset:1024
	ds_read_b128 v[138:141], v186 offset:2048
	ds_read_b128 v[142:145], v186 offset:3072
	ds_read_b128 v[146:149], v187
	ds_read_b128 v[150:153], v187 offset:1024
	ds_read_b128 v[170:173], v187 offset:2048
	ds_read_b128 v[174:177], v187 offset:3072
	s_add_u32 s0, s30, 0xfff50080
	s_addc_u32 s1, s31, -1
	s_cmp_eq_u32 s55, 40
	s_cselect_b32 s35, s9, s1
	s_cselect_b32 s34, s8, s0
	s_cselect_b32 s3, s29, s54
	s_cselect_b32 s2, s28, s53
	v_lshl_add_u64 v[218:219], s[30:31], 0, v[162:163]
	s_add_i32 m0, s40, 0xc000
	ds_read_b128 v[178:181], v188
	ds_read_b128 v[190:193], v188 offset:1024
	ds_read_b128 v[194:197], v188 offset:2048
	ds_read_b128 v[198:201], v188 offset:3072
	ds_read_b128 v[202:205], v188 offset:4096
	ds_read_b128 v[206:209], v188 offset:5120
	ds_read_b128 v[210:213], v188 offset:6144
	ds_read_b128 v[214:217], v188 offset:7168
	global_load_lds_dwordx4 v[218:219], off
	v_lshl_add_u64 v[218:219], s[30:31], 0, v[164:165]
	s_add_i32 m0, s40, 0xe000
	s_nop 0
	global_load_lds_dwordx4 v[218:219], off
	s_waitcnt vmcnt(8)
	s_waitcnt lgkmcnt(0)
	s_barrier
	s_setprio 1
	s_waitcnt lgkmcnt(0)
	v_mfma_f32_16x16x32_bf16 v[126:129], v[130:133], v[178:181], v[126:129]
	v_mfma_f32_16x16x32_bf16 v[126:129], v[134:137], v[190:193], v[126:129]
	v_mfma_f32_16x16x32_bf16 v[122:125], v[138:141], v[178:181], v[122:125]
	v_mfma_f32_16x16x32_bf16 v[122:125], v[142:145], v[190:193], v[122:125]
	v_mfma_f32_16x16x32_bf16 v[110:113], v[130:133], v[194:197], v[110:113]
	v_mfma_f32_16x16x32_bf16 v[110:113], v[134:137], v[198:201], v[110:113]
	v_mfma_f32_16x16x32_bf16 v[106:109], v[138:141], v[194:197], v[106:109]
	v_mfma_f32_16x16x32_bf16 v[106:109], v[142:145], v[198:201], v[106:109]
	v_mfma_f32_16x16x32_bf16 v[94:97], v[130:133], v[202:205], v[94:97]
	v_mfma_f32_16x16x32_bf16 v[94:97], v[134:137], v[206:209], v[94:97]
	v_mfma_f32_16x16x32_bf16 v[90:93], v[138:141], v[202:205], v[90:93]
	v_mfma_f32_16x16x32_bf16 v[90:93], v[142:145], v[206:209], v[90:93]
	v_mfma_f32_16x16x32_bf16 v[78:81], v[130:133], v[210:213], v[78:81]
	v_mfma_f32_16x16x32_bf16 v[78:81], v[134:137], v[214:217], v[78:81]
	v_mfma_f32_16x16x32_bf16 v[74:77], v[138:141], v[210:213], v[74:77]
	v_mfma_f32_16x16x32_bf16 v[74:77], v[142:145], v[214:217], v[74:77]
	s_setprio 0
	s_setprio 1
	v_mfma_f32_16x16x32_bf16 v[118:121], v[146:149], v[178:181], v[118:121]
	v_mfma_f32_16x16x32_bf16 v[118:121], v[150:153], v[190:193], v[118:121]
	v_mfma_f32_16x16x32_bf16 v[114:117], v[170:173], v[178:181], v[114:117]
	v_mfma_f32_16x16x32_bf16 v[114:117], v[174:177], v[190:193], v[114:117]
	v_mfma_f32_16x16x32_bf16 v[102:105], v[146:149], v[194:197], v[102:105]
	v_mfma_f32_16x16x32_bf16 v[102:105], v[150:153], v[198:201], v[102:105]
	v_mfma_f32_16x16x32_bf16 v[98:101], v[170:173], v[194:197], v[98:101]
	v_mfma_f32_16x16x32_bf16 v[98:101], v[174:177], v[198:201], v[98:101]
	v_mfma_f32_16x16x32_bf16 v[86:89], v[146:149], v[202:205], v[86:89]
	v_mfma_f32_16x16x32_bf16 v[86:89], v[150:153], v[206:209], v[86:89]
	v_mfma_f32_16x16x32_bf16 v[82:85], v[170:173], v[202:205], v[82:85]
	v_mfma_f32_16x16x32_bf16 v[82:85], v[174:177], v[206:209], v[82:85]
	v_mfma_f32_16x16x32_bf16 v[70:73], v[146:149], v[210:213], v[70:73]
	v_mfma_f32_16x16x32_bf16 v[70:73], v[150:153], v[214:217], v[70:73]
	v_mfma_f32_16x16x32_bf16 v[66:69], v[170:173], v[210:213], v[66:69]
	v_mfma_f32_16x16x32_bf16 v[66:69], v[174:177], v[214:217], v[66:69]
	s_setprio 0
	s_barrier
	s_add_i32 s0, s49, s39
	v_lshl_add_u64 v[218:219], s[2:3], 0, v[156:157]
	s_mov_b32 m0, s0
	ds_read_b128 v[178:181], v188 offset:16384
	ds_read_b128 v[190:193], v188 offset:17408
	ds_read_b128 v[194:197], v188 offset:18432
	ds_read_b128 v[198:201], v188 offset:19456
	ds_read_b128 v[202:205], v188 offset:20480
	ds_read_b128 v[206:209], v188 offset:21504
	ds_read_b128 v[210:213], v188 offset:22528
	ds_read_b128 v[214:217], v188 offset:23552
	global_load_lds_dwordx4 v[218:219], off
	s_add_i32 m0, s0, 0x2000
	s_add_u32 s0, s2, 0xb0000
	v_lshl_add_u64 v[220:221], s[2:3], 0, v[160:161]
	s_addc_u32 s1, s3, 0
	s_add_i32 s56, s50, s39
	global_load_lds_dwordx4 v[220:221], off
	v_lshl_add_u64 v[222:223], s[0:1], 0, v[156:157]
	s_mov_b32 m0, s56
	v_lshl_add_u64 v[224:225], s[34:35], 0, v[158:159]
	global_load_lds_dwordx4 v[222:223], off
	v_lshl_add_u64 v[222:223], s[0:1], 0, v[160:161]
	s_add_i32 m0, s56, 0x2000
	s_nop 0
	global_load_lds_dwordx4 v[222:223], off
	v_lshl_add_u64 v[222:223], s[34:35], 0, v[154:155]
	s_mov_b32 m0, s40
	s_nop 0
	global_load_lds_dwordx4 v[222:223], off
	s_mov_b32 m0, s41
	s_nop 0
	global_load_lds_dwordx4 v[224:225], off
	s_waitcnt vmcnt(8)
	s_waitcnt lgkmcnt(0)
	s_barrier
	s_setprio 1
	s_waitcnt lgkmcnt(0)
	v_mfma_f32_16x16x32_bf16 v[62:65], v[130:133], v[178:181], v[62:65]
	v_mfma_f32_16x16x32_bf16 v[62:65], v[134:137], v[190:193], v[62:65]
	v_mfma_f32_16x16x32_bf16 v[58:61], v[138:141], v[178:181], v[58:61]
	v_mfma_f32_16x16x32_bf16 v[58:61], v[142:145], v[190:193], v[58:61]
	v_mfma_f32_16x16x32_bf16 v[46:49], v[130:133], v[194:197], v[46:49]
	v_mfma_f32_16x16x32_bf16 v[46:49], v[134:137], v[198:201], v[46:49]
	v_mfma_f32_16x16x32_bf16 v[42:45], v[138:141], v[194:197], v[42:45]
	v_mfma_f32_16x16x32_bf16 v[42:45], v[142:145], v[198:201], v[42:45]
	v_mfma_f32_16x16x32_bf16 v[30:33], v[130:133], v[202:205], v[30:33]
	v_mfma_f32_16x16x32_bf16 v[30:33], v[134:137], v[206:209], v[30:33]
	v_mfma_f32_16x16x32_bf16 v[26:29], v[138:141], v[202:205], v[26:29]
	v_mfma_f32_16x16x32_bf16 v[26:29], v[142:145], v[206:209], v[26:29]
	v_mfma_f32_16x16x32_bf16 v[14:17], v[130:133], v[210:213], v[14:17]
	v_mfma_f32_16x16x32_bf16 v[14:17], v[134:137], v[214:217], v[14:17]
	v_mfma_f32_16x16x32_bf16 v[10:13], v[138:141], v[210:213], v[10:13]
	v_mfma_f32_16x16x32_bf16 v[10:13], v[142:145], v[214:217], v[10:13]
	s_setprio 0
	s_setprio 1
	v_mfma_f32_16x16x32_bf16 v[54:57], v[146:149], v[178:181], v[54:57]
	v_mfma_f32_16x16x32_bf16 v[54:57], v[150:153], v[190:193], v[54:57]
	v_mfma_f32_16x16x32_bf16 v[50:53], v[170:173], v[178:181], v[50:53]
	v_mfma_f32_16x16x32_bf16 v[50:53], v[174:177], v[190:193], v[50:53]
	v_mfma_f32_16x16x32_bf16 v[38:41], v[146:149], v[194:197], v[38:41]
	v_mfma_f32_16x16x32_bf16 v[38:41], v[150:153], v[198:201], v[38:41]
	v_mfma_f32_16x16x32_bf16 v[34:37], v[170:173], v[194:197], v[34:37]
	v_mfma_f32_16x16x32_bf16 v[34:37], v[174:177], v[198:201], v[34:37]
	v_mfma_f32_16x16x32_bf16 v[22:25], v[146:149], v[202:205], v[22:25]
	v_mfma_f32_16x16x32_bf16 v[22:25], v[150:153], v[206:209], v[22:25]
	v_mfma_f32_16x16x32_bf16 v[18:21], v[170:173], v[202:205], v[18:21]
	v_mfma_f32_16x16x32_bf16 v[18:21], v[174:177], v[206:209], v[18:21]
	v_mfma_f32_16x16x32_bf16 v[6:9], v[146:149], v[210:213], v[6:9]
	v_mfma_f32_16x16x32_bf16 v[6:9], v[150:153], v[214:217], v[6:9]
	v_mfma_f32_16x16x32_bf16 v[2:5], v[170:173], v[210:213], v[2:5]
	v_mfma_f32_16x16x32_bf16 v[2:5], v[174:177], v[214:217], v[2:5]
	s_setprio 0
	s_barrier
	s_add_i32 s56, 0, 0x18000
	s_add_i32 s57, 0, 0x1c000
	v_add_u32_e32 v142, s56, v182
	v_add_u32_e32 v174, s57, v182
	ds_read_b128 v[130:133], v142
	ds_read_b128 v[134:137], v142 offset:1024
	ds_read_b128 v[138:141], v142 offset:2048
	ds_read_b128 v[142:145], v142 offset:3072
	ds_read_b128 v[146:149], v174
	ds_read_b128 v[150:153], v174 offset:1024
	ds_read_b128 v[170:173], v174 offset:2048
	ds_read_b128 v[174:177], v174 offset:3072
	s_add_u32 s0, s34, 0xb0000
	s_addc_u32 s1, s35, 0
	s_mov_b32 m0, s42
	v_lshl_add_u64 v[226:227], s[0:1], 0, v[154:155]
	ds_read_b128 v[178:181], v188 offset:32768
	ds_read_b128 v[190:193], v188 offset:33792
	ds_read_b128 v[194:197], v188 offset:34816
	ds_read_b128 v[198:201], v188 offset:35840
	ds_read_b128 v[202:205], v188 offset:36864
	ds_read_b128 v[206:209], v188 offset:37888
	ds_read_b128 v[210:213], v188 offset:38912
	ds_read_b128 v[214:217], v188 offset:39936
	global_load_lds_dwordx4 v[226:227], off
	v_lshl_add_u64 v[226:227], s[0:1], 0, v[158:159]
	s_mov_b32 m0, s43
	s_nop 0
	global_load_lds_dwordx4 v[226:227], off
	s_waitcnt vmcnt(8)
	s_waitcnt lgkmcnt(0)
	s_barrier
	s_setprio 1
	s_waitcnt lgkmcnt(0)
	v_mfma_f32_16x16x32_bf16 v[126:129], v[130:133], v[178:181], v[126:129]
	v_mfma_f32_16x16x32_bf16 v[126:129], v[134:137], v[190:193], v[126:129]
	v_mfma_f32_16x16x32_bf16 v[122:125], v[138:141], v[178:181], v[122:125]
	v_mfma_f32_16x16x32_bf16 v[122:125], v[142:145], v[190:193], v[122:125]
	v_mfma_f32_16x16x32_bf16 v[110:113], v[130:133], v[194:197], v[110:113]
	v_mfma_f32_16x16x32_bf16 v[110:113], v[134:137], v[198:201], v[110:113]
	v_mfma_f32_16x16x32_bf16 v[106:109], v[138:141], v[194:197], v[106:109]
	v_mfma_f32_16x16x32_bf16 v[106:109], v[142:145], v[198:201], v[106:109]
	v_mfma_f32_16x16x32_bf16 v[94:97], v[130:133], v[202:205], v[94:97]
	v_mfma_f32_16x16x32_bf16 v[94:97], v[134:137], v[206:209], v[94:97]
	v_mfma_f32_16x16x32_bf16 v[90:93], v[138:141], v[202:205], v[90:93]
	v_mfma_f32_16x16x32_bf16 v[90:93], v[142:145], v[206:209], v[90:93]
	v_mfma_f32_16x16x32_bf16 v[78:81], v[130:133], v[210:213], v[78:81]
	v_mfma_f32_16x16x32_bf16 v[78:81], v[134:137], v[214:217], v[78:81]
	v_mfma_f32_16x16x32_bf16 v[74:77], v[138:141], v[210:213], v[74:77]
	v_mfma_f32_16x16x32_bf16 v[74:77], v[142:145], v[214:217], v[74:77]
	s_setprio 0
	s_setprio 1
	v_mfma_f32_16x16x32_bf16 v[118:121], v[146:149], v[178:181], v[118:121]
	v_mfma_f32_16x16x32_bf16 v[118:121], v[150:153], v[190:193], v[118:121]
	v_mfma_f32_16x16x32_bf16 v[114:117], v[170:173], v[178:181], v[114:117]
	v_mfma_f32_16x16x32_bf16 v[114:117], v[174:177], v[190:193], v[114:117]
	v_mfma_f32_16x16x32_bf16 v[102:105], v[146:149], v[194:197], v[102:105]
	v_mfma_f32_16x16x32_bf16 v[102:105], v[150:153], v[198:201], v[102:105]
	v_mfma_f32_16x16x32_bf16 v[98:101], v[170:173], v[194:197], v[98:101]
	v_mfma_f32_16x16x32_bf16 v[98:101], v[174:177], v[198:201], v[98:101]
	v_mfma_f32_16x16x32_bf16 v[86:89], v[146:149], v[202:205], v[86:89]
	v_mfma_f32_16x16x32_bf16 v[86:89], v[150:153], v[206:209], v[86:89]
	v_mfma_f32_16x16x32_bf16 v[82:85], v[170:173], v[202:205], v[82:85]
	v_mfma_f32_16x16x32_bf16 v[82:85], v[174:177], v[206:209], v[82:85]
	v_mfma_f32_16x16x32_bf16 v[70:73], v[146:149], v[210:213], v[70:73]
	v_mfma_f32_16x16x32_bf16 v[70:73], v[150:153], v[214:217], v[70:73]
	v_mfma_f32_16x16x32_bf16 v[66:69], v[170:173], v[210:213], v[66:69]
	v_mfma_f32_16x16x32_bf16 v[66:69], v[174:177], v[214:217], v[66:69]
	s_setprio 0
	s_barrier
	s_add_i32 s0, s56, s39
	v_lshl_add_u64 v[218:219], v[218:219], 0, s[16:17]
	s_mov_b32 m0, s0
	ds_read_b128 v[178:181], v188 offset:49152
	ds_read_b128 v[190:193], v188 offset:50176
	ds_read_b128 v[194:197], v188 offset:51200
	ds_read_b128 v[198:201], v188 offset:52224
	ds_read_b128 v[202:205], v188 offset:53248
	ds_read_b128 v[206:209], v188 offset:54272
	ds_read_b128 v[210:213], v188 offset:55296
	ds_read_b128 v[214:217], v188 offset:56320
	global_load_lds_dwordx4 v[218:219], off
	s_add_i32 m0, s0, 0x2000
	s_add_u32 s0, s2, 0xb0080
	v_lshl_add_u64 v[218:219], v[220:221], 0, s[16:17]
	s_addc_u32 s1, s3, 0
	s_add_i32 s2, s57, s39
	global_load_lds_dwordx4 v[218:219], off
	v_lshl_add_u64 v[218:219], s[0:1], 0, v[156:157]
	s_mov_b32 m0, s2
	s_nop 0
	global_load_lds_dwordx4 v[218:219], off
	v_lshl_add_u64 v[218:219], s[0:1], 0, v[160:161]
	s_add_i32 m0, s2, 0x2000
	s_nop 0
	global_load_lds_dwordx4 v[218:219], off
	v_lshl_add_u64 v[218:219], v[222:223], 0, s[16:17]
	s_mov_b32 m0, s45
	s_nop 0
	global_load_lds_dwordx4 v[218:219], off
	v_lshl_add_u64 v[218:219], v[224:225], 0, s[16:17]
	s_mov_b32 m0, s46
	s_nop 0
	global_load_lds_dwordx4 v[218:219], off
	s_waitcnt vmcnt(8)
	s_waitcnt lgkmcnt(0)
	s_barrier
	s_setprio 1
	s_waitcnt lgkmcnt(0)
	v_mfma_f32_16x16x32_bf16 v[62:65], v[130:133], v[178:181], v[62:65]
	v_mfma_f32_16x16x32_bf16 v[62:65], v[134:137], v[190:193], v[62:65]
	v_mfma_f32_16x16x32_bf16 v[58:61], v[138:141], v[178:181], v[58:61]
	v_mfma_f32_16x16x32_bf16 v[58:61], v[142:145], v[190:193], v[58:61]
	v_mfma_f32_16x16x32_bf16 v[46:49], v[130:133], v[194:197], v[46:49]
	v_mfma_f32_16x16x32_bf16 v[46:49], v[134:137], v[198:201], v[46:49]
	v_mfma_f32_16x16x32_bf16 v[42:45], v[138:141], v[194:197], v[42:45]
	v_mfma_f32_16x16x32_bf16 v[42:45], v[142:145], v[198:201], v[42:45]
	v_mfma_f32_16x16x32_bf16 v[30:33], v[130:133], v[202:205], v[30:33]
	v_mfma_f32_16x16x32_bf16 v[30:33], v[134:137], v[206:209], v[30:33]
	v_mfma_f32_16x16x32_bf16 v[26:29], v[138:141], v[202:205], v[26:29]
	v_mfma_f32_16x16x32_bf16 v[26:29], v[142:145], v[206:209], v[26:29]
	v_mfma_f32_16x16x32_bf16 v[14:17], v[130:133], v[210:213], v[14:17]
	v_mfma_f32_16x16x32_bf16 v[14:17], v[134:137], v[214:217], v[14:17]
	v_mfma_f32_16x16x32_bf16 v[10:13], v[138:141], v[210:213], v[10:13]
	v_mfma_f32_16x16x32_bf16 v[10:13], v[142:145], v[214:217], v[10:13]
	s_setprio 0
	s_setprio 1
	v_mfma_f32_16x16x32_bf16 v[54:57], v[146:149], v[178:181], v[54:57]
	s_add_i32 s55, s55, 2
	s_add_u32 s30, s30, 0x100
	s_addc_u32 s31, s31, 0
	s_add_u32 s53, s53, 0x100
	s_addc_u32 s54, s54, 0
	s_cmp_gt_u32 s55, 41
	v_mfma_f32_16x16x32_bf16 v[54:57], v[150:153], v[190:193], v[54:57]
	v_mfma_f32_16x16x32_bf16 v[50:53], v[170:173], v[178:181], v[50:53]
	v_mfma_f32_16x16x32_bf16 v[50:53], v[174:177], v[190:193], v[50:53]
	v_mfma_f32_16x16x32_bf16 v[38:41], v[146:149], v[194:197], v[38:41]
	v_mfma_f32_16x16x32_bf16 v[38:41], v[150:153], v[198:201], v[38:41]
	v_mfma_f32_16x16x32_bf16 v[34:37], v[170:173], v[194:197], v[34:37]
	v_mfma_f32_16x16x32_bf16 v[34:37], v[174:177], v[198:201], v[34:37]
	v_mfma_f32_16x16x32_bf16 v[22:25], v[146:149], v[202:205], v[22:25]
	v_mfma_f32_16x16x32_bf16 v[22:25], v[150:153], v[206:209], v[22:25]
	v_mfma_f32_16x16x32_bf16 v[18:21], v[170:173], v[202:205], v[18:21]
	v_mfma_f32_16x16x32_bf16 v[18:21], v[174:177], v[206:209], v[18:21]
	v_mfma_f32_16x16x32_bf16 v[6:9], v[146:149], v[210:213], v[6:9]
	v_mfma_f32_16x16x32_bf16 v[6:9], v[150:153], v[214:217], v[6:9]
	v_mfma_f32_16x16x32_bf16 v[2:5], v[170:173], v[210:213], v[2:5]
	v_mfma_f32_16x16x32_bf16 v[2:5], v[174:177], v[214:217], v[2:5]
	s_setprio 0
	s_barrier
	s_cbranch_scc0 .LBB0_1841
	s_and_b64 vcc, exec, s[18:19]
	s_cbranch_vccz .LBB0_1844
	s_barrier

.LBB0_1938:
	ds_read_b128 v[148:151], v161
	ds_read_b128 v[152:155], v161 offset:1024
	ds_read_b128 v[156:159], v161 offset:2048
	ds_read_b128 v[166:169], v161 offset:3072
	ds_read_b128 v[170:173], v162
	ds_read_b128 v[174:177], v162 offset:1024
	ds_read_b128 v[178:181], v162 offset:2048
	ds_read_b128 v[182:185], v162 offset:3072
	s_add_u32 s0, s28, 0xfffc0080
	s_addc_u32 s1, s29, -1
	s_cmp_eq_u32 s51, 12
	s_cselect_b32 s31, s21, s1
	s_cselect_b32 s30, s47, s0
	s_cselect_b32 s3, s19, s50
	s_cselect_b32 s2, s48, s49
	v_lshl_add_u64 v[218:219], s[28:29], 0, v[140:141]
	s_add_i32 m0, s27, 0xc000
	ds_read_b128 v[186:189], v163
	ds_read_b128 v[190:193], v163 offset:1024
	ds_read_b128 v[194:197], v163 offset:2048
	ds_read_b128 v[198:201], v163 offset:3072
	ds_read_b128 v[202:205], v163 offset:4096
	ds_read_b128 v[206:209], v163 offset:5120
	ds_read_b128 v[210:213], v163 offset:6144
	ds_read_b128 v[214:217], v163 offset:7168
	global_load_lds_dwordx4 v[218:219], off
	v_lshl_add_u64 v[218:219], s[28:29], 0, v[142:143]
	s_add_i32 m0, s27, 0xe000
	s_nop 0
	global_load_lds_dwordx4 v[218:219], off
	s_waitcnt vmcnt(8)
	s_waitcnt lgkmcnt(0)
	s_barrier
	s_setprio 1
	s_waitcnt lgkmcnt(0)
	v_mfma_f32_16x16x32_bf16 v[126:129], v[148:151], v[186:189], v[126:129]
	v_mfma_f32_16x16x32_bf16 v[126:129], v[152:155], v[190:193], v[126:129]
	v_mfma_f32_16x16x32_bf16 v[118:121], v[156:159], v[186:189], v[118:121]
	v_mfma_f32_16x16x32_bf16 v[118:121], v[166:169], v[190:193], v[118:121]
	v_mfma_f32_16x16x32_bf16 v[110:113], v[148:151], v[194:197], v[110:113]
	v_mfma_f32_16x16x32_bf16 v[110:113], v[152:155], v[198:201], v[110:113]
	v_mfma_f32_16x16x32_bf16 v[106:109], v[156:159], v[194:197], v[106:109]
	v_mfma_f32_16x16x32_bf16 v[106:109], v[166:169], v[198:201], v[106:109]
	v_mfma_f32_16x16x32_bf16 v[94:97], v[148:151], v[202:205], v[94:97]
	v_mfma_f32_16x16x32_bf16 v[94:97], v[152:155], v[206:209], v[94:97]
	v_mfma_f32_16x16x32_bf16 v[90:93], v[156:159], v[202:205], v[90:93]
	v_mfma_f32_16x16x32_bf16 v[90:93], v[166:169], v[206:209], v[90:93]
	v_mfma_f32_16x16x32_bf16 v[78:81], v[148:151], v[210:213], v[78:81]
	v_mfma_f32_16x16x32_bf16 v[78:81], v[152:155], v[214:217], v[78:81]
	v_mfma_f32_16x16x32_bf16 v[74:77], v[156:159], v[210:213], v[74:77]
	v_mfma_f32_16x16x32_bf16 v[74:77], v[166:169], v[214:217], v[74:77]
	s_setprio 0
	s_setprio 1
	v_mfma_f32_16x16x32_bf16 v[122:125], v[170:173], v[186:189], v[122:125]
	v_mfma_f32_16x16x32_bf16 v[122:125], v[174:177], v[190:193], v[122:125]
	v_mfma_f32_16x16x32_bf16 v[114:117], v[178:181], v[186:189], v[114:117]
	v_mfma_f32_16x16x32_bf16 v[114:117], v[182:185], v[190:193], v[114:117]
	v_mfma_f32_16x16x32_bf16 v[102:105], v[170:173], v[194:197], v[102:105]
	v_mfma_f32_16x16x32_bf16 v[102:105], v[174:177], v[198:201], v[102:105]
	v_mfma_f32_16x16x32_bf16 v[98:101], v[178:181], v[194:197], v[98:101]
	v_mfma_f32_16x16x32_bf16 v[98:101], v[182:185], v[198:201], v[98:101]
	v_mfma_f32_16x16x32_bf16 v[86:89], v[170:173], v[202:205], v[86:89]
	v_mfma_f32_16x16x32_bf16 v[86:89], v[174:177], v[206:209], v[86:89]
	v_mfma_f32_16x16x32_bf16 v[82:85], v[178:181], v[202:205], v[82:85]
	v_mfma_f32_16x16x32_bf16 v[82:85], v[182:185], v[206:209], v[82:85]
	v_mfma_f32_16x16x32_bf16 v[70:73], v[170:173], v[210:213], v[70:73]
	v_mfma_f32_16x16x32_bf16 v[70:73], v[174:177], v[214:217], v[70:73]
	v_mfma_f32_16x16x32_bf16 v[66:69], v[178:181], v[210:213], v[66:69]
	v_mfma_f32_16x16x32_bf16 v[66:69], v[182:185], v[214:217], v[66:69]
	s_setprio 0
	s_barrier
	s_add_i32 s0, s43, s36
	v_lshl_add_u64 v[218:219], s[2:3], 0, v[132:133]
	s_mov_b32 m0, s0
	ds_read_b128 v[186:189], v163 offset:16384
	ds_read_b128 v[190:193], v163 offset:17408
	ds_read_b128 v[194:197], v163 offset:18432
	ds_read_b128 v[198:201], v163 offset:19456
	ds_read_b128 v[202:205], v163 offset:20480
	ds_read_b128 v[206:209], v163 offset:21504
	ds_read_b128 v[210:213], v163 offset:22528
	ds_read_b128 v[214:217], v163 offset:23552
	global_load_lds_dwordx4 v[218:219], off
	s_add_i32 m0, s0, 0x2000
	s_add_u32 s0, s2, 0x40000
	v_lshl_add_u64 v[220:221], s[2:3], 0, v[136:137]
	s_addc_u32 s1, s3, 0
	s_add_i32 s52, s44, s36
	global_load_lds_dwordx4 v[220:221], off
	v_lshl_add_u64 v[222:223], s[0:1], 0, v[132:133]
	s_mov_b32 m0, s52
	v_lshl_add_u64 v[224:225], s[30:31], 0, v[134:135]
	global_load_lds_dwordx4 v[222:223], off
	v_lshl_add_u64 v[222:223], s[0:1], 0, v[136:137]
	s_add_i32 m0, s52, 0x2000
	s_nop 0
	global_load_lds_dwordx4 v[222:223], off
	v_lshl_add_u64 v[222:223], s[30:31], 0, v[130:131]
	s_mov_b32 m0, s27
	s_nop 0
	global_load_lds_dwordx4 v[222:223], off
	s_mov_b32 m0, s37
	s_nop 0
	global_load_lds_dwordx4 v[224:225], off
	s_waitcnt vmcnt(8)
	s_waitcnt lgkmcnt(0)
	s_barrier
	s_setprio 1
	s_waitcnt lgkmcnt(0)
	v_mfma_f32_16x16x32_bf16 v[62:65], v[148:151], v[186:189], v[62:65]
	v_mfma_f32_16x16x32_bf16 v[62:65], v[152:155], v[190:193], v[62:65]
	v_mfma_f32_16x16x32_bf16 v[58:61], v[156:159], v[186:189], v[58:61]
	v_mfma_f32_16x16x32_bf16 v[58:61], v[166:169], v[190:193], v[58:61]
	v_mfma_f32_16x16x32_bf16 v[46:49], v[148:151], v[194:197], v[46:49]
	v_mfma_f32_16x16x32_bf16 v[46:49], v[152:155], v[198:201], v[46:49]
	v_mfma_f32_16x16x32_bf16 v[42:45], v[156:159], v[194:197], v[42:45]
	v_mfma_f32_16x16x32_bf16 v[42:45], v[166:169], v[198:201], v[42:45]
	v_mfma_f32_16x16x32_bf16 v[30:33], v[148:151], v[202:205], v[30:33]
	v_mfma_f32_16x16x32_bf16 v[30:33], v[152:155], v[206:209], v[30:33]
	v_mfma_f32_16x16x32_bf16 v[26:29], v[156:159], v[202:205], v[26:29]
	v_mfma_f32_16x16x32_bf16 v[26:29], v[166:169], v[206:209], v[26:29]
	v_mfma_f32_16x16x32_bf16 v[14:17], v[148:151], v[210:213], v[14:17]
	v_mfma_f32_16x16x32_bf16 v[14:17], v[152:155], v[214:217], v[14:17]
	v_mfma_f32_16x16x32_bf16 v[10:13], v[156:159], v[210:213], v[10:13]
	v_mfma_f32_16x16x32_bf16 v[10:13], v[166:169], v[214:217], v[10:13]
	s_setprio 0
	s_setprio 1
	v_mfma_f32_16x16x32_bf16 v[54:57], v[170:173], v[186:189], v[54:57]
	v_mfma_f32_16x16x32_bf16 v[54:57], v[174:177], v[190:193], v[54:57]
	v_mfma_f32_16x16x32_bf16 v[50:53], v[178:181], v[186:189], v[50:53]
	v_mfma_f32_16x16x32_bf16 v[50:53], v[182:185], v[190:193], v[50:53]
	v_mfma_f32_16x16x32_bf16 v[38:41], v[170:173], v[194:197], v[38:41]
	v_mfma_f32_16x16x32_bf16 v[38:41], v[174:177], v[198:201], v[38:41]
	v_mfma_f32_16x16x32_bf16 v[34:37], v[178:181], v[194:197], v[34:37]
	v_mfma_f32_16x16x32_bf16 v[34:37], v[182:185], v[198:201], v[34:37]
	v_mfma_f32_16x16x32_bf16 v[22:25], v[170:173], v[202:205], v[22:25]
	v_mfma_f32_16x16x32_bf16 v[22:25], v[174:177], v[206:209], v[22:25]
	v_mfma_f32_16x16x32_bf16 v[18:21], v[178:181], v[202:205], v[18:21]
	v_mfma_f32_16x16x32_bf16 v[18:21], v[182:185], v[206:209], v[18:21]
	v_mfma_f32_16x16x32_bf16 v[6:9], v[170:173], v[210:213], v[6:9]
	v_mfma_f32_16x16x32_bf16 v[6:9], v[174:177], v[214:217], v[6:9]
	v_mfma_f32_16x16x32_bf16 v[2:5], v[178:181], v[210:213], v[2:5]
	v_mfma_f32_16x16x32_bf16 v[2:5], v[182:185], v[214:217], v[2:5]
	s_setprio 0
	s_barrier
	s_add_i32 s52, 0, 0x18000
	v_add_u32_e32 v165, s52, v160
	s_add_i32 s53, 0, 0x1c000
	ds_read_b128 v[148:151], v165
	ds_read_b128 v[152:155], v165 offset:1024
	ds_read_b128 v[156:159], v165 offset:2048
	ds_read_b128 v[166:169], v165 offset:3072
	v_add_u32_e32 v165, s53, v160
	ds_read_b128 v[170:173], v165
	ds_read_b128 v[174:177], v165 offset:1024
	ds_read_b128 v[178:181], v165 offset:2048
	ds_read_b128 v[182:185], v165 offset:3072
	s_add_u32 s0, s30, 0x40000
	s_addc_u32 s1, s31, 0
	s_mov_b32 m0, s38
	v_lshl_add_u64 v[226:227], s[0:1], 0, v[130:131]
	ds_read_b128 v[186:189], v163 offset:32768
	ds_read_b128 v[190:193], v163 offset:33792
	ds_read_b128 v[194:197], v163 offset:34816
	ds_read_b128 v[198:201], v163 offset:35840
	ds_read_b128 v[202:205], v163 offset:36864
	ds_read_b128 v[206:209], v163 offset:37888
	ds_read_b128 v[210:213], v163 offset:38912
	ds_read_b128 v[214:217], v163 offset:39936
	global_load_lds_dwordx4 v[226:227], off
	v_lshl_add_u64 v[226:227], s[0:1], 0, v[134:135]
	s_mov_b32 m0, s39
	s_nop 0
	global_load_lds_dwordx4 v[226:227], off
	s_waitcnt vmcnt(8)
	s_waitcnt lgkmcnt(0)
	s_barrier
	s_setprio 1
	s_waitcnt lgkmcnt(0)
	v_mfma_f32_16x16x32_bf16 v[126:129], v[148:151], v[186:189], v[126:129]
	v_mfma_f32_16x16x32_bf16 v[126:129], v[152:155], v[190:193], v[126:129]
	v_mfma_f32_16x16x32_bf16 v[118:121], v[156:159], v[186:189], v[118:121]
	v_mfma_f32_16x16x32_bf16 v[118:121], v[166:169], v[190:193], v[118:121]
	v_mfma_f32_16x16x32_bf16 v[110:113], v[148:151], v[194:197], v[110:113]
	v_mfma_f32_16x16x32_bf16 v[110:113], v[152:155], v[198:201], v[110:113]
	v_mfma_f32_16x16x32_bf16 v[106:109], v[156:159], v[194:197], v[106:109]
	v_mfma_f32_16x16x32_bf16 v[106:109], v[166:169], v[198:201], v[106:109]
	v_mfma_f32_16x16x32_bf16 v[94:97], v[148:151], v[202:205], v[94:97]
	v_mfma_f32_16x16x32_bf16 v[94:97], v[152:155], v[206:209], v[94:97]
	v_mfma_f32_16x16x32_bf16 v[90:93], v[156:159], v[202:205], v[90:93]
	v_mfma_f32_16x16x32_bf16 v[90:93], v[166:169], v[206:209], v[90:93]
	v_mfma_f32_16x16x32_bf16 v[78:81], v[148:151], v[210:213], v[78:81]
	v_mfma_f32_16x16x32_bf16 v[78:81], v[152:155], v[214:217], v[78:81]
	v_mfma_f32_16x16x32_bf16 v[74:77], v[156:159], v[210:213], v[74:77]
	v_mfma_f32_16x16x32_bf16 v[74:77], v[166:169], v[214:217], v[74:77]
	s_setprio 0
	s_setprio 1
	v_mfma_f32_16x16x32_bf16 v[122:125], v[170:173], v[186:189], v[122:125]
	v_mfma_f32_16x16x32_bf16 v[122:125], v[174:177], v[190:193], v[122:125]
	v_mfma_f32_16x16x32_bf16 v[114:117], v[178:181], v[186:189], v[114:117]
	v_mfma_f32_16x16x32_bf16 v[114:117], v[182:185], v[190:193], v[114:117]
	v_mfma_f32_16x16x32_bf16 v[102:105], v[170:173], v[194:197], v[102:105]
	v_mfma_f32_16x16x32_bf16 v[102:105], v[174:177], v[198:201], v[102:105]
	v_mfma_f32_16x16x32_bf16 v[98:101], v[178:181], v[194:197], v[98:101]
	v_mfma_f32_16x16x32_bf16 v[98:101], v[182:185], v[198:201], v[98:101]
	v_mfma_f32_16x16x32_bf16 v[86:89], v[170:173], v[202:205], v[86:89]
	v_mfma_f32_16x16x32_bf16 v[86:89], v[174:177], v[206:209], v[86:89]
	v_mfma_f32_16x16x32_bf16 v[82:85], v[178:181], v[202:205], v[82:85]
	v_mfma_f32_16x16x32_bf16 v[82:85], v[182:185], v[206:209], v[82:85]
	v_mfma_f32_16x16x32_bf16 v[70:73], v[170:173], v[210:213], v[70:73]
	v_mfma_f32_16x16x32_bf16 v[70:73], v[174:177], v[214:217], v[70:73]
	v_mfma_f32_16x16x32_bf16 v[66:69], v[178:181], v[210:213], v[66:69]
	v_mfma_f32_16x16x32_bf16 v[66:69], v[182:185], v[214:217], v[66:69]
	s_setprio 0
	s_barrier
	s_add_i32 s0, s52, s36
	v_lshl_add_u64 v[218:219], v[218:219], 0, s[14:15]
	s_mov_b32 m0, s0
	ds_read_b128 v[186:189], v163 offset:49152
	ds_read_b128 v[190:193], v163 offset:50176
	ds_read_b128 v[194:197], v163 offset:51200
	ds_read_b128 v[198:201], v163 offset:52224
	ds_read_b128 v[202:205], v163 offset:53248
	ds_read_b128 v[206:209], v163 offset:54272
	ds_read_b128 v[210:213], v163 offset:55296
	ds_read_b128 v[214:217], v163 offset:56320
	global_load_lds_dwordx4 v[218:219], off
	s_add_i32 m0, s0, 0x2000
	s_add_u32 s0, s2, 0x40080
	v_lshl_add_u64 v[218:219], v[220:221], 0, s[14:15]
	s_addc_u32 s1, s3, 0
	s_add_i32 s2, s53, s36
	global_load_lds_dwordx4 v[218:219], off
	v_lshl_add_u64 v[218:219], s[0:1], 0, v[132:133]
	s_mov_b32 m0, s2
	s_nop 0
	global_load_lds_dwordx4 v[218:219], off
	v_lshl_add_u64 v[218:219], s[0:1], 0, v[136:137]
	s_add_i32 m0, s2, 0x2000
	s_nop 0
	global_load_lds_dwordx4 v[218:219], off
	v_lshl_add_u64 v[218:219], v[222:223], 0, s[14:15]
	s_mov_b32 m0, s40
	s_nop 0
	global_load_lds_dwordx4 v[218:219], off
	v_lshl_add_u64 v[218:219], v[224:225], 0, s[14:15]
	s_mov_b32 m0, s41
	s_nop 0
	global_load_lds_dwordx4 v[218:219], off
	s_waitcnt vmcnt(8)
	s_waitcnt lgkmcnt(0)
	s_barrier
	s_setprio 1
	s_waitcnt lgkmcnt(0)
	v_mfma_f32_16x16x32_bf16 v[62:65], v[148:151], v[186:189], v[62:65]
	v_mfma_f32_16x16x32_bf16 v[62:65], v[152:155], v[190:193], v[62:65]
	v_mfma_f32_16x16x32_bf16 v[58:61], v[156:159], v[186:189], v[58:61]
	v_mfma_f32_16x16x32_bf16 v[58:61], v[166:169], v[190:193], v[58:61]
	v_mfma_f32_16x16x32_bf16 v[46:49], v[148:151], v[194:197], v[46:49]
	v_mfma_f32_16x16x32_bf16 v[46:49], v[152:155], v[198:201], v[46:49]
	v_mfma_f32_16x16x32_bf16 v[42:45], v[156:159], v[194:197], v[42:45]
	v_mfma_f32_16x16x32_bf16 v[42:45], v[166:169], v[198:201], v[42:45]
	v_mfma_f32_16x16x32_bf16 v[30:33], v[148:151], v[202:205], v[30:33]
	v_mfma_f32_16x16x32_bf16 v[30:33], v[152:155], v[206:209], v[30:33]
	v_mfma_f32_16x16x32_bf16 v[26:29], v[156:159], v[202:205], v[26:29]
	v_mfma_f32_16x16x32_bf16 v[26:29], v[166:169], v[206:209], v[26:29]
	v_mfma_f32_16x16x32_bf16 v[14:17], v[148:151], v[210:213], v[14:17]
	v_mfma_f32_16x16x32_bf16 v[14:17], v[152:155], v[214:217], v[14:17]
	v_mfma_f32_16x16x32_bf16 v[10:13], v[156:159], v[210:213], v[10:13]
	v_mfma_f32_16x16x32_bf16 v[10:13], v[166:169], v[214:217], v[10:13]
	s_setprio 0
	s_setprio 1
	v_mfma_f32_16x16x32_bf16 v[54:57], v[170:173], v[186:189], v[54:57]
	s_add_i32 s51, s51, 2
	s_add_u32 s28, s28, 0x100
	s_addc_u32 s29, s29, 0
	s_add_u32 s49, s49, 0x100
	s_addc_u32 s50, s50, 0
	s_cmp_gt_u32 s51, 13
	v_mfma_f32_16x16x32_bf16 v[54:57], v[174:177], v[190:193], v[54:57]
	v_mfma_f32_16x16x32_bf16 v[50:53], v[178:181], v[186:189], v[50:53]
	v_mfma_f32_16x16x32_bf16 v[50:53], v[182:185], v[190:193], v[50:53]
	v_mfma_f32_16x16x32_bf16 v[38:41], v[170:173], v[194:197], v[38:41]
	v_mfma_f32_16x16x32_bf16 v[38:41], v[174:177], v[198:201], v[38:41]
	v_mfma_f32_16x16x32_bf16 v[34:37], v[178:181], v[194:197], v[34:37]
	v_mfma_f32_16x16x32_bf16 v[34:37], v[182:185], v[198:201], v[34:37]
	v_mfma_f32_16x16x32_bf16 v[22:25], v[170:173], v[202:205], v[22:25]
	v_mfma_f32_16x16x32_bf16 v[22:25], v[174:177], v[206:209], v[22:25]
	v_mfma_f32_16x16x32_bf16 v[18:21], v[178:181], v[202:205], v[18:21]
	v_mfma_f32_16x16x32_bf16 v[18:21], v[182:185], v[206:209], v[18:21]
	v_mfma_f32_16x16x32_bf16 v[6:9], v[170:173], v[210:213], v[6:9]
	v_mfma_f32_16x16x32_bf16 v[6:9], v[174:177], v[214:217], v[6:9]
	v_mfma_f32_16x16x32_bf16 v[2:5], v[178:181], v[210:213], v[2:5]
	v_mfma_f32_16x16x32_bf16 v[2:5], v[182:185], v[214:217], v[2:5]
	s_setprio 0
	s_barrier
	s_cbranch_scc0 .LBB0_1938
	s_and_b64 vcc, exec, s[16:17]
	s_cbranch_vccz .LBB0_1941
	s_barrier

.LBB0_2019:
	ds_read_b128 v[110:113], v227
	ds_read_b128 v[114:117], v227 offset:1024
	ds_read_b128 v[122:125], v227 offset:2048
	ds_read_b128 v[126:129], v227 offset:3072
	ds_read_b128 v[146:149], v228
	ds_read_b128 v[150:153], v228 offset:1024
	ds_read_b128 v[154:157], v228 offset:2048
	ds_read_b128 v[158:161], v228 offset:3072
	s_add_u32 s0, s10, 0xfffc0080
	s_addc_u32 s1, s11, -1
	s_cmp_eq_u32 s77, 12
	s_cselect_b32 s13, s7, s1
	s_cselect_b32 s12, s9, s0
	s_cselect_b32 s3, s55, s63
	s_cselect_b32 s2, s57, s62
	v_lshl_add_u64 v[212:213], s[10:11], 0, v[180:181]
	s_add_i32 m0, s66, 0xc000
	ds_read_b128 v[162:165], v229
	ds_read_b128 v[166:169], v229 offset:1024
	ds_read_b128 v[188:191], v229 offset:2048
	ds_read_b128 v[192:195], v229 offset:3072
	ds_read_b128 v[196:199], v229 offset:4096
	ds_read_b128 v[200:203], v229 offset:5120
	ds_read_b128 v[204:207], v229 offset:6144
	ds_read_b128 v[208:211], v229 offset:7168
	global_load_lds_dwordx4 v[212:213], off
	v_lshl_add_u64 v[212:213], s[10:11], 0, v[182:183]
	s_add_i32 m0, s66, 0xe000
	s_nop 0
	global_load_lds_dwordx4 v[212:213], off
	s_waitcnt vmcnt(8)
	s_waitcnt lgkmcnt(0)
	s_barrier
	s_setprio 1
	s_waitcnt lgkmcnt(0)
	v_mfma_f32_16x16x32_bf16 v[142:145], v[110:113], v[162:165], v[142:145]
	v_mfma_f32_16x16x32_bf16 v[142:145], v[114:117], v[166:169], v[142:145]
	v_mfma_f32_16x16x32_bf16 v[138:141], v[122:125], v[162:165], v[138:141]
	v_mfma_f32_16x16x32_bf16 v[138:141], v[126:129], v[166:169], v[138:141]
	v_mfma_f32_16x16x32_bf16 v[134:137], v[110:113], v[188:191], v[134:137]
	v_mfma_f32_16x16x32_bf16 v[134:137], v[114:117], v[192:195], v[134:137]
	v_mfma_f32_16x16x32_bf16 v[130:133], v[122:125], v[188:191], v[130:133]
	v_mfma_f32_16x16x32_bf16 v[130:133], v[126:129], v[192:195], v[130:133]
	v_mfma_f32_16x16x32_bf16 v[118:121], v[110:113], v[196:199], v[118:121]
	v_mfma_f32_16x16x32_bf16 v[118:121], v[114:117], v[200:203], v[118:121]
	v_mfma_f32_16x16x32_bf16 v[106:109], v[122:125], v[196:199], v[106:109]
	v_mfma_f32_16x16x32_bf16 v[106:109], v[126:129], v[200:203], v[106:109]
	v_mfma_f32_16x16x32_bf16 v[102:105], v[110:113], v[204:207], v[102:105]
	v_mfma_f32_16x16x32_bf16 v[102:105], v[114:117], v[208:211], v[102:105]
	v_mfma_f32_16x16x32_bf16 v[98:101], v[122:125], v[204:207], v[98:101]
	v_mfma_f32_16x16x32_bf16 v[98:101], v[126:129], v[208:211], v[98:101]
	s_setprio 0
	s_setprio 1
	v_mfma_f32_16x16x32_bf16 v[62:65], v[146:149], v[162:165], v[62:65]
	v_mfma_f32_16x16x32_bf16 v[62:65], v[150:153], v[166:169], v[62:65]
	v_mfma_f32_16x16x32_bf16 v[58:61], v[154:157], v[162:165], v[58:61]
	v_mfma_f32_16x16x32_bf16 v[58:61], v[158:161], v[166:169], v[58:61]
	v_mfma_f32_16x16x32_bf16 v[54:57], v[146:149], v[188:191], v[54:57]
	v_mfma_f32_16x16x32_bf16 v[54:57], v[150:153], v[192:195], v[54:57]
	v_mfma_f32_16x16x32_bf16 v[50:53], v[154:157], v[188:191], v[50:53]
	v_mfma_f32_16x16x32_bf16 v[50:53], v[158:161], v[192:195], v[50:53]
	v_mfma_f32_16x16x32_bf16 v[46:49], v[146:149], v[196:199], v[46:49]
	v_mfma_f32_16x16x32_bf16 v[46:49], v[150:153], v[200:203], v[46:49]
	v_mfma_f32_16x16x32_bf16 v[42:45], v[154:157], v[196:199], v[42:45]
	v_mfma_f32_16x16x32_bf16 v[42:45], v[158:161], v[200:203], v[42:45]
	v_mfma_f32_16x16x32_bf16 v[38:41], v[146:149], v[204:207], v[38:41]
	v_mfma_f32_16x16x32_bf16 v[38:41], v[150:153], v[208:211], v[38:41]
	v_mfma_f32_16x16x32_bf16 v[34:37], v[154:157], v[204:207], v[34:37]
	v_mfma_f32_16x16x32_bf16 v[34:37], v[158:161], v[208:211], v[34:37]
	s_setprio 0
	s_barrier
	s_add_i32 s0, s75, s65
	v_lshl_add_u64 v[212:213], s[2:3], 0, v[172:173]
	s_mov_b32 m0, s0
	ds_read_b128 v[162:165], v229 offset:16384
	ds_read_b128 v[166:169], v229 offset:17408
	ds_read_b128 v[188:191], v229 offset:18432
	ds_read_b128 v[192:195], v229 offset:19456
	ds_read_b128 v[196:199], v229 offset:20480
	ds_read_b128 v[200:203], v229 offset:21504
	ds_read_b128 v[204:207], v229 offset:22528
	ds_read_b128 v[208:211], v229 offset:23552
	global_load_lds_dwordx4 v[212:213], off
	s_add_i32 m0, s0, 0x2000
	s_add_u32 s0, s2, 0x40000
	v_lshl_add_u64 v[214:215], s[2:3], 0, v[176:177]
	s_addc_u32 s1, s3, 0
	s_add_i32 s78, s76, s65
	global_load_lds_dwordx4 v[214:215], off
	v_lshl_add_u64 v[216:217], s[0:1], 0, v[172:173]
	s_mov_b32 m0, s78
	v_lshl_add_u64 v[218:219], s[12:13], 0, v[174:175]
	global_load_lds_dwordx4 v[216:217], off
	v_lshl_add_u64 v[216:217], s[0:1], 0, v[176:177]
	s_add_i32 m0, s78, 0x2000
	s_nop 0
	global_load_lds_dwordx4 v[216:217], off
	v_lshl_add_u64 v[216:217], s[12:13], 0, v[170:171]
	s_mov_b32 m0, s66
	s_nop 0
	global_load_lds_dwordx4 v[216:217], off
	s_mov_b32 m0, s67
	s_nop 0
	global_load_lds_dwordx4 v[218:219], off
	s_waitcnt vmcnt(8)
	s_waitcnt lgkmcnt(0)
	s_barrier
	s_setprio 1
	s_waitcnt lgkmcnt(0)
	v_mfma_f32_16x16x32_bf16 v[94:97], v[110:113], v[162:165], v[94:97]
	v_mfma_f32_16x16x32_bf16 v[94:97], v[114:117], v[166:169], v[94:97]
	v_mfma_f32_16x16x32_bf16 v[90:93], v[122:125], v[162:165], v[90:93]
	v_mfma_f32_16x16x32_bf16 v[90:93], v[126:129], v[166:169], v[90:93]
	v_mfma_f32_16x16x32_bf16 v[86:89], v[110:113], v[188:191], v[86:89]
	v_mfma_f32_16x16x32_bf16 v[86:89], v[114:117], v[192:195], v[86:89]
	v_mfma_f32_16x16x32_bf16 v[82:85], v[122:125], v[188:191], v[82:85]
	v_mfma_f32_16x16x32_bf16 v[82:85], v[126:129], v[192:195], v[82:85]
	v_mfma_f32_16x16x32_bf16 v[78:81], v[110:113], v[196:199], v[78:81]
	v_mfma_f32_16x16x32_bf16 v[78:81], v[114:117], v[200:203], v[78:81]
	v_mfma_f32_16x16x32_bf16 v[74:77], v[122:125], v[196:199], v[74:77]
	v_mfma_f32_16x16x32_bf16 v[74:77], v[126:129], v[200:203], v[74:77]
	v_mfma_f32_16x16x32_bf16 v[70:73], v[110:113], v[204:207], v[70:73]
	v_mfma_f32_16x16x32_bf16 v[70:73], v[114:117], v[208:211], v[70:73]
	v_mfma_f32_16x16x32_bf16 v[66:69], v[122:125], v[204:207], v[66:69]
	v_mfma_f32_16x16x32_bf16 v[66:69], v[126:129], v[208:211], v[66:69]
	s_setprio 0
	s_setprio 1
	v_mfma_f32_16x16x32_bf16 v[30:33], v[146:149], v[162:165], v[30:33]
	v_mfma_f32_16x16x32_bf16 v[30:33], v[150:153], v[166:169], v[30:33]
	v_mfma_f32_16x16x32_bf16 v[26:29], v[154:157], v[162:165], v[26:29]
	v_mfma_f32_16x16x32_bf16 v[26:29], v[158:161], v[166:169], v[26:29]
	v_mfma_f32_16x16x32_bf16 v[22:25], v[146:149], v[188:191], v[22:25]
	v_mfma_f32_16x16x32_bf16 v[22:25], v[150:153], v[192:195], v[22:25]
	v_mfma_f32_16x16x32_bf16 v[18:21], v[154:157], v[188:191], v[18:21]
	v_mfma_f32_16x16x32_bf16 v[18:21], v[158:161], v[192:195], v[18:21]
	v_mfma_f32_16x16x32_bf16 v[14:17], v[146:149], v[196:199], v[14:17]
	v_mfma_f32_16x16x32_bf16 v[14:17], v[150:153], v[200:203], v[14:17]
	v_mfma_f32_16x16x32_bf16 v[10:13], v[154:157], v[196:199], v[10:13]
	v_mfma_f32_16x16x32_bf16 v[10:13], v[158:161], v[200:203], v[10:13]
	v_mfma_f32_16x16x32_bf16 v[6:9], v[146:149], v[204:207], v[6:9]
	v_mfma_f32_16x16x32_bf16 v[6:9], v[150:153], v[208:211], v[6:9]
	v_mfma_f32_16x16x32_bf16 v[2:5], v[154:157], v[204:207], v[2:5]
	v_mfma_f32_16x16x32_bf16 v[2:5], v[158:161], v[208:211], v[2:5]
	s_setprio 0
	s_barrier
	s_add_i32 s78, 0, 0x18000
	s_add_i32 s79, 0, 0x1c000
	v_add_u32_e32 v126, s78, v222
	v_add_u32_e32 v158, s79, v222
	ds_read_b128 v[110:113], v126
	ds_read_b128 v[114:117], v126 offset:1024
	ds_read_b128 v[122:125], v126 offset:2048
	ds_read_b128 v[126:129], v126 offset:3072
	ds_read_b128 v[146:149], v158
	ds_read_b128 v[150:153], v158 offset:1024
	ds_read_b128 v[154:157], v158 offset:2048
	ds_read_b128 v[158:161], v158 offset:3072
	s_add_u32 s0, s12, 0x40000
	s_addc_u32 s1, s13, 0
	s_mov_b32 m0, s68
	v_lshl_add_u64 v[220:221], s[0:1], 0, v[170:171]
	ds_read_b128 v[162:165], v229 offset:32768
	ds_read_b128 v[166:169], v229 offset:33792
	ds_read_b128 v[188:191], v229 offset:34816
	ds_read_b128 v[192:195], v229 offset:35840
	ds_read_b128 v[196:199], v229 offset:36864
	ds_read_b128 v[200:203], v229 offset:37888
	ds_read_b128 v[204:207], v229 offset:38912
	ds_read_b128 v[208:211], v229 offset:39936
	global_load_lds_dwordx4 v[220:221], off
	v_lshl_add_u64 v[220:221], s[0:1], 0, v[174:175]
	s_mov_b32 m0, s69
	s_nop 0
	global_load_lds_dwordx4 v[220:221], off
	s_waitcnt vmcnt(8)
	s_waitcnt lgkmcnt(0)
	s_barrier
	s_setprio 1
	s_waitcnt lgkmcnt(0)
	v_mfma_f32_16x16x32_bf16 v[142:145], v[110:113], v[162:165], v[142:145]
	v_mfma_f32_16x16x32_bf16 v[142:145], v[114:117], v[166:169], v[142:145]
	v_mfma_f32_16x16x32_bf16 v[138:141], v[122:125], v[162:165], v[138:141]
	v_mfma_f32_16x16x32_bf16 v[138:141], v[126:129], v[166:169], v[138:141]
	v_mfma_f32_16x16x32_bf16 v[134:137], v[110:113], v[188:191], v[134:137]
	v_mfma_f32_16x16x32_bf16 v[134:137], v[114:117], v[192:195], v[134:137]
	v_mfma_f32_16x16x32_bf16 v[130:133], v[122:125], v[188:191], v[130:133]
	v_mfma_f32_16x16x32_bf16 v[130:133], v[126:129], v[192:195], v[130:133]
	v_mfma_f32_16x16x32_bf16 v[118:121], v[110:113], v[196:199], v[118:121]
	v_mfma_f32_16x16x32_bf16 v[118:121], v[114:117], v[200:203], v[118:121]
	v_mfma_f32_16x16x32_bf16 v[106:109], v[122:125], v[196:199], v[106:109]
	v_mfma_f32_16x16x32_bf16 v[106:109], v[126:129], v[200:203], v[106:109]
	v_mfma_f32_16x16x32_bf16 v[102:105], v[110:113], v[204:207], v[102:105]
	v_mfma_f32_16x16x32_bf16 v[102:105], v[114:117], v[208:211], v[102:105]
	v_mfma_f32_16x16x32_bf16 v[98:101], v[122:125], v[204:207], v[98:101]
	v_mfma_f32_16x16x32_bf16 v[98:101], v[126:129], v[208:211], v[98:101]
	s_setprio 0
	s_setprio 1
	v_mfma_f32_16x16x32_bf16 v[62:65], v[146:149], v[162:165], v[62:65]
	v_mfma_f32_16x16x32_bf16 v[62:65], v[150:153], v[166:169], v[62:65]
	v_mfma_f32_16x16x32_bf16 v[58:61], v[154:157], v[162:165], v[58:61]
	v_mfma_f32_16x16x32_bf16 v[58:61], v[158:161], v[166:169], v[58:61]
	v_mfma_f32_16x16x32_bf16 v[54:57], v[146:149], v[188:191], v[54:57]
	v_mfma_f32_16x16x32_bf16 v[54:57], v[150:153], v[192:195], v[54:57]
	v_mfma_f32_16x16x32_bf16 v[50:53], v[154:157], v[188:191], v[50:53]
	v_mfma_f32_16x16x32_bf16 v[50:53], v[158:161], v[192:195], v[50:53]
	v_mfma_f32_16x16x32_bf16 v[46:49], v[146:149], v[196:199], v[46:49]
	v_mfma_f32_16x16x32_bf16 v[46:49], v[150:153], v[200:203], v[46:49]
	v_mfma_f32_16x16x32_bf16 v[42:45], v[154:157], v[196:199], v[42:45]
	v_mfma_f32_16x16x32_bf16 v[42:45], v[158:161], v[200:203], v[42:45]
	v_mfma_f32_16x16x32_bf16 v[38:41], v[146:149], v[204:207], v[38:41]
	v_mfma_f32_16x16x32_bf16 v[38:41], v[150:153], v[208:211], v[38:41]
	v_mfma_f32_16x16x32_bf16 v[34:37], v[154:157], v[204:207], v[34:37]
	v_mfma_f32_16x16x32_bf16 v[34:37], v[158:161], v[208:211], v[34:37]
	s_setprio 0
	s_barrier
	s_add_i32 s0, s78, s65
	v_lshl_add_u64 v[212:213], v[212:213], 0, s[24:25]
	s_mov_b32 m0, s0
	ds_read_b128 v[162:165], v229 offset:49152
	ds_read_b128 v[166:169], v229 offset:50176
	ds_read_b128 v[188:191], v229 offset:51200
	ds_read_b128 v[192:195], v229 offset:52224
	ds_read_b128 v[196:199], v229 offset:53248
	ds_read_b128 v[200:203], v229 offset:54272
	ds_read_b128 v[204:207], v229 offset:55296
	ds_read_b128 v[208:211], v229 offset:56320
	global_load_lds_dwordx4 v[212:213], off
	s_add_i32 m0, s0, 0x2000
	s_add_u32 s0, s2, 0x40080
	v_lshl_add_u64 v[212:213], v[214:215], 0, s[24:25]
	s_addc_u32 s1, s3, 0
	s_add_i32 s2, s79, s65
	global_load_lds_dwordx4 v[212:213], off
	v_lshl_add_u64 v[212:213], s[0:1], 0, v[172:173]
	s_mov_b32 m0, s2
	s_nop 0
	global_load_lds_dwordx4 v[212:213], off
	v_lshl_add_u64 v[212:213], s[0:1], 0, v[176:177]
	s_add_i32 m0, s2, 0x2000
	s_nop 0
	global_load_lds_dwordx4 v[212:213], off
	v_lshl_add_u64 v[212:213], v[216:217], 0, s[24:25]
	s_mov_b32 m0, s71
	s_nop 0
	global_load_lds_dwordx4 v[212:213], off
	v_lshl_add_u64 v[212:213], v[218:219], 0, s[24:25]
	s_mov_b32 m0, s72
	s_nop 0
	global_load_lds_dwordx4 v[212:213], off
	s_waitcnt vmcnt(8)
	s_waitcnt lgkmcnt(0)
	s_barrier
	s_setprio 1
	s_waitcnt lgkmcnt(0)
	v_mfma_f32_16x16x32_bf16 v[94:97], v[110:113], v[162:165], v[94:97]
	v_mfma_f32_16x16x32_bf16 v[94:97], v[114:117], v[166:169], v[94:97]
	v_mfma_f32_16x16x32_bf16 v[90:93], v[122:125], v[162:165], v[90:93]
	v_mfma_f32_16x16x32_bf16 v[90:93], v[126:129], v[166:169], v[90:93]
	v_mfma_f32_16x16x32_bf16 v[86:89], v[110:113], v[188:191], v[86:89]
	v_mfma_f32_16x16x32_bf16 v[86:89], v[114:117], v[192:195], v[86:89]
	v_mfma_f32_16x16x32_bf16 v[82:85], v[122:125], v[188:191], v[82:85]
	v_mfma_f32_16x16x32_bf16 v[82:85], v[126:129], v[192:195], v[82:85]
	v_mfma_f32_16x16x32_bf16 v[78:81], v[110:113], v[196:199], v[78:81]
	v_mfma_f32_16x16x32_bf16 v[78:81], v[114:117], v[200:203], v[78:81]
	v_mfma_f32_16x16x32_bf16 v[74:77], v[122:125], v[196:199], v[74:77]
	v_mfma_f32_16x16x32_bf16 v[74:77], v[126:129], v[200:203], v[74:77]
	v_mfma_f32_16x16x32_bf16 v[70:73], v[110:113], v[204:207], v[70:73]
	v_mfma_f32_16x16x32_bf16 v[70:73], v[114:117], v[208:211], v[70:73]
	v_mfma_f32_16x16x32_bf16 v[66:69], v[122:125], v[204:207], v[66:69]
	v_mfma_f32_16x16x32_bf16 v[66:69], v[126:129], v[208:211], v[66:69]
	s_setprio 0
	s_setprio 1
	v_mfma_f32_16x16x32_bf16 v[30:33], v[146:149], v[162:165], v[30:33]
	s_add_i32 s77, s77, 2
	s_add_u32 s10, s10, 0x100
	s_addc_u32 s11, s11, 0
	s_add_u32 s62, s62, 0x100
	s_addc_u32 s63, s63, 0
	s_cmp_gt_u32 s77, 13
	v_mfma_f32_16x16x32_bf16 v[30:33], v[150:153], v[166:169], v[30:33]
	v_mfma_f32_16x16x32_bf16 v[26:29], v[154:157], v[162:165], v[26:29]
	v_mfma_f32_16x16x32_bf16 v[26:29], v[158:161], v[166:169], v[26:29]
	v_mfma_f32_16x16x32_bf16 v[22:25], v[146:149], v[188:191], v[22:25]
	v_mfma_f32_16x16x32_bf16 v[22:25], v[150:153], v[192:195], v[22:25]
	v_mfma_f32_16x16x32_bf16 v[18:21], v[154:157], v[188:191], v[18:21]
	v_mfma_f32_16x16x32_bf16 v[18:21], v[158:161], v[192:195], v[18:21]
	v_mfma_f32_16x16x32_bf16 v[14:17], v[146:149], v[196:199], v[14:17]
	v_mfma_f32_16x16x32_bf16 v[14:17], v[150:153], v[200:203], v[14:17]
	v_mfma_f32_16x16x32_bf16 v[10:13], v[154:157], v[196:199], v[10:13]
	v_mfma_f32_16x16x32_bf16 v[10:13], v[158:161], v[200:203], v[10:13]
	v_mfma_f32_16x16x32_bf16 v[6:9], v[146:149], v[204:207], v[6:9]
	v_mfma_f32_16x16x32_bf16 v[6:9], v[150:153], v[208:211], v[6:9]
	v_mfma_f32_16x16x32_bf16 v[2:5], v[154:157], v[204:207], v[2:5]
	v_mfma_f32_16x16x32_bf16 v[2:5], v[158:161], v[208:211], v[2:5]
	s_setprio 0
	s_barrier
	s_cbranch_scc0 .LBB0_2019
	s_and_b64 vcc, exec, s[26:27]
	s_cbranch_vccz .LBB0_2022
	s_barrier

.LBB0_2118:
	ds_read_b128 v[130:133], v186
	ds_read_b128 v[134:137], v186 offset:1024
	ds_read_b128 v[138:141], v186 offset:2048
	ds_read_b128 v[142:145], v186 offset:3072
	ds_read_b128 v[146:149], v187
	ds_read_b128 v[150:153], v187 offset:1024
	ds_read_b128 v[170:173], v187 offset:2048
	ds_read_b128 v[174:177], v187 offset:3072
	s_add_u32 s0, s38, 0xfffc0080
	s_addc_u32 s1, s39, -1
	s_cmp_eq_u32 s59, 12
	s_cselect_b32 s41, s11, s1
	s_cselect_b32 s40, s29, s0
	s_cselect_b32 s3, s27, s58
	s_cselect_b32 s2, s56, s57
	v_lshl_add_u64 v[218:219], s[38:39], 0, v[162:163]
	s_add_i32 m0, s37, 0xc000
	ds_read_b128 v[178:181], v188
	ds_read_b128 v[190:193], v188 offset:1024
	ds_read_b128 v[194:197], v188 offset:2048
	ds_read_b128 v[198:201], v188 offset:3072
	ds_read_b128 v[202:205], v188 offset:4096
	ds_read_b128 v[206:209], v188 offset:5120
	ds_read_b128 v[210:213], v188 offset:6144
	ds_read_b128 v[214:217], v188 offset:7168
	global_load_lds_dwordx4 v[218:219], off
	v_lshl_add_u64 v[218:219], s[38:39], 0, v[164:165]
	s_add_i32 m0, s37, 0xe000
	s_nop 0
	global_load_lds_dwordx4 v[218:219], off
	s_waitcnt vmcnt(8)
	s_waitcnt lgkmcnt(0)
	s_barrier
	s_setprio 1
	s_waitcnt lgkmcnt(0)
	v_mfma_f32_16x16x32_bf16 v[126:129], v[130:133], v[178:181], v[126:129]
	v_mfma_f32_16x16x32_bf16 v[126:129], v[134:137], v[190:193], v[126:129]
	v_mfma_f32_16x16x32_bf16 v[122:125], v[138:141], v[178:181], v[122:125]
	v_mfma_f32_16x16x32_bf16 v[122:125], v[142:145], v[190:193], v[122:125]
	v_mfma_f32_16x16x32_bf16 v[110:113], v[130:133], v[194:197], v[110:113]
	v_mfma_f32_16x16x32_bf16 v[110:113], v[134:137], v[198:201], v[110:113]
	v_mfma_f32_16x16x32_bf16 v[106:109], v[138:141], v[194:197], v[106:109]
	v_mfma_f32_16x16x32_bf16 v[106:109], v[142:145], v[198:201], v[106:109]
	v_mfma_f32_16x16x32_bf16 v[94:97], v[130:133], v[202:205], v[94:97]
	v_mfma_f32_16x16x32_bf16 v[94:97], v[134:137], v[206:209], v[94:97]
	v_mfma_f32_16x16x32_bf16 v[90:93], v[138:141], v[202:205], v[90:93]
	v_mfma_f32_16x16x32_bf16 v[90:93], v[142:145], v[206:209], v[90:93]
	v_mfma_f32_16x16x32_bf16 v[78:81], v[130:133], v[210:213], v[78:81]
	v_mfma_f32_16x16x32_bf16 v[78:81], v[134:137], v[214:217], v[78:81]
	v_mfma_f32_16x16x32_bf16 v[74:77], v[138:141], v[210:213], v[74:77]
	v_mfma_f32_16x16x32_bf16 v[74:77], v[142:145], v[214:217], v[74:77]
	s_setprio 0
	s_setprio 1
	v_mfma_f32_16x16x32_bf16 v[118:121], v[146:149], v[178:181], v[118:121]
	v_mfma_f32_16x16x32_bf16 v[118:121], v[150:153], v[190:193], v[118:121]
	v_mfma_f32_16x16x32_bf16 v[114:117], v[170:173], v[178:181], v[114:117]
	v_mfma_f32_16x16x32_bf16 v[114:117], v[174:177], v[190:193], v[114:117]
	v_mfma_f32_16x16x32_bf16 v[102:105], v[146:149], v[194:197], v[102:105]
	v_mfma_f32_16x16x32_bf16 v[102:105], v[150:153], v[198:201], v[102:105]
	v_mfma_f32_16x16x32_bf16 v[98:101], v[170:173], v[194:197], v[98:101]
	v_mfma_f32_16x16x32_bf16 v[98:101], v[174:177], v[198:201], v[98:101]
	v_mfma_f32_16x16x32_bf16 v[86:89], v[146:149], v[202:205], v[86:89]
	v_mfma_f32_16x16x32_bf16 v[86:89], v[150:153], v[206:209], v[86:89]
	v_mfma_f32_16x16x32_bf16 v[82:85], v[170:173], v[202:205], v[82:85]
	v_mfma_f32_16x16x32_bf16 v[82:85], v[174:177], v[206:209], v[82:85]
	v_mfma_f32_16x16x32_bf16 v[70:73], v[146:149], v[210:213], v[70:73]
	v_mfma_f32_16x16x32_bf16 v[70:73], v[150:153], v[214:217], v[70:73]
	v_mfma_f32_16x16x32_bf16 v[66:69], v[170:173], v[210:213], v[66:69]
	v_mfma_f32_16x16x32_bf16 v[66:69], v[174:177], v[214:217], v[66:69]
	s_setprio 0
	s_barrier
	s_add_i32 s0, s54, s45
	v_lshl_add_u64 v[218:219], s[2:3], 0, v[156:157]
	s_mov_b32 m0, s0
	ds_read_b128 v[178:181], v188 offset:16384
	ds_read_b128 v[190:193], v188 offset:17408
	ds_read_b128 v[194:197], v188 offset:18432
	ds_read_b128 v[198:201], v188 offset:19456
	ds_read_b128 v[202:205], v188 offset:20480
	ds_read_b128 v[206:209], v188 offset:21504
	ds_read_b128 v[210:213], v188 offset:22528
	ds_read_b128 v[214:217], v188 offset:23552
	global_load_lds_dwordx4 v[218:219], off
	s_add_i32 m0, s0, 0x2000
	s_add_u32 s0, s2, 0x40000
	v_lshl_add_u64 v[220:221], s[2:3], 0, v[160:161]
	s_addc_u32 s1, s3, 0
	s_add_i32 s60, s55, s45
	global_load_lds_dwordx4 v[220:221], off
	v_lshl_add_u64 v[222:223], s[0:1], 0, v[156:157]
	s_mov_b32 m0, s60
	v_lshl_add_u64 v[224:225], s[40:41], 0, v[158:159]
	global_load_lds_dwordx4 v[222:223], off
	v_lshl_add_u64 v[222:223], s[0:1], 0, v[160:161]
	s_add_i32 m0, s60, 0x2000
	s_nop 0
	global_load_lds_dwordx4 v[222:223], off
	v_lshl_add_u64 v[222:223], s[40:41], 0, v[154:155]
	s_mov_b32 m0, s37
	s_nop 0
	global_load_lds_dwordx4 v[222:223], off
	s_mov_b32 m0, s46
	s_nop 0
	global_load_lds_dwordx4 v[224:225], off
	s_waitcnt vmcnt(8)
	s_waitcnt lgkmcnt(0)
	s_barrier
	s_setprio 1
	s_waitcnt lgkmcnt(0)
	v_mfma_f32_16x16x32_bf16 v[62:65], v[130:133], v[178:181], v[62:65]
	v_mfma_f32_16x16x32_bf16 v[62:65], v[134:137], v[190:193], v[62:65]
	v_mfma_f32_16x16x32_bf16 v[58:61], v[138:141], v[178:181], v[58:61]
	v_mfma_f32_16x16x32_bf16 v[58:61], v[142:145], v[190:193], v[58:61]
	v_mfma_f32_16x16x32_bf16 v[46:49], v[130:133], v[194:197], v[46:49]
	v_mfma_f32_16x16x32_bf16 v[46:49], v[134:137], v[198:201], v[46:49]
	v_mfma_f32_16x16x32_bf16 v[42:45], v[138:141], v[194:197], v[42:45]
	v_mfma_f32_16x16x32_bf16 v[42:45], v[142:145], v[198:201], v[42:45]
	v_mfma_f32_16x16x32_bf16 v[30:33], v[130:133], v[202:205], v[30:33]
	v_mfma_f32_16x16x32_bf16 v[30:33], v[134:137], v[206:209], v[30:33]
	v_mfma_f32_16x16x32_bf16 v[26:29], v[138:141], v[202:205], v[26:29]
	v_mfma_f32_16x16x32_bf16 v[26:29], v[142:145], v[206:209], v[26:29]
	v_mfma_f32_16x16x32_bf16 v[14:17], v[130:133], v[210:213], v[14:17]
	v_mfma_f32_16x16x32_bf16 v[14:17], v[134:137], v[214:217], v[14:17]
	v_mfma_f32_16x16x32_bf16 v[10:13], v[138:141], v[210:213], v[10:13]
	v_mfma_f32_16x16x32_bf16 v[10:13], v[142:145], v[214:217], v[10:13]
	s_setprio 0
	s_setprio 1
	v_mfma_f32_16x16x32_bf16 v[54:57], v[146:149], v[178:181], v[54:57]
	v_mfma_f32_16x16x32_bf16 v[54:57], v[150:153], v[190:193], v[54:57]
	v_mfma_f32_16x16x32_bf16 v[50:53], v[170:173], v[178:181], v[50:53]
	v_mfma_f32_16x16x32_bf16 v[50:53], v[174:177], v[190:193], v[50:53]
	v_mfma_f32_16x16x32_bf16 v[38:41], v[146:149], v[194:197], v[38:41]
	v_mfma_f32_16x16x32_bf16 v[38:41], v[150:153], v[198:201], v[38:41]
	v_mfma_f32_16x16x32_bf16 v[34:37], v[170:173], v[194:197], v[34:37]
	v_mfma_f32_16x16x32_bf16 v[34:37], v[174:177], v[198:201], v[34:37]
	v_mfma_f32_16x16x32_bf16 v[22:25], v[146:149], v[202:205], v[22:25]
	v_mfma_f32_16x16x32_bf16 v[22:25], v[150:153], v[206:209], v[22:25]
	v_mfma_f32_16x16x32_bf16 v[18:21], v[170:173], v[202:205], v[18:21]
	v_mfma_f32_16x16x32_bf16 v[18:21], v[174:177], v[206:209], v[18:21]
	v_mfma_f32_16x16x32_bf16 v[6:9], v[146:149], v[210:213], v[6:9]
	v_mfma_f32_16x16x32_bf16 v[6:9], v[150:153], v[214:217], v[6:9]
	v_mfma_f32_16x16x32_bf16 v[2:5], v[170:173], v[210:213], v[2:5]
	v_mfma_f32_16x16x32_bf16 v[2:5], v[174:177], v[214:217], v[2:5]
	s_setprio 0
	s_barrier
	s_add_i32 s60, 0, 0x18000
	s_add_i32 s61, 0, 0x1c000
	v_add_u32_e32 v142, s60, v182
	v_add_u32_e32 v174, s61, v182
	ds_read_b128 v[130:133], v142
	ds_read_b128 v[134:137], v142 offset:1024
	ds_read_b128 v[138:141], v142 offset:2048
	ds_read_b128 v[142:145], v142 offset:3072
	ds_read_b128 v[146:149], v174
	ds_read_b128 v[150:153], v174 offset:1024
	ds_read_b128 v[170:173], v174 offset:2048
	ds_read_b128 v[174:177], v174 offset:3072
	s_add_u32 s0, s40, 0x40000
	s_addc_u32 s1, s41, 0
	s_mov_b32 m0, s47
	v_lshl_add_u64 v[226:227], s[0:1], 0, v[154:155]
	ds_read_b128 v[178:181], v188 offset:32768
	ds_read_b128 v[190:193], v188 offset:33792
	ds_read_b128 v[194:197], v188 offset:34816
	ds_read_b128 v[198:201], v188 offset:35840
	ds_read_b128 v[202:205], v188 offset:36864
	ds_read_b128 v[206:209], v188 offset:37888
	ds_read_b128 v[210:213], v188 offset:38912
	ds_read_b128 v[214:217], v188 offset:39936
	global_load_lds_dwordx4 v[226:227], off
	v_lshl_add_u64 v[226:227], s[0:1], 0, v[158:159]
	s_mov_b32 m0, s48
	s_nop 0
	global_load_lds_dwordx4 v[226:227], off
	s_waitcnt vmcnt(8)
	s_waitcnt lgkmcnt(0)
	s_barrier
	s_setprio 1
	s_waitcnt lgkmcnt(0)
	v_mfma_f32_16x16x32_bf16 v[126:129], v[130:133], v[178:181], v[126:129]
	v_mfma_f32_16x16x32_bf16 v[126:129], v[134:137], v[190:193], v[126:129]
	v_mfma_f32_16x16x32_bf16 v[122:125], v[138:141], v[178:181], v[122:125]
	v_mfma_f32_16x16x32_bf16 v[122:125], v[142:145], v[190:193], v[122:125]
	v_mfma_f32_16x16x32_bf16 v[110:113], v[130:133], v[194:197], v[110:113]
	v_mfma_f32_16x16x32_bf16 v[110:113], v[134:137], v[198:201], v[110:113]
	v_mfma_f32_16x16x32_bf16 v[106:109], v[138:141], v[194:197], v[106:109]
	v_mfma_f32_16x16x32_bf16 v[106:109], v[142:145], v[198:201], v[106:109]
	v_mfma_f32_16x16x32_bf16 v[94:97], v[130:133], v[202:205], v[94:97]
	v_mfma_f32_16x16x32_bf16 v[94:97], v[134:137], v[206:209], v[94:97]
	v_mfma_f32_16x16x32_bf16 v[90:93], v[138:141], v[202:205], v[90:93]
	v_mfma_f32_16x16x32_bf16 v[90:93], v[142:145], v[206:209], v[90:93]
	v_mfma_f32_16x16x32_bf16 v[78:81], v[130:133], v[210:213], v[78:81]
	v_mfma_f32_16x16x32_bf16 v[78:81], v[134:137], v[214:217], v[78:81]
	v_mfma_f32_16x16x32_bf16 v[74:77], v[138:141], v[210:213], v[74:77]
	v_mfma_f32_16x16x32_bf16 v[74:77], v[142:145], v[214:217], v[74:77]
	s_setprio 0
	s_setprio 1
	v_mfma_f32_16x16x32_bf16 v[118:121], v[146:149], v[178:181], v[118:121]
	v_mfma_f32_16x16x32_bf16 v[118:121], v[150:153], v[190:193], v[118:121]
	v_mfma_f32_16x16x32_bf16 v[114:117], v[170:173], v[178:181], v[114:117]
	v_mfma_f32_16x16x32_bf16 v[114:117], v[174:177], v[190:193], v[114:117]
	v_mfma_f32_16x16x32_bf16 v[102:105], v[146:149], v[194:197], v[102:105]
	v_mfma_f32_16x16x32_bf16 v[102:105], v[150:153], v[198:201], v[102:105]
	v_mfma_f32_16x16x32_bf16 v[98:101], v[170:173], v[194:197], v[98:101]
	v_mfma_f32_16x16x32_bf16 v[98:101], v[174:177], v[198:201], v[98:101]
	v_mfma_f32_16x16x32_bf16 v[86:89], v[146:149], v[202:205], v[86:89]
	v_mfma_f32_16x16x32_bf16 v[86:89], v[150:153], v[206:209], v[86:89]
	v_mfma_f32_16x16x32_bf16 v[82:85], v[170:173], v[202:205], v[82:85]
	v_mfma_f32_16x16x32_bf16 v[82:85], v[174:177], v[206:209], v[82:85]
	v_mfma_f32_16x16x32_bf16 v[70:73], v[146:149], v[210:213], v[70:73]
	v_mfma_f32_16x16x32_bf16 v[70:73], v[150:153], v[214:217], v[70:73]
	v_mfma_f32_16x16x32_bf16 v[66:69], v[170:173], v[210:213], v[66:69]
	v_mfma_f32_16x16x32_bf16 v[66:69], v[174:177], v[214:217], v[66:69]
	s_setprio 0
	s_barrier
	s_add_i32 s0, s60, s45
	v_lshl_add_u64 v[218:219], v[218:219], 0, s[16:17]
	s_mov_b32 m0, s0
	ds_read_b128 v[178:181], v188 offset:49152
	ds_read_b128 v[190:193], v188 offset:50176
	ds_read_b128 v[194:197], v188 offset:51200
	ds_read_b128 v[198:201], v188 offset:52224
	ds_read_b128 v[202:205], v188 offset:53248
	ds_read_b128 v[206:209], v188 offset:54272
	ds_read_b128 v[210:213], v188 offset:55296
	ds_read_b128 v[214:217], v188 offset:56320
	global_load_lds_dwordx4 v[218:219], off
	s_add_i32 m0, s0, 0x2000
	s_add_u32 s0, s2, 0x40080
	v_lshl_add_u64 v[218:219], v[220:221], 0, s[16:17]
	s_addc_u32 s1, s3, 0
	s_add_i32 s2, s61, s45
	global_load_lds_dwordx4 v[218:219], off
	v_lshl_add_u64 v[218:219], s[0:1], 0, v[156:157]
	s_mov_b32 m0, s2
	s_nop 0
	global_load_lds_dwordx4 v[218:219], off
	v_lshl_add_u64 v[218:219], s[0:1], 0, v[160:161]
	s_add_i32 m0, s2, 0x2000
	s_nop 0
	global_load_lds_dwordx4 v[218:219], off
	v_lshl_add_u64 v[218:219], v[222:223], 0, s[16:17]
	s_mov_b32 m0, s50
	s_nop 0
	global_load_lds_dwordx4 v[218:219], off
	v_lshl_add_u64 v[218:219], v[224:225], 0, s[16:17]
	s_mov_b32 m0, s51
	s_nop 0
	global_load_lds_dwordx4 v[218:219], off
	s_waitcnt vmcnt(8)
	s_waitcnt lgkmcnt(0)
	s_barrier
	s_setprio 1
	s_waitcnt lgkmcnt(0)
	v_mfma_f32_16x16x32_bf16 v[62:65], v[130:133], v[178:181], v[62:65]
	v_mfma_f32_16x16x32_bf16 v[62:65], v[134:137], v[190:193], v[62:65]
	v_mfma_f32_16x16x32_bf16 v[58:61], v[138:141], v[178:181], v[58:61]
	v_mfma_f32_16x16x32_bf16 v[58:61], v[142:145], v[190:193], v[58:61]
	v_mfma_f32_16x16x32_bf16 v[46:49], v[130:133], v[194:197], v[46:49]
	v_mfma_f32_16x16x32_bf16 v[46:49], v[134:137], v[198:201], v[46:49]
	v_mfma_f32_16x16x32_bf16 v[42:45], v[138:141], v[194:197], v[42:45]
	v_mfma_f32_16x16x32_bf16 v[42:45], v[142:145], v[198:201], v[42:45]
	v_mfma_f32_16x16x32_bf16 v[30:33], v[130:133], v[202:205], v[30:33]
	v_mfma_f32_16x16x32_bf16 v[30:33], v[134:137], v[206:209], v[30:33]
	v_mfma_f32_16x16x32_bf16 v[26:29], v[138:141], v[202:205], v[26:29]
	v_mfma_f32_16x16x32_bf16 v[26:29], v[142:145], v[206:209], v[26:29]
	v_mfma_f32_16x16x32_bf16 v[14:17], v[130:133], v[210:213], v[14:17]
	v_mfma_f32_16x16x32_bf16 v[14:17], v[134:137], v[214:217], v[14:17]
	v_mfma_f32_16x16x32_bf16 v[10:13], v[138:141], v[210:213], v[10:13]
	v_mfma_f32_16x16x32_bf16 v[10:13], v[142:145], v[214:217], v[10:13]
	s_setprio 0
	s_setprio 1
	v_mfma_f32_16x16x32_bf16 v[54:57], v[146:149], v[178:181], v[54:57]
	s_add_i32 s59, s59, 2
	s_add_u32 s38, s38, 0x100
	s_addc_u32 s39, s39, 0
	s_add_u32 s57, s57, 0x100
	s_addc_u32 s58, s58, 0
	s_cmp_gt_u32 s59, 13
	v_mfma_f32_16x16x32_bf16 v[54:57], v[150:153], v[190:193], v[54:57]
	v_mfma_f32_16x16x32_bf16 v[50:53], v[170:173], v[178:181], v[50:53]
	v_mfma_f32_16x16x32_bf16 v[50:53], v[174:177], v[190:193], v[50:53]
	v_mfma_f32_16x16x32_bf16 v[38:41], v[146:149], v[194:197], v[38:41]
	v_mfma_f32_16x16x32_bf16 v[38:41], v[150:153], v[198:201], v[38:41]
	v_mfma_f32_16x16x32_bf16 v[34:37], v[170:173], v[194:197], v[34:37]
	v_mfma_f32_16x16x32_bf16 v[34:37], v[174:177], v[198:201], v[34:37]
	v_mfma_f32_16x16x32_bf16 v[22:25], v[146:149], v[202:205], v[22:25]
	v_mfma_f32_16x16x32_bf16 v[22:25], v[150:153], v[206:209], v[22:25]
	v_mfma_f32_16x16x32_bf16 v[18:21], v[170:173], v[202:205], v[18:21]
	v_mfma_f32_16x16x32_bf16 v[18:21], v[174:177], v[206:209], v[18:21]
	v_mfma_f32_16x16x32_bf16 v[6:9], v[146:149], v[210:213], v[6:9]
	v_mfma_f32_16x16x32_bf16 v[6:9], v[150:153], v[214:217], v[6:9]
	v_mfma_f32_16x16x32_bf16 v[2:5], v[170:173], v[210:213], v[2:5]
	v_mfma_f32_16x16x32_bf16 v[2:5], v[174:177], v[214:217], v[2:5]
	s_setprio 0
	s_barrier
	s_cbranch_scc0 .LBB0_2118
	s_and_b64 vcc, exec, s[18:19]
	s_cbranch_vccz .LBB0_2121
	s_barrier

.LBB0_2207:
	ds_read_b128 v[148:151], v165
	ds_read_b128 v[152:155], v165 offset:1024
	ds_read_b128 v[156:159], v165 offset:2048
	ds_read_b128 v[160:163], v165 offset:3072
	ds_read_b128 v[170:173], v166
	ds_read_b128 v[174:177], v166 offset:1024
	ds_read_b128 v[178:181], v166 offset:2048
	ds_read_b128 v[182:185], v166 offset:3072
	s_add_u32 s0, s28, 0xfffc0080
	s_addc_u32 s1, s29, -1
	s_cmp_eq_u32 s53, 12
	s_cselect_b32 s31, s21, s1
	s_cselect_b32 s30, s49, s0
	s_cselect_b32 s3, s19, s52
	s_cselect_b32 s2, s50, s51
	v_lshl_add_u64 v[218:219], s[28:29], 0, v[140:141]
	s_add_i32 m0, s27, 0xc000
	ds_read_b128 v[186:189], v167
	ds_read_b128 v[190:193], v167 offset:1024
	ds_read_b128 v[194:197], v167 offset:2048
	ds_read_b128 v[198:201], v167 offset:3072
	ds_read_b128 v[202:205], v167 offset:4096
	ds_read_b128 v[206:209], v167 offset:5120
	ds_read_b128 v[210:213], v167 offset:6144
	ds_read_b128 v[214:217], v167 offset:7168
	global_load_lds_dwordx4 v[218:219], off
	v_lshl_add_u64 v[218:219], s[28:29], 0, v[142:143]
	s_add_i32 m0, s27, 0xe000
	s_nop 0
	global_load_lds_dwordx4 v[218:219], off
	s_waitcnt vmcnt(8)
	s_waitcnt lgkmcnt(0)
	s_barrier
	s_setprio 1
	s_waitcnt lgkmcnt(0)
	v_mfma_f32_16x16x32_bf16 v[126:129], v[148:151], v[186:189], v[126:129]
	v_mfma_f32_16x16x32_bf16 v[126:129], v[152:155], v[190:193], v[126:129]
	v_mfma_f32_16x16x32_bf16 v[118:121], v[156:159], v[186:189], v[118:121]
	v_mfma_f32_16x16x32_bf16 v[118:121], v[160:163], v[190:193], v[118:121]
	v_mfma_f32_16x16x32_bf16 v[110:113], v[148:151], v[194:197], v[110:113]
	v_mfma_f32_16x16x32_bf16 v[110:113], v[152:155], v[198:201], v[110:113]
	v_mfma_f32_16x16x32_bf16 v[102:105], v[156:159], v[194:197], v[102:105]
	v_mfma_f32_16x16x32_bf16 v[102:105], v[160:163], v[198:201], v[102:105]
	v_mfma_f32_16x16x32_bf16 v[94:97], v[148:151], v[202:205], v[94:97]
	v_mfma_f32_16x16x32_bf16 v[94:97], v[152:155], v[206:209], v[94:97]
	v_mfma_f32_16x16x32_bf16 v[86:89], v[156:159], v[202:205], v[86:89]
	v_mfma_f32_16x16x32_bf16 v[86:89], v[160:163], v[206:209], v[86:89]
	v_mfma_f32_16x16x32_bf16 v[78:81], v[148:151], v[210:213], v[78:81]
	v_mfma_f32_16x16x32_bf16 v[78:81], v[152:155], v[214:217], v[78:81]
	v_mfma_f32_16x16x32_bf16 v[70:73], v[156:159], v[210:213], v[70:73]
	v_mfma_f32_16x16x32_bf16 v[70:73], v[160:163], v[214:217], v[70:73]
	s_setprio 0
	s_setprio 1
	v_mfma_f32_16x16x32_bf16 v[122:125], v[170:173], v[186:189], v[122:125]
	v_mfma_f32_16x16x32_bf16 v[122:125], v[174:177], v[190:193], v[122:125]
	v_mfma_f32_16x16x32_bf16 v[114:117], v[178:181], v[186:189], v[114:117]
	v_mfma_f32_16x16x32_bf16 v[114:117], v[182:185], v[190:193], v[114:117]
	v_mfma_f32_16x16x32_bf16 v[106:109], v[170:173], v[194:197], v[106:109]
	v_mfma_f32_16x16x32_bf16 v[106:109], v[174:177], v[198:201], v[106:109]
	v_mfma_f32_16x16x32_bf16 v[98:101], v[178:181], v[194:197], v[98:101]
	v_mfma_f32_16x16x32_bf16 v[98:101], v[182:185], v[198:201], v[98:101]
	v_mfma_f32_16x16x32_bf16 v[90:93], v[170:173], v[202:205], v[90:93]
	v_mfma_f32_16x16x32_bf16 v[90:93], v[174:177], v[206:209], v[90:93]
	v_mfma_f32_16x16x32_bf16 v[82:85], v[178:181], v[202:205], v[82:85]
	v_mfma_f32_16x16x32_bf16 v[82:85], v[182:185], v[206:209], v[82:85]
	v_mfma_f32_16x16x32_bf16 v[74:77], v[170:173], v[210:213], v[74:77]
	v_mfma_f32_16x16x32_bf16 v[74:77], v[174:177], v[214:217], v[74:77]
	v_mfma_f32_16x16x32_bf16 v[66:69], v[178:181], v[210:213], v[66:69]
	v_mfma_f32_16x16x32_bf16 v[66:69], v[182:185], v[214:217], v[66:69]
	s_setprio 0
	s_barrier
	s_add_i32 s0, s44, s35
	v_lshl_add_u64 v[218:219], s[2:3], 0, v[134:135]
	s_mov_b32 m0, s0
	ds_read_b128 v[186:189], v167 offset:16384
	ds_read_b128 v[190:193], v167 offset:17408
	ds_read_b128 v[194:197], v167 offset:18432
	ds_read_b128 v[198:201], v167 offset:19456
	ds_read_b128 v[202:205], v167 offset:20480
	ds_read_b128 v[206:209], v167 offset:21504
	ds_read_b128 v[210:213], v167 offset:22528
	ds_read_b128 v[214:217], v167 offset:23552
	global_load_lds_dwordx4 v[218:219], off
	s_add_i32 m0, s0, 0x2000
	s_add_u32 s0, s2, 0x40000
	v_lshl_add_u64 v[220:221], s[2:3], 0, v[130:131]
	s_addc_u32 s1, s3, 0
	s_add_i32 s54, s45, s35
	global_load_lds_dwordx4 v[220:221], off
	v_lshl_add_u64 v[222:223], s[0:1], 0, v[134:135]
	s_mov_b32 m0, s54
	v_lshl_add_u64 v[224:225], s[30:31], 0, v[132:133]
	global_load_lds_dwordx4 v[222:223], off
	v_lshl_add_u64 v[222:223], s[0:1], 0, v[130:131]
	s_add_i32 m0, s54, 0x2000
	s_nop 0
	global_load_lds_dwordx4 v[222:223], off
	v_lshl_add_u64 v[222:223], s[30:31], 0, v[136:137]
	s_mov_b32 m0, s27
	s_nop 0
	global_load_lds_dwordx4 v[222:223], off
	s_mov_b32 m0, s38
	s_nop 0
	global_load_lds_dwordx4 v[224:225], off
	s_waitcnt vmcnt(8)
	s_waitcnt lgkmcnt(0)
	s_barrier
	s_setprio 1
	s_waitcnt lgkmcnt(0)
	v_mfma_f32_16x16x32_bf16 v[62:65], v[148:151], v[186:189], v[62:65]
	v_mfma_f32_16x16x32_bf16 v[62:65], v[152:155], v[190:193], v[62:65]
	v_mfma_f32_16x16x32_bf16 v[54:57], v[156:159], v[186:189], v[54:57]
	v_mfma_f32_16x16x32_bf16 v[54:57], v[160:163], v[190:193], v[54:57]
	v_mfma_f32_16x16x32_bf16 v[46:49], v[148:151], v[194:197], v[46:49]
	v_mfma_f32_16x16x32_bf16 v[46:49], v[152:155], v[198:201], v[46:49]
	v_mfma_f32_16x16x32_bf16 v[38:41], v[156:159], v[194:197], v[38:41]
	v_mfma_f32_16x16x32_bf16 v[38:41], v[160:163], v[198:201], v[38:41]
	v_mfma_f32_16x16x32_bf16 v[30:33], v[148:151], v[202:205], v[30:33]
	v_mfma_f32_16x16x32_bf16 v[30:33], v[152:155], v[206:209], v[30:33]
	v_mfma_f32_16x16x32_bf16 v[22:25], v[156:159], v[202:205], v[22:25]
	v_mfma_f32_16x16x32_bf16 v[22:25], v[160:163], v[206:209], v[22:25]
	v_mfma_f32_16x16x32_bf16 v[14:17], v[148:151], v[210:213], v[14:17]
	v_mfma_f32_16x16x32_bf16 v[14:17], v[152:155], v[214:217], v[14:17]
	v_mfma_f32_16x16x32_bf16 v[6:9], v[156:159], v[210:213], v[6:9]
	v_mfma_f32_16x16x32_bf16 v[6:9], v[160:163], v[214:217], v[6:9]
	s_setprio 0
	s_setprio 1
	v_mfma_f32_16x16x32_bf16 v[58:61], v[170:173], v[186:189], v[58:61]
	v_mfma_f32_16x16x32_bf16 v[58:61], v[174:177], v[190:193], v[58:61]
	v_mfma_f32_16x16x32_bf16 v[50:53], v[178:181], v[186:189], v[50:53]
	v_mfma_f32_16x16x32_bf16 v[50:53], v[182:185], v[190:193], v[50:53]
	v_mfma_f32_16x16x32_bf16 v[42:45], v[170:173], v[194:197], v[42:45]
	v_mfma_f32_16x16x32_bf16 v[42:45], v[174:177], v[198:201], v[42:45]
	v_mfma_f32_16x16x32_bf16 v[34:37], v[178:181], v[194:197], v[34:37]
	v_mfma_f32_16x16x32_bf16 v[34:37], v[182:185], v[198:201], v[34:37]
	v_mfma_f32_16x16x32_bf16 v[26:29], v[170:173], v[202:205], v[26:29]
	v_mfma_f32_16x16x32_bf16 v[26:29], v[174:177], v[206:209], v[26:29]
	v_mfma_f32_16x16x32_bf16 v[18:21], v[178:181], v[202:205], v[18:21]
	v_mfma_f32_16x16x32_bf16 v[18:21], v[182:185], v[206:209], v[18:21]
	v_mfma_f32_16x16x32_bf16 v[10:13], v[170:173], v[210:213], v[10:13]
	v_mfma_f32_16x16x32_bf16 v[10:13], v[174:177], v[214:217], v[10:13]
	v_mfma_f32_16x16x32_bf16 v[2:5], v[178:181], v[210:213], v[2:5]
	v_mfma_f32_16x16x32_bf16 v[2:5], v[182:185], v[214:217], v[2:5]
	s_setprio 0
	s_barrier
	s_add_i32 s54, 0, 0x18000
	s_add_i32 s55, 0, 0x1c000
	v_add_u32_e32 v160, s54, v164
	v_add_u32_e32 v169, s55, v164
	ds_read_b128 v[148:151], v160
	ds_read_b128 v[152:155], v160 offset:1024
	ds_read_b128 v[156:159], v160 offset:2048
	ds_read_b128 v[160:163], v160 offset:3072
	ds_read_b128 v[170:173], v169
	ds_read_b128 v[174:177], v169 offset:1024
	ds_read_b128 v[178:181], v169 offset:2048
	ds_read_b128 v[182:185], v169 offset:3072
	s_add_u32 s0, s30, 0x40000
	s_addc_u32 s1, s31, 0
	s_mov_b32 m0, s39
	v_lshl_add_u64 v[226:227], s[0:1], 0, v[136:137]
	ds_read_b128 v[186:189], v167 offset:32768
	ds_read_b128 v[190:193], v167 offset:33792
	ds_read_b128 v[194:197], v167 offset:34816
	ds_read_b128 v[198:201], v167 offset:35840
	ds_read_b128 v[202:205], v167 offset:36864
	ds_read_b128 v[206:209], v167 offset:37888
	ds_read_b128 v[210:213], v167 offset:38912
	ds_read_b128 v[214:217], v167 offset:39936
	global_load_lds_dwordx4 v[226:227], off
	v_lshl_add_u64 v[226:227], s[0:1], 0, v[132:133]
	s_mov_b32 m0, s40
	s_nop 0
	global_load_lds_dwordx4 v[226:227], off
	s_waitcnt vmcnt(8)
	s_waitcnt lgkmcnt(0)
	s_barrier
	s_setprio 1
	s_waitcnt lgkmcnt(0)
	v_mfma_f32_16x16x32_bf16 v[126:129], v[148:151], v[186:189], v[126:129]
	v_mfma_f32_16x16x32_bf16 v[126:129], v[152:155], v[190:193], v[126:129]
	v_mfma_f32_16x16x32_bf16 v[118:121], v[156:159], v[186:189], v[118:121]
	v_mfma_f32_16x16x32_bf16 v[118:121], v[160:163], v[190:193], v[118:121]
	v_mfma_f32_16x16x32_bf16 v[110:113], v[148:151], v[194:197], v[110:113]
	v_mfma_f32_16x16x32_bf16 v[110:113], v[152:155], v[198:201], v[110:113]
	v_mfma_f32_16x16x32_bf16 v[102:105], v[156:159], v[194:197], v[102:105]
	v_mfma_f32_16x16x32_bf16 v[102:105], v[160:163], v[198:201], v[102:105]
	v_mfma_f32_16x16x32_bf16 v[94:97], v[148:151], v[202:205], v[94:97]
	v_mfma_f32_16x16x32_bf16 v[94:97], v[152:155], v[206:209], v[94:97]
	v_mfma_f32_16x16x32_bf16 v[86:89], v[156:159], v[202:205], v[86:89]
	v_mfma_f32_16x16x32_bf16 v[86:89], v[160:163], v[206:209], v[86:89]
	v_mfma_f32_16x16x32_bf16 v[78:81], v[148:151], v[210:213], v[78:81]
	v_mfma_f32_16x16x32_bf16 v[78:81], v[152:155], v[214:217], v[78:81]
	v_mfma_f32_16x16x32_bf16 v[70:73], v[156:159], v[210:213], v[70:73]
	v_mfma_f32_16x16x32_bf16 v[70:73], v[160:163], v[214:217], v[70:73]
	s_setprio 0
	s_setprio 1
	v_mfma_f32_16x16x32_bf16 v[122:125], v[170:173], v[186:189], v[122:125]
	v_mfma_f32_16x16x32_bf16 v[122:125], v[174:177], v[190:193], v[122:125]
	v_mfma_f32_16x16x32_bf16 v[114:117], v[178:181], v[186:189], v[114:117]
	v_mfma_f32_16x16x32_bf16 v[114:117], v[182:185], v[190:193], v[114:117]
	v_mfma_f32_16x16x32_bf16 v[106:109], v[170:173], v[194:197], v[106:109]
	v_mfma_f32_16x16x32_bf16 v[106:109], v[174:177], v[198:201], v[106:109]
	v_mfma_f32_16x16x32_bf16 v[98:101], v[178:181], v[194:197], v[98:101]
	v_mfma_f32_16x16x32_bf16 v[98:101], v[182:185], v[198:201], v[98:101]
	v_mfma_f32_16x16x32_bf16 v[90:93], v[170:173], v[202:205], v[90:93]
	v_mfma_f32_16x16x32_bf16 v[90:93], v[174:177], v[206:209], v[90:93]
	v_mfma_f32_16x16x32_bf16 v[82:85], v[178:181], v[202:205], v[82:85]
	v_mfma_f32_16x16x32_bf16 v[82:85], v[182:185], v[206:209], v[82:85]
	v_mfma_f32_16x16x32_bf16 v[74:77], v[170:173], v[210:213], v[74:77]
	v_mfma_f32_16x16x32_bf16 v[74:77], v[174:177], v[214:217], v[74:77]
	v_mfma_f32_16x16x32_bf16 v[66:69], v[178:181], v[210:213], v[66:69]
	v_mfma_f32_16x16x32_bf16 v[66:69], v[182:185], v[214:217], v[66:69]
	s_setprio 0
	s_barrier
	s_add_i32 s0, s54, s35
	v_lshl_add_u64 v[218:219], v[218:219], 0, s[14:15]
	s_mov_b32 m0, s0
	ds_read_b128 v[186:189], v167 offset:49152
	ds_read_b128 v[190:193], v167 offset:50176
	ds_read_b128 v[194:197], v167 offset:51200
	ds_read_b128 v[198:201], v167 offset:52224
	ds_read_b128 v[202:205], v167 offset:53248
	ds_read_b128 v[206:209], v167 offset:54272
	ds_read_b128 v[210:213], v167 offset:55296
	ds_read_b128 v[214:217], v167 offset:56320
	global_load_lds_dwordx4 v[218:219], off
	s_add_i32 m0, s0, 0x2000
	s_add_u32 s0, s2, 0x40080
	v_lshl_add_u64 v[218:219], v[220:221], 0, s[14:15]
	s_addc_u32 s1, s3, 0
	s_add_i32 s2, s55, s35
	global_load_lds_dwordx4 v[218:219], off
	v_lshl_add_u64 v[218:219], s[0:1], 0, v[134:135]
	s_mov_b32 m0, s2
	s_nop 0
	global_load_lds_dwordx4 v[218:219], off
	v_lshl_add_u64 v[218:219], s[0:1], 0, v[130:131]
	s_add_i32 m0, s2, 0x2000
	s_nop 0
	global_load_lds_dwordx4 v[218:219], off
	v_lshl_add_u64 v[218:219], v[222:223], 0, s[14:15]
	s_mov_b32 m0, s41
	s_nop 0
	global_load_lds_dwordx4 v[218:219], off
	v_lshl_add_u64 v[218:219], v[224:225], 0, s[14:15]
	s_mov_b32 m0, s42
	s_nop 0
	global_load_lds_dwordx4 v[218:219], off
	s_waitcnt vmcnt(8)
	s_waitcnt lgkmcnt(0)
	s_barrier
	s_setprio 1
	s_waitcnt lgkmcnt(0)
	v_mfma_f32_16x16x32_bf16 v[62:65], v[148:151], v[186:189], v[62:65]
	v_mfma_f32_16x16x32_bf16 v[62:65], v[152:155], v[190:193], v[62:65]
	v_mfma_f32_16x16x32_bf16 v[54:57], v[156:159], v[186:189], v[54:57]
	v_mfma_f32_16x16x32_bf16 v[54:57], v[160:163], v[190:193], v[54:57]
	v_mfma_f32_16x16x32_bf16 v[46:49], v[148:151], v[194:197], v[46:49]
	v_mfma_f32_16x16x32_bf16 v[46:49], v[152:155], v[198:201], v[46:49]
	v_mfma_f32_16x16x32_bf16 v[38:41], v[156:159], v[194:197], v[38:41]
	v_mfma_f32_16x16x32_bf16 v[38:41], v[160:163], v[198:201], v[38:41]
	v_mfma_f32_16x16x32_bf16 v[30:33], v[148:151], v[202:205], v[30:33]
	v_mfma_f32_16x16x32_bf16 v[30:33], v[152:155], v[206:209], v[30:33]
	v_mfma_f32_16x16x32_bf16 v[22:25], v[156:159], v[202:205], v[22:25]
	v_mfma_f32_16x16x32_bf16 v[22:25], v[160:163], v[206:209], v[22:25]
	v_mfma_f32_16x16x32_bf16 v[14:17], v[148:151], v[210:213], v[14:17]
	v_mfma_f32_16x16x32_bf16 v[14:17], v[152:155], v[214:217], v[14:17]
	v_mfma_f32_16x16x32_bf16 v[6:9], v[156:159], v[210:213], v[6:9]
	v_mfma_f32_16x16x32_bf16 v[6:9], v[160:163], v[214:217], v[6:9]
	s_setprio 0
	s_setprio 1
	v_mfma_f32_16x16x32_bf16 v[58:61], v[170:173], v[186:189], v[58:61]
	s_add_i32 s53, s53, 2
	s_add_u32 s28, s28, 0x100
	s_addc_u32 s29, s29, 0
	s_add_u32 s51, s51, 0x100
	s_addc_u32 s52, s52, 0
	s_cmp_gt_u32 s53, 13
	v_mfma_f32_16x16x32_bf16 v[58:61], v[174:177], v[190:193], v[58:61]
	v_mfma_f32_16x16x32_bf16 v[50:53], v[178:181], v[186:189], v[50:53]
	v_mfma_f32_16x16x32_bf16 v[50:53], v[182:185], v[190:193], v[50:53]
	v_mfma_f32_16x16x32_bf16 v[42:45], v[170:173], v[194:197], v[42:45]
	v_mfma_f32_16x16x32_bf16 v[42:45], v[174:177], v[198:201], v[42:45]
	v_mfma_f32_16x16x32_bf16 v[34:37], v[178:181], v[194:197], v[34:37]
	v_mfma_f32_16x16x32_bf16 v[34:37], v[182:185], v[198:201], v[34:37]
	v_mfma_f32_16x16x32_bf16 v[26:29], v[170:173], v[202:205], v[26:29]
	v_mfma_f32_16x16x32_bf16 v[26:29], v[174:177], v[206:209], v[26:29]
	v_mfma_f32_16x16x32_bf16 v[18:21], v[178:181], v[202:205], v[18:21]
	v_mfma_f32_16x16x32_bf16 v[18:21], v[182:185], v[206:209], v[18:21]
	v_mfma_f32_16x16x32_bf16 v[10:13], v[170:173], v[210:213], v[10:13]
	v_mfma_f32_16x16x32_bf16 v[10:13], v[174:177], v[214:217], v[10:13]
	v_mfma_f32_16x16x32_bf16 v[2:5], v[178:181], v[210:213], v[2:5]
	v_mfma_f32_16x16x32_bf16 v[2:5], v[182:185], v[214:217], v[2:5]
	s_setprio 0
	s_barrier
	s_cbranch_scc0 .LBB0_2207
	s_and_b64 vcc, exec, s[16:17]
	s_cbranch_vccz .LBB0_2210
	s_barrier

.LBB0_2290:
	ds_read_b128 v[144:147], v153
	ds_read_b128 v[156:159], v153 offset:1024
	ds_read_b128 v[160:163], v153 offset:2048
	ds_read_b128 v[164:167], v153 offset:3072
	ds_read_b128 v[168:171], v154
	ds_read_b128 v[172:175], v154 offset:1024
	ds_read_b128 v[176:179], v154 offset:2048
	ds_read_b128 v[180:183], v154 offset:3072
	s_add_u32 s2, s16, 0xfff50080
	s_addc_u32 s3, s17, -1
	s_cmp_eq_u32 s43, 40
	s_cselect_b32 s19, s5, s3
	s_cselect_b32 s18, s4, s2
	s_cselect_b32 s3, s15, s42
	s_cselect_b32 s2, s14, s41
	v_lshl_add_u64 v[148:149], s[16:17], 0, v[136:137]
	s_add_i32 m0, s26, 0xc000
	ds_read_b128 v[184:187], v155
	ds_read_b128 v[188:191], v155 offset:1024
	ds_read_b128 v[192:195], v155 offset:2048
	ds_read_b128 v[196:199], v155 offset:3072
	ds_read_b128 v[200:203], v155 offset:4096
	ds_read_b128 v[204:207], v155 offset:5120
	ds_read_b128 v[208:211], v155 offset:6144
	ds_read_b128 v[212:215], v155 offset:7168
	global_load_lds_dwordx4 v[148:149], off
	v_lshl_add_u64 v[148:149], s[16:17], 0, v[138:139]
	s_add_i32 m0, s26, 0xe000
	s_nop 0
	global_load_lds_dwordx4 v[148:149], off
	s_waitcnt vmcnt(8)
	s_waitcnt lgkmcnt(0)
	s_barrier
	s_setprio 1
	s_waitcnt lgkmcnt(0)
	v_mfma_f32_16x16x32_bf16 v[124:127], v[144:147], v[184:187], v[124:127]
	v_mfma_f32_16x16x32_bf16 v[124:127], v[156:159], v[188:191], v[124:127]
	v_mfma_f32_16x16x32_bf16 v[120:123], v[160:163], v[184:187], v[120:123]
	v_mfma_f32_16x16x32_bf16 v[120:123], v[164:167], v[188:191], v[120:123]
	v_mfma_f32_16x16x32_bf16 v[112:115], v[144:147], v[192:195], v[112:115]
	v_mfma_f32_16x16x32_bf16 v[112:115], v[156:159], v[196:199], v[112:115]
	v_mfma_f32_16x16x32_bf16 v[104:107], v[160:163], v[192:195], v[104:107]
	v_mfma_f32_16x16x32_bf16 v[104:107], v[164:167], v[196:199], v[104:107]
	v_mfma_f32_16x16x32_bf16 v[96:99], v[144:147], v[200:203], v[96:99]
	v_mfma_f32_16x16x32_bf16 v[96:99], v[156:159], v[204:207], v[96:99]
	v_mfma_f32_16x16x32_bf16 v[88:91], v[160:163], v[200:203], v[88:91]
	v_mfma_f32_16x16x32_bf16 v[88:91], v[164:167], v[204:207], v[88:91]
	v_mfma_f32_16x16x32_bf16 v[80:83], v[144:147], v[208:211], v[80:83]
	v_mfma_f32_16x16x32_bf16 v[80:83], v[156:159], v[212:215], v[80:83]
	v_mfma_f32_16x16x32_bf16 v[72:75], v[160:163], v[208:211], v[72:75]
	v_mfma_f32_16x16x32_bf16 v[72:75], v[164:167], v[212:215], v[72:75]
	s_setprio 0
	s_setprio 1
	v_mfma_f32_16x16x32_bf16 v[116:119], v[168:171], v[184:187], v[116:119]
	v_mfma_f32_16x16x32_bf16 v[116:119], v[172:175], v[188:191], v[116:119]
	v_mfma_f32_16x16x32_bf16 v[108:111], v[176:179], v[184:187], v[108:111]
	v_mfma_f32_16x16x32_bf16 v[108:111], v[180:183], v[188:191], v[108:111]
	v_mfma_f32_16x16x32_bf16 v[100:103], v[168:171], v[192:195], v[100:103]
	v_mfma_f32_16x16x32_bf16 v[100:103], v[172:175], v[196:199], v[100:103]
	v_mfma_f32_16x16x32_bf16 v[92:95], v[176:179], v[192:195], v[92:95]
	v_mfma_f32_16x16x32_bf16 v[92:95], v[180:183], v[196:199], v[92:95]
	v_mfma_f32_16x16x32_bf16 v[84:87], v[168:171], v[200:203], v[84:87]
	v_mfma_f32_16x16x32_bf16 v[84:87], v[172:175], v[204:207], v[84:87]
	v_mfma_f32_16x16x32_bf16 v[76:79], v[176:179], v[200:203], v[76:79]
	v_mfma_f32_16x16x32_bf16 v[76:79], v[180:183], v[204:207], v[76:79]
	v_mfma_f32_16x16x32_bf16 v[68:71], v[168:171], v[208:211], v[68:71]
	v_mfma_f32_16x16x32_bf16 v[68:71], v[172:175], v[212:215], v[68:71]
	v_mfma_f32_16x16x32_bf16 v[64:67], v[176:179], v[208:211], v[64:67]
	v_mfma_f32_16x16x32_bf16 v[64:67], v[180:183], v[212:215], v[64:67]
	s_setprio 0
	s_barrier
	s_add_i32 s44, s35, s25
	v_lshl_add_u64 v[148:149], s[2:3], 0, v[130:131]
	s_mov_b32 m0, s44
	ds_read_b128 v[184:187], v155 offset:16384
	ds_read_b128 v[188:191], v155 offset:17408
	ds_read_b128 v[192:195], v155 offset:18432
	ds_read_b128 v[196:199], v155 offset:19456
	ds_read_b128 v[200:203], v155 offset:20480
	ds_read_b128 v[204:207], v155 offset:21504
	ds_read_b128 v[208:211], v155 offset:22528
	ds_read_b128 v[212:215], v155 offset:23552
	global_load_lds_dwordx4 v[148:149], off
	s_add_i32 m0, s44, 0x2000
	s_add_u32 s44, s2, 0xb0000
	v_lshl_add_u64 v[216:217], s[2:3], 0, v[134:135]
	s_addc_u32 s45, s3, 0
	s_add_i32 s46, s36, s25
	global_load_lds_dwordx4 v[216:217], off
	v_lshl_add_u64 v[218:219], s[44:45], 0, v[130:131]
	s_mov_b32 m0, s46
	v_lshl_add_u64 v[220:221], s[18:19], 0, v[132:133]
	global_load_lds_dwordx4 v[218:219], off
	v_lshl_add_u64 v[218:219], s[44:45], 0, v[134:135]
	s_add_i32 m0, s46, 0x2000
	s_nop 0
	global_load_lds_dwordx4 v[218:219], off
	v_lshl_add_u64 v[218:219], s[18:19], 0, v[128:129]
	s_mov_b32 m0, s26
	s_nop 0
	global_load_lds_dwordx4 v[218:219], off
	s_mov_b32 m0, s27
	s_nop 0
	global_load_lds_dwordx4 v[220:221], off
	s_waitcnt vmcnt(8)
	s_waitcnt lgkmcnt(0)
	s_barrier
	s_setprio 1
	s_waitcnt lgkmcnt(0)
	v_mfma_f32_16x16x32_bf16 v[60:63], v[144:147], v[184:187], v[60:63]
	v_mfma_f32_16x16x32_bf16 v[60:63], v[156:159], v[188:191], v[60:63]
	v_mfma_f32_16x16x32_bf16 v[56:59], v[160:163], v[184:187], v[56:59]
	v_mfma_f32_16x16x32_bf16 v[56:59], v[164:167], v[188:191], v[56:59]
	v_mfma_f32_16x16x32_bf16 v[48:51], v[144:147], v[192:195], v[48:51]
	v_mfma_f32_16x16x32_bf16 v[48:51], v[156:159], v[196:199], v[48:51]
	v_mfma_f32_16x16x32_bf16 v[40:43], v[160:163], v[192:195], v[40:43]
	v_mfma_f32_16x16x32_bf16 v[40:43], v[164:167], v[196:199], v[40:43]
	v_mfma_f32_16x16x32_bf16 v[32:35], v[144:147], v[200:203], v[32:35]
	v_mfma_f32_16x16x32_bf16 v[32:35], v[156:159], v[204:207], v[32:35]
	v_mfma_f32_16x16x32_bf16 v[24:27], v[160:163], v[200:203], v[24:27]
	v_mfma_f32_16x16x32_bf16 v[24:27], v[164:167], v[204:207], v[24:27]
	v_mfma_f32_16x16x32_bf16 v[16:19], v[144:147], v[208:211], v[16:19]
	v_mfma_f32_16x16x32_bf16 v[16:19], v[156:159], v[212:215], v[16:19]
	v_mfma_f32_16x16x32_bf16 v[8:11], v[160:163], v[208:211], v[8:11]
	v_mfma_f32_16x16x32_bf16 v[8:11], v[164:167], v[212:215], v[8:11]
	s_setprio 0
	s_setprio 1
	v_mfma_f32_16x16x32_bf16 v[52:55], v[168:171], v[184:187], v[52:55]
	v_mfma_f32_16x16x32_bf16 v[52:55], v[172:175], v[188:191], v[52:55]
	v_mfma_f32_16x16x32_bf16 v[44:47], v[176:179], v[184:187], v[44:47]
	v_mfma_f32_16x16x32_bf16 v[44:47], v[180:183], v[188:191], v[44:47]
	v_mfma_f32_16x16x32_bf16 v[36:39], v[168:171], v[192:195], v[36:39]
	v_mfma_f32_16x16x32_bf16 v[36:39], v[172:175], v[196:199], v[36:39]
	v_mfma_f32_16x16x32_bf16 v[28:31], v[176:179], v[192:195], v[28:31]
	v_mfma_f32_16x16x32_bf16 v[28:31], v[180:183], v[196:199], v[28:31]
	v_mfma_f32_16x16x32_bf16 v[20:23], v[168:171], v[200:203], v[20:23]
	v_mfma_f32_16x16x32_bf16 v[20:23], v[172:175], v[204:207], v[20:23]
	v_mfma_f32_16x16x32_bf16 v[12:15], v[176:179], v[200:203], v[12:15]
	v_mfma_f32_16x16x32_bf16 v[12:15], v[180:183], v[204:207], v[12:15]
	v_mfma_f32_16x16x32_bf16 v[4:7], v[168:171], v[208:211], v[4:7]
	v_mfma_f32_16x16x32_bf16 v[4:7], v[172:175], v[212:215], v[4:7]
	v_mfma_f32_16x16x32_bf16 v[0:3], v[176:179], v[208:211], v[0:3]
	v_mfma_f32_16x16x32_bf16 v[0:3], v[180:183], v[212:215], v[0:3]
	s_setprio 0
	s_barrier
	s_add_i32 s44, 0, 0x18000
	s_add_i32 s45, 0, 0x1c000
	v_add_u32_e32 v164, s44, v151
	v_add_u32_e32 v180, s45, v151
	ds_read_b128 v[144:147], v164
	ds_read_b128 v[156:159], v164 offset:1024
	ds_read_b128 v[160:163], v164 offset:2048
	ds_read_b128 v[164:167], v164 offset:3072
	ds_read_b128 v[168:171], v180
	ds_read_b128 v[172:175], v180 offset:1024
	ds_read_b128 v[176:179], v180 offset:2048
	ds_read_b128 v[180:183], v180 offset:3072
	s_add_u32 s18, s18, 0xb0000
	s_addc_u32 s19, s19, 0
	s_mov_b32 m0, s28
	v_lshl_add_u64 v[222:223], s[18:19], 0, v[128:129]
	ds_read_b128 v[184:187], v155 offset:32768
	ds_read_b128 v[188:191], v155 offset:33792
	ds_read_b128 v[192:195], v155 offset:34816
	ds_read_b128 v[196:199], v155 offset:35840
	ds_read_b128 v[200:203], v155 offset:36864
	ds_read_b128 v[204:207], v155 offset:37888
	ds_read_b128 v[208:211], v155 offset:38912
	ds_read_b128 v[212:215], v155 offset:39936
	global_load_lds_dwordx4 v[222:223], off
	v_lshl_add_u64 v[222:223], s[18:19], 0, v[132:133]
	s_mov_b32 m0, s29
	s_nop 0
	global_load_lds_dwordx4 v[222:223], off
	s_waitcnt vmcnt(8)
	s_waitcnt lgkmcnt(0)
	s_barrier
	s_setprio 1
	s_waitcnt lgkmcnt(0)
	v_mfma_f32_16x16x32_bf16 v[124:127], v[144:147], v[184:187], v[124:127]
	v_mfma_f32_16x16x32_bf16 v[124:127], v[156:159], v[188:191], v[124:127]
	v_mfma_f32_16x16x32_bf16 v[120:123], v[160:163], v[184:187], v[120:123]
	v_mfma_f32_16x16x32_bf16 v[120:123], v[164:167], v[188:191], v[120:123]
	v_mfma_f32_16x16x32_bf16 v[112:115], v[144:147], v[192:195], v[112:115]
	v_mfma_f32_16x16x32_bf16 v[112:115], v[156:159], v[196:199], v[112:115]
	v_mfma_f32_16x16x32_bf16 v[104:107], v[160:163], v[192:195], v[104:107]
	v_mfma_f32_16x16x32_bf16 v[104:107], v[164:167], v[196:199], v[104:107]
	v_mfma_f32_16x16x32_bf16 v[96:99], v[144:147], v[200:203], v[96:99]
	v_mfma_f32_16x16x32_bf16 v[96:99], v[156:159], v[204:207], v[96:99]
	v_mfma_f32_16x16x32_bf16 v[88:91], v[160:163], v[200:203], v[88:91]
	v_mfma_f32_16x16x32_bf16 v[88:91], v[164:167], v[204:207], v[88:91]
	v_mfma_f32_16x16x32_bf16 v[80:83], v[144:147], v[208:211], v[80:83]
	v_mfma_f32_16x16x32_bf16 v[80:83], v[156:159], v[212:215], v[80:83]
	v_mfma_f32_16x16x32_bf16 v[72:75], v[160:163], v[208:211], v[72:75]
	v_mfma_f32_16x16x32_bf16 v[72:75], v[164:167], v[212:215], v[72:75]
	s_setprio 0
	s_setprio 1
	v_mfma_f32_16x16x32_bf16 v[116:119], v[168:171], v[184:187], v[116:119]
	v_mfma_f32_16x16x32_bf16 v[116:119], v[172:175], v[188:191], v[116:119]
	v_mfma_f32_16x16x32_bf16 v[108:111], v[176:179], v[184:187], v[108:111]
	v_mfma_f32_16x16x32_bf16 v[108:111], v[180:183], v[188:191], v[108:111]
	v_mfma_f32_16x16x32_bf16 v[100:103], v[168:171], v[192:195], v[100:103]
	v_mfma_f32_16x16x32_bf16 v[100:103], v[172:175], v[196:199], v[100:103]
	v_mfma_f32_16x16x32_bf16 v[92:95], v[176:179], v[192:195], v[92:95]
	v_mfma_f32_16x16x32_bf16 v[92:95], v[180:183], v[196:199], v[92:95]
	v_mfma_f32_16x16x32_bf16 v[84:87], v[168:171], v[200:203], v[84:87]
	v_mfma_f32_16x16x32_bf16 v[84:87], v[172:175], v[204:207], v[84:87]
	v_mfma_f32_16x16x32_bf16 v[76:79], v[176:179], v[200:203], v[76:79]
	v_mfma_f32_16x16x32_bf16 v[76:79], v[180:183], v[204:207], v[76:79]
	v_mfma_f32_16x16x32_bf16 v[68:71], v[168:171], v[208:211], v[68:71]
	v_mfma_f32_16x16x32_bf16 v[68:71], v[172:175], v[212:215], v[68:71]
	v_mfma_f32_16x16x32_bf16 v[64:67], v[176:179], v[208:211], v[64:67]
	v_mfma_f32_16x16x32_bf16 v[64:67], v[180:183], v[212:215], v[64:67]
	s_setprio 0
	s_barrier
	s_add_i32 s18, s44, s25
	v_lshl_add_u64 v[148:149], v[148:149], 0, s[10:11]
	s_mov_b32 m0, s18
	ds_read_b128 v[184:187], v155 offset:49152
	ds_read_b128 v[188:191], v155 offset:50176
	ds_read_b128 v[192:195], v155 offset:51200
	ds_read_b128 v[196:199], v155 offset:52224
	ds_read_b128 v[200:203], v155 offset:53248
	ds_read_b128 v[204:207], v155 offset:54272
	ds_read_b128 v[208:211], v155 offset:55296
	ds_read_b128 v[212:215], v155 offset:56320
	global_load_lds_dwordx4 v[148:149], off
	s_add_i32 m0, s18, 0x2000
	s_add_u32 s2, s2, 0xb0080
	v_lshl_add_u64 v[148:149], v[216:217], 0, s[10:11]
	s_addc_u32 s3, s3, 0
	s_add_i32 s18, s45, s25
	global_load_lds_dwordx4 v[148:149], off
	v_lshl_add_u64 v[148:149], s[2:3], 0, v[130:131]
	s_mov_b32 m0, s18
	s_nop 0
	global_load_lds_dwordx4 v[148:149], off
	v_lshl_add_u64 v[148:149], s[2:3], 0, v[134:135]
	s_add_i32 m0, s18, 0x2000
	s_nop 0
	global_load_lds_dwordx4 v[148:149], off
	v_lshl_add_u64 v[148:149], v[218:219], 0, s[10:11]
	s_mov_b32 m0, s31
	s_nop 0
	global_load_lds_dwordx4 v[148:149], off
	v_lshl_add_u64 v[148:149], v[220:221], 0, s[10:11]
	s_mov_b32 m0, s33
	s_nop 0
	global_load_lds_dwordx4 v[148:149], off
	s_waitcnt vmcnt(8)
	s_waitcnt lgkmcnt(0)
	s_barrier
	s_setprio 1
	s_waitcnt lgkmcnt(0)
	v_mfma_f32_16x16x32_bf16 v[60:63], v[144:147], v[184:187], v[60:63]
	v_mfma_f32_16x16x32_bf16 v[60:63], v[156:159], v[188:191], v[60:63]
	v_mfma_f32_16x16x32_bf16 v[56:59], v[160:163], v[184:187], v[56:59]
	v_mfma_f32_16x16x32_bf16 v[56:59], v[164:167], v[188:191], v[56:59]
	v_mfma_f32_16x16x32_bf16 v[48:51], v[144:147], v[192:195], v[48:51]
	v_mfma_f32_16x16x32_bf16 v[48:51], v[156:159], v[196:199], v[48:51]
	v_mfma_f32_16x16x32_bf16 v[40:43], v[160:163], v[192:195], v[40:43]
	v_mfma_f32_16x16x32_bf16 v[40:43], v[164:167], v[196:199], v[40:43]
	v_mfma_f32_16x16x32_bf16 v[32:35], v[144:147], v[200:203], v[32:35]
	v_mfma_f32_16x16x32_bf16 v[32:35], v[156:159], v[204:207], v[32:35]
	v_mfma_f32_16x16x32_bf16 v[24:27], v[160:163], v[200:203], v[24:27]
	v_mfma_f32_16x16x32_bf16 v[24:27], v[164:167], v[204:207], v[24:27]
	v_mfma_f32_16x16x32_bf16 v[16:19], v[144:147], v[208:211], v[16:19]
	v_mfma_f32_16x16x32_bf16 v[16:19], v[156:159], v[212:215], v[16:19]
	v_mfma_f32_16x16x32_bf16 v[8:11], v[160:163], v[208:211], v[8:11]
	v_mfma_f32_16x16x32_bf16 v[8:11], v[164:167], v[212:215], v[8:11]
	s_setprio 0
	s_setprio 1
	v_mfma_f32_16x16x32_bf16 v[52:55], v[168:171], v[184:187], v[52:55]
	s_add_i32 s43, s43, 2
	s_add_u32 s16, s16, 0x100
	s_addc_u32 s17, s17, 0
	s_add_u32 s41, s41, 0x100
	s_addc_u32 s42, s42, 0
	s_cmp_gt_u32 s43, 41
	v_mfma_f32_16x16x32_bf16 v[52:55], v[172:175], v[188:191], v[52:55]
	v_mfma_f32_16x16x32_bf16 v[44:47], v[176:179], v[184:187], v[44:47]
	v_mfma_f32_16x16x32_bf16 v[44:47], v[180:183], v[188:191], v[44:47]
	v_mfma_f32_16x16x32_bf16 v[36:39], v[168:171], v[192:195], v[36:39]
	v_mfma_f32_16x16x32_bf16 v[36:39], v[172:175], v[196:199], v[36:39]
	v_mfma_f32_16x16x32_bf16 v[28:31], v[176:179], v[192:195], v[28:31]
	v_mfma_f32_16x16x32_bf16 v[28:31], v[180:183], v[196:199], v[28:31]
	v_mfma_f32_16x16x32_bf16 v[20:23], v[168:171], v[200:203], v[20:23]
	v_mfma_f32_16x16x32_bf16 v[20:23], v[172:175], v[204:207], v[20:23]
	v_mfma_f32_16x16x32_bf16 v[12:15], v[176:179], v[200:203], v[12:15]
	v_mfma_f32_16x16x32_bf16 v[12:15], v[180:183], v[204:207], v[12:15]
	v_mfma_f32_16x16x32_bf16 v[4:7], v[168:171], v[208:211], v[4:7]
	v_mfma_f32_16x16x32_bf16 v[4:7], v[172:175], v[212:215], v[4:7]
	v_mfma_f32_16x16x32_bf16 v[0:3], v[176:179], v[208:211], v[0:3]
	v_mfma_f32_16x16x32_bf16 v[0:3], v[180:183], v[212:215], v[0:3]
	s_setprio 0
	s_barrier
	s_cbranch_scc0 .LBB0_2290
	s_and_b64 vcc, exec, s[12:13]
	s_cbranch_vccz .LBB0_2293
	s_barrier
